# baseline (speedup 1.0000x reference)
; #define LDA(dst, b, h)                                                                                               \
;   _Pragma("unroll") for (int m = 0; m < 4; ++m) _Pragma("unroll") for (int k = 0; k < 2; ++k) dst[m][k] =            \
;       *reinterpret_cast<const bf16x8*>(SA(b, h) + lds_byte(wr * 64 + m * 16 + fr, k * 32 + fq * 8))
; #define LDB(dst, b, h)                                                                                               \
;   _Pragma("unroll") for (int n = 0; n < 2; ++n) _Pragma("unroll") for (int k = 0; k < 2; ++k) dst[n][k] =            \
;       *reinterpret_cast<const bf16x8*>(SB(b, h) + lds_byte(wc * 32 + n * 16 + fr, k * 32 + fq * 8))
; #define WAIT_V(n) asm volatile("s_waitcnt vmcnt(" #n ")" ::: "memory")
; #define WAIT_L(n) asm volatile("s_waitcnt lgkmcnt(" #n ")" ::: "memory")
; #define BAR __builtin_amdgcn_s_barrier()
; #define SCHED __builtin_amdgcn_sched_barrier(0)
; template <int EPI>
; __device__ __forceinline__ void gemm_phase(const u16* __restrict__ A, const u16* __restrict__ Bt, const int K,
;                                            const int nN, char* shm, const EpiArgs& ea) {
;     ...
;     for (int t = 0; t < nt - 2; t += 2) {
;       LDB(B0, 0, 0); SCHED; LDA(At, 0, 0); STAGE(SA(1, 1), rA, brow + HALF, t + 1);
;       WAIT_V(10); WAIT_L(8); BAR; WAIT_L(0); MMA(0, 0, At, B0); BAR; SCHED;
;       LDB(B1, 0, 1); STAGE(SB(0, 0), rB, bcol, t + 2);
;       WAIT_V(10); BAR; WAIT_L(0); MMA(0, 1, At, B1); BAR;
;       LDA(At, 0, 1); STAGE(SA(0, 0), rA, brow, t + 2);
;       BAR; WAIT_L(0); MMA(1, 0, At, B0); BAR; SCHED;
;       STAGE(SB(0, 1), rB, bcol + HALF, t + 2);
;       WAIT_V(10); BAR; MMA(1, 1, At, B1); BAR;
.LBB0_172:
	ds_read_b128 v[142:145], v133
	ds_read_b128 v[146:149], v133 offset:1024
	ds_read_b128 v[150:153], v133 offset:2048
	ds_read_b128 v[154:157], v133 offset:3072
	s_add_i32 s73, s67, s72
	s_mov_b32 m0, s57
	s_add_i32 s6, s73, 0x4000
	ds_read_b128 v[162:165], v134
	ds_read_b128 v[166:169], v134 offset:1024
	ds_read_b128 v[170:173], v135
	ds_read_b128 v[176:179], v135 offset:1024
	ds_read_b128 v[180:183], v136
	ds_read_b128 v[184:187], v136 offset:1024
	ds_read_b128 v[188:191], v137
	ds_read_b128 v[192:195], v137 offset:1024
	buffer_load_dwordx4 v130, s[0:3], s6 offen lds
	s_add_i32 s6, s73, 0x6000
	s_mov_b32 m0, s58
	s_nop 0
	buffer_load_dwordx4 v130, s[0:3], s6 offen lds
	s_waitcnt vmcnt(10)
	s_waitcnt lgkmcnt(8)
	s_barrier
	s_waitcnt lgkmcnt(0)
	v_mfma_f32_16x16x32_bf16 v[124:127], v[142:145], v[162:165], v[124:127]
	v_mfma_f32_16x16x32_bf16 v[120:123], v[150:153], v[162:165], v[120:123]
	v_mfma_f32_16x16x32_bf16 v[112:115], v[150:153], v[170:173], v[112:115]
	v_mfma_f32_16x16x32_bf16 v[116:119], v[142:145], v[170:173], v[116:119]
	v_mfma_f32_16x16x32_bf16 v[108:111], v[142:145], v[180:183], v[108:111]
	v_mfma_f32_16x16x32_bf16 v[104:107], v[150:153], v[180:183], v[104:107]
	v_mfma_f32_16x16x32_bf16 v[96:99], v[150:153], v[188:191], v[96:99]
	v_mfma_f32_16x16x32_bf16 v[100:103], v[142:145], v[188:191], v[100:103]
	v_mfma_f32_16x16x32_bf16 v[124:127], v[146:149], v[166:169], v[124:127]
	v_mfma_f32_16x16x32_bf16 v[120:123], v[154:157], v[166:169], v[120:123]
	v_mfma_f32_16x16x32_bf16 v[112:115], v[154:157], v[176:179], v[112:115]
	v_mfma_f32_16x16x32_bf16 v[116:119], v[146:149], v[176:179], v[116:119]
	v_mfma_f32_16x16x32_bf16 v[108:111], v[146:149], v[184:187], v[108:111]
	v_mfma_f32_16x16x32_bf16 v[104:107], v[154:157], v[184:187], v[104:107]
	v_mfma_f32_16x16x32_bf16 v[96:99], v[154:157], v[192:195], v[96:99]
	v_mfma_f32_16x16x32_bf16 v[100:103], v[146:149], v[192:195], v[100:103]
	s_barrier
	s_add_i32 s74, s70, s72
	s_mov_b32 m0, s34
	s_add_i32 s75, s74, 0x8000
	s_mov_b32 s6, s2
	s_mov_b32 s7, s3
	ds_read_b128 v[196:199], v138
	ds_read_b128 v[200:203], v138 offset:1024
	ds_read_b128 v[204:207], v138 offset:2048
	ds_read_b128 v[208:211], v138 offset:3072
	buffer_load_dwordx4 v130, s[4:7], s75 offen lds
	s_add_i32 s75, s74, 0xa000
	s_mov_b32 m0, s35
	s_nop 0
	buffer_load_dwordx4 v130, s[4:7], s75 offen lds
	s_waitcnt vmcnt(10)
	s_barrier
	s_waitcnt lgkmcnt(0)
	v_mfma_f32_16x16x32_bf16 v[92:95], v[196:199], v[162:165], v[92:95]
	v_mfma_f32_16x16x32_bf16 v[88:91], v[204:207], v[162:165], v[88:91]
	v_mfma_f32_16x16x32_bf16 v[80:83], v[204:207], v[170:173], v[80:83]
	v_mfma_f32_16x16x32_bf16 v[84:87], v[196:199], v[170:173], v[84:87]
	v_mfma_f32_16x16x32_bf16 v[76:79], v[196:199], v[180:183], v[76:79]
	v_mfma_f32_16x16x32_bf16 v[72:75], v[204:207], v[180:183], v[72:75]
	v_mfma_f32_16x16x32_bf16 v[64:67], v[204:207], v[188:191], v[64:67]
	v_mfma_f32_16x16x32_bf16 v[68:71], v[196:199], v[188:191], v[68:71]
	v_mfma_f32_16x16x32_bf16 v[92:95], v[200:203], v[166:169], v[92:95]
	v_mfma_f32_16x16x32_bf16 v[88:91], v[208:211], v[166:169], v[88:91]
	v_mfma_f32_16x16x32_bf16 v[80:83], v[208:211], v[176:179], v[80:83]
	v_mfma_f32_16x16x32_bf16 v[84:87], v[200:203], v[176:179], v[84:87]
	v_mfma_f32_16x16x32_bf16 v[76:79], v[200:203], v[184:187], v[76:79]
	v_mfma_f32_16x16x32_bf16 v[72:75], v[208:211], v[184:187], v[72:75]
	v_mfma_f32_16x16x32_bf16 v[64:67], v[208:211], v[192:195], v[64:67]
	v_mfma_f32_16x16x32_bf16 v[68:71], v[200:203], v[192:195], v[68:71]
	s_add_i32 s75, s69, s72
	s_mov_b32 m0, s38
	s_add_i32 s78, s75, 0x8000
	s_barrier
	ds_read_b128 v[162:165], v134 offset:16384
	ds_read_b128 v[166:169], v134 offset:17408
	ds_read_b128 v[170:173], v135 offset:16384
	ds_read_b128 v[176:179], v135 offset:17408
	ds_read_b128 v[180:183], v136 offset:16384
	ds_read_b128 v[184:187], v136 offset:17408
	ds_read_b128 v[188:191], v137 offset:16384
	ds_read_b128 v[192:195], v137 offset:17408
	buffer_load_dwordx4 v130, s[0:3], s78 offen lds
	s_add_i32 s78, s75, 0xa000
	s_mov_b32 m0, s39
	s_nop 0
	buffer_load_dwordx4 v130, s[0:3], s78 offen lds
	s_barrier
	s_waitcnt lgkmcnt(0)
	v_mfma_f32_16x16x32_bf16 v[60:63], v[142:145], v[162:165], v[60:63]
	v_mfma_f32_16x16x32_bf16 v[56:59], v[150:153], v[162:165], v[56:59]
	v_mfma_f32_16x16x32_bf16 v[48:51], v[150:153], v[170:173], v[48:51]
	v_mfma_f32_16x16x32_bf16 v[52:55], v[142:145], v[170:173], v[52:55]
	v_mfma_f32_16x16x32_bf16 v[44:47], v[142:145], v[180:183], v[44:47]
	v_mfma_f32_16x16x32_bf16 v[40:43], v[150:153], v[180:183], v[40:43]
	v_mfma_f32_16x16x32_bf16 v[32:35], v[150:153], v[188:191], v[32:35]
	v_mfma_f32_16x16x32_bf16 v[36:39], v[142:145], v[188:191], v[36:39]
	v_mfma_f32_16x16x32_bf16 v[60:63], v[146:149], v[166:169], v[60:63]
	v_mfma_f32_16x16x32_bf16 v[56:59], v[154:157], v[166:169], v[56:59]
	v_mfma_f32_16x16x32_bf16 v[48:51], v[154:157], v[176:179], v[48:51]
	v_mfma_f32_16x16x32_bf16 v[52:55], v[146:149], v[176:179], v[52:55]
	v_mfma_f32_16x16x32_bf16 v[44:47], v[146:149], v[184:187], v[44:47]
	v_mfma_f32_16x16x32_bf16 v[40:43], v[154:157], v[184:187], v[40:43]
	v_mfma_f32_16x16x32_bf16 v[32:35], v[154:157], v[192:195], v[32:35]
	v_mfma_f32_16x16x32_bf16 v[36:39], v[146:149], v[192:195], v[36:39]
	s_barrier
	s_add_i32 s78, s68, s72
	s_mov_b32 m0, s40
	s_add_i32 s79, s78, 0x8000
	buffer_load_dwordx4 v130, s[4:7], s79 offen lds
	s_add_i32 s79, s78, 0xa000
	s_mov_b32 m0, s41
	s_nop 0
	buffer_load_dwordx4 v130, s[4:7], s79 offen lds
	s_waitcnt vmcnt(10)
	s_barrier
; #define LDA(dst, b, h)                                                                                               \
;   _Pragma("unroll") for (int m = 0; m < 4; ++m) _Pragma("unroll") for (int k = 0; k < 2; ++k) dst[m][k] =            \
;       *reinterpret_cast<const bf16x8*>(SA(b, h) + lds_byte(wr * 64 + m * 16 + fr, k * 32 + fq * 8))
; #define LDB(dst, b, h)                                                                                               \
;   _Pragma("unroll") for (int n = 0; n < 2; ++n) _Pragma("unroll") for (int k = 0; k < 2; ++k) dst[n][k] =            \
;       *reinterpret_cast<const bf16x8*>(SB(b, h) + lds_byte(wc * 32 + n * 16 + fr, k * 32 + fq * 8))
; #define WAIT_V(n) asm volatile("s_waitcnt vmcnt(" #n ")" ::: "memory")
; #define WAIT_L(n) asm volatile("s_waitcnt lgkmcnt(" #n ")" ::: "memory")
; #define BAR __builtin_amdgcn_s_barrier()
; #define SCHED __builtin_amdgcn_sched_barrier(0)
; template <int EPI>
; __device__ __forceinline__ void gemm_phase(const u16* __restrict__ A, const u16* __restrict__ Bt, const int K,
;                                            const int nN, char* shm, const EpiArgs& ea) {
;     ...
;       WAIT_V(10); BAR; WAIT_L(0); MMA(0, 1, At, B1); BAR;
;       LDA(At, 0, 1); STAGE(SA(0, 0), rA, brow, t + 2);
;       BAR; WAIT_L(0); MMA(1, 0, At, B0); BAR; SCHED;
;       STAGE(SB(0, 1), rB, bcol + HALF, t + 2);
;       WAIT_V(10); BAR; MMA(1, 1, At, B1); BAR;
;       LDB(B0, 1, 0); SCHED; LDA(At, 1, 0); STAGE(SA(0, 1), rA, brow + HALF, t + 2);
;       WAIT_V(10); WAIT_L(8); BAR; WAIT_L(0); MMA(0, 0, At, B0); BAR; SCHED;
;       LDB(B1, 1, 1); STAGE(SB(1, 0), rB, bcol, t + 3);
;       WAIT_V(10); BAR; WAIT_L(0); MMA(0, 1, At, B1); BAR;
	v_mfma_f32_16x16x32_bf16 v[28:31], v[196:199], v[162:165], v[28:31]
	v_mfma_f32_16x16x32_bf16 v[24:27], v[204:207], v[162:165], v[24:27]
	v_mfma_f32_16x16x32_bf16 v[16:19], v[204:207], v[170:173], v[16:19]
	v_mfma_f32_16x16x32_bf16 v[20:23], v[196:199], v[170:173], v[20:23]
	v_mfma_f32_16x16x32_bf16 v[12:15], v[196:199], v[180:183], v[12:15]
	v_mfma_f32_16x16x32_bf16 v[8:11], v[204:207], v[180:183], v[8:11]
	v_mfma_f32_16x16x32_bf16 v[0:3], v[204:207], v[188:191], v[0:3]
	v_mfma_f32_16x16x32_bf16 v[4:7], v[196:199], v[188:191], v[4:7]
	v_mfma_f32_16x16x32_bf16 v[28:31], v[200:203], v[166:169], v[28:31]
	v_mfma_f32_16x16x32_bf16 v[24:27], v[208:211], v[166:169], v[24:27]
	v_mfma_f32_16x16x32_bf16 v[16:19], v[208:211], v[176:179], v[16:19]
	v_mfma_f32_16x16x32_bf16 v[20:23], v[200:203], v[176:179], v[20:23]
	v_mfma_f32_16x16x32_bf16 v[12:15], v[200:203], v[184:187], v[12:15]
	v_mfma_f32_16x16x32_bf16 v[8:11], v[208:211], v[184:187], v[8:11]
	v_mfma_f32_16x16x32_bf16 v[0:3], v[208:211], v[192:195], v[0:3]
	v_mfma_f32_16x16x32_bf16 v[4:7], v[200:203], v[192:195], v[4:7]
	s_barrier
	ds_read_b128 v[142:145], v139
	ds_read_b128 v[146:149], v139 offset:1024
	ds_read_b128 v[150:153], v139 offset:2048
	ds_read_b128 v[154:157], v139 offset:3072
	s_mov_b32 m0, s42
	s_add_i32 s79, s73, 0x8000
	ds_read_b128 v[162:165], v134 offset:32768
	ds_read_b128 v[166:169], v134 offset:33792
	ds_read_b128 v[170:173], v135 offset:32768
	ds_read_b128 v[176:179], v135 offset:33792
	ds_read_b128 v[180:183], v136 offset:32768
	ds_read_b128 v[184:187], v136 offset:33792
	ds_read_b128 v[188:191], v137 offset:32768
	ds_read_b128 v[192:195], v137 offset:33792
	buffer_load_dwordx4 v130, s[0:3], s79 offen lds
	s_add_i32 s73, s73, 0xa000
	s_mov_b32 m0, s43
	s_nop 0
	buffer_load_dwordx4 v130, s[0:3], s73 offen lds
	s_waitcnt vmcnt(10)
	s_waitcnt lgkmcnt(8)
	s_barrier
	s_waitcnt lgkmcnt(0)
	v_mfma_f32_16x16x32_bf16 v[124:127], v[142:145], v[162:165], v[124:127]
	v_mfma_f32_16x16x32_bf16 v[120:123], v[150:153], v[162:165], v[120:123]
	v_mfma_f32_16x16x32_bf16 v[112:115], v[150:153], v[170:173], v[112:115]
	v_mfma_f32_16x16x32_bf16 v[116:119], v[142:145], v[170:173], v[116:119]
	v_mfma_f32_16x16x32_bf16 v[108:111], v[142:145], v[180:183], v[108:111]
	v_mfma_f32_16x16x32_bf16 v[104:107], v[150:153], v[180:183], v[104:107]
	v_mfma_f32_16x16x32_bf16 v[96:99], v[150:153], v[188:191], v[96:99]
	v_mfma_f32_16x16x32_bf16 v[100:103], v[142:145], v[188:191], v[100:103]
	v_mfma_f32_16x16x32_bf16 v[124:127], v[146:149], v[166:169], v[124:127]
	v_mfma_f32_16x16x32_bf16 v[120:123], v[154:157], v[166:169], v[120:123]
	v_mfma_f32_16x16x32_bf16 v[112:115], v[154:157], v[176:179], v[112:115]
	v_mfma_f32_16x16x32_bf16 v[116:119], v[146:149], v[176:179], v[116:119]
	v_mfma_f32_16x16x32_bf16 v[108:111], v[146:149], v[184:187], v[108:111]
	v_mfma_f32_16x16x32_bf16 v[104:107], v[154:157], v[184:187], v[104:107]
	v_mfma_f32_16x16x32_bf16 v[96:99], v[154:157], v[192:195], v[96:99]
	v_mfma_f32_16x16x32_bf16 v[100:103], v[146:149], v[192:195], v[100:103]
	s_barrier
	s_mov_b32 m0, s48
	s_add_i32 s73, s74, 0xc000
	ds_read_b128 v[196:199], v140
	ds_read_b128 v[200:203], v140 offset:1024
	ds_read_b128 v[204:207], v140 offset:2048
	ds_read_b128 v[208:211], v140 offset:3072
	buffer_load_dwordx4 v130, s[4:7], s73 offen lds
	s_add_i32 s74, s74, 0xe000
	s_mov_b32 m0, s49
	s_nop 0
	buffer_load_dwordx4 v130, s[4:7], s74 offen lds
	s_waitcnt vmcnt(10)
	s_barrier
	s_waitcnt lgkmcnt(0)
	v_mfma_f32_16x16x32_bf16 v[92:95], v[196:199], v[162:165], v[92:95]
	v_mfma_f32_16x16x32_bf16 v[88:91], v[204:207], v[162:165], v[88:91]
	v_mfma_f32_16x16x32_bf16 v[80:83], v[204:207], v[170:173], v[80:83]
	v_mfma_f32_16x16x32_bf16 v[84:87], v[196:199], v[170:173], v[84:87]
	v_mfma_f32_16x16x32_bf16 v[76:79], v[196:199], v[180:183], v[76:79]
	v_mfma_f32_16x16x32_bf16 v[72:75], v[204:207], v[180:183], v[72:75]
	v_mfma_f32_16x16x32_bf16 v[64:67], v[204:207], v[188:191], v[64:67]
	v_mfma_f32_16x16x32_bf16 v[68:71], v[196:199], v[188:191], v[68:71]
	v_mfma_f32_16x16x32_bf16 v[92:95], v[200:203], v[166:169], v[92:95]
	v_mfma_f32_16x16x32_bf16 v[88:91], v[208:211], v[166:169], v[88:91]
	v_mfma_f32_16x16x32_bf16 v[80:83], v[208:211], v[176:179], v[80:83]
	v_mfma_f32_16x16x32_bf16 v[84:87], v[200:203], v[176:179], v[84:87]
	v_mfma_f32_16x16x32_bf16 v[76:79], v[200:203], v[184:187], v[76:79]
	v_mfma_f32_16x16x32_bf16 v[72:75], v[208:211], v[184:187], v[72:75]
	v_mfma_f32_16x16x32_bf16 v[64:67], v[208:211], v[192:195], v[64:67]
	v_mfma_f32_16x16x32_bf16 v[68:71], v[200:203], v[192:195], v[68:71]
	s_mov_b32 m0, s52
	s_add_i32 s73, s75, 0xc000
	s_barrier
	ds_read_b128 v[162:165], v134 offset:49152
	ds_read_b128 v[166:169], v134 offset:50176
	ds_read_b128 v[170:173], v135 offset:49152
	ds_read_b128 v[176:179], v135 offset:50176
	ds_read_b128 v[180:183], v136 offset:49152
	ds_read_b128 v[184:187], v136 offset:50176
	ds_read_b128 v[188:191], v137 offset:49152
	ds_read_b128 v[192:195], v137 offset:50176
	buffer_load_dwordx4 v130, s[0:3], s73 offen lds
	s_add_i32 s75, s75, 0xe000
	s_mov_b32 m0, s53
	s_nop 0
	buffer_load_dwordx4 v130, s[0:3], s75 offen lds
	s_barrier
; #define LDA(dst, b, h)                                                                                               \
;   _Pragma("unroll") for (int m = 0; m < 4; ++m) _Pragma("unroll") for (int k = 0; k < 2; ++k) dst[m][k] =            \
;       *reinterpret_cast<const bf16x8*>(SA(b, h) + lds_byte(wr * 64 + m * 16 + fr, k * 32 + fq * 8))
; #define LDB(dst, b, h)                                                                                               \
;   _Pragma("unroll") for (int n = 0; n < 2; ++n) _Pragma("unroll") for (int k = 0; k < 2; ++k) dst[n][k] =            \
;       *reinterpret_cast<const bf16x8*>(SB(b, h) + lds_byte(wc * 32 + n * 16 + fr, k * 32 + fq * 8))
; #define WAIT_V(n) asm volatile("s_waitcnt vmcnt(" #n ")" ::: "memory")
; #define WAIT_L(n) asm volatile("s_waitcnt lgkmcnt(" #n ")" ::: "memory")
; #define BAR __builtin_amdgcn_s_barrier()
; #define SCHED __builtin_amdgcn_sched_barrier(0)
; template <int EPI>
; __device__ __forceinline__ void gemm_phase(const u16* __restrict__ A, const u16* __restrict__ Bt, const int K,
;                                            const int nN, char* shm, const EpiArgs& ea) {
;     ...
;       WAIT_V(10); BAR; WAIT_L(0); MMA(0, 1, At, B1); BAR;
;       LDA(At, 1, 1); STAGE(SA(1, 0), rA, brow, t + 3);
;       BAR; WAIT_L(0); MMA(1, 0, At, B0); BAR; SCHED;
;       STAGE(SB(1, 1), rB, bcol + HALF, t + 3);
;       WAIT_V(10); BAR; MMA(1, 1, At, B1); BAR;
;     }
;     float eC = 0.f, eB = 0.f;
;     float2 eS = make_float2(0.f, 0.f);
;     if (EPI == EPI_IN || EPI == EPI_SWIGLU_LN) {
;       if (wr == 0) {
;         eC = ea.c1[bcol + tid];
;         eS = *(const float2*)(ea.st_in + (size_t)(brow + tid) * 2);
;       } else {
;         eC = ea.c2[bcol + tid - 256];
;         if (EPI == EPI_IN) eB = ea.bias[bcol + tid - 256];
;       }
;     }
;     {
;       LDB(B0, 0, 0); LDA(At, 0, 0); STAGE(SA(1, 1), rA, brow + HALF, nt - 1);
;       WAIT_V(10); BAR; WAIT_L(0); MMA(0, 0, At, B0); BAR;
;       LDB(B1, 0, 1); WAIT_V(8); BAR; WAIT_L(0); MMA(0, 1, At, B1); BAR;
;       LDA(At, 0, 1); WAIT_V(4); BAR; WAIT_L(0); MMA(1, 0, At, B0); MMA(1, 1, At, B1); BAR;
	s_waitcnt lgkmcnt(0)
	v_mfma_f32_16x16x32_bf16 v[60:63], v[142:145], v[162:165], v[60:63]
	v_mfma_f32_16x16x32_bf16 v[56:59], v[150:153], v[162:165], v[56:59]
	v_mfma_f32_16x16x32_bf16 v[48:51], v[150:153], v[170:173], v[48:51]
	v_mfma_f32_16x16x32_bf16 v[52:55], v[142:145], v[170:173], v[52:55]
	v_mfma_f32_16x16x32_bf16 v[44:47], v[142:145], v[180:183], v[44:47]
	v_mfma_f32_16x16x32_bf16 v[40:43], v[150:153], v[180:183], v[40:43]
	v_mfma_f32_16x16x32_bf16 v[32:35], v[150:153], v[188:191], v[32:35]
	v_mfma_f32_16x16x32_bf16 v[36:39], v[142:145], v[188:191], v[36:39]
	v_mfma_f32_16x16x32_bf16 v[60:63], v[146:149], v[166:169], v[60:63]
	v_mfma_f32_16x16x32_bf16 v[56:59], v[154:157], v[166:169], v[56:59]
	v_mfma_f32_16x16x32_bf16 v[48:51], v[154:157], v[176:179], v[48:51]
	v_mfma_f32_16x16x32_bf16 v[52:55], v[146:149], v[176:179], v[52:55]
	v_mfma_f32_16x16x32_bf16 v[44:47], v[146:149], v[184:187], v[44:47]
	v_mfma_f32_16x16x32_bf16 v[40:43], v[154:157], v[184:187], v[40:43]
	v_mfma_f32_16x16x32_bf16 v[32:35], v[154:157], v[192:195], v[32:35]
	v_mfma_f32_16x16x32_bf16 v[36:39], v[146:149], v[192:195], v[36:39]
	s_barrier
	s_mov_b32 m0, s54
	s_add_i32 s73, s78, 0xc000
	buffer_load_dwordx4 v130, s[4:7], s73 offen lds
	s_add_i32 s78, s78, 0xe000
	s_mov_b32 m0, s55
	s_nop 0
	buffer_load_dwordx4 v130, s[4:7], s78 offen lds
	s_waitcnt vmcnt(10)
	s_barrier
	v_mfma_f32_16x16x32_bf16 v[28:31], v[196:199], v[162:165], v[28:31]
	v_mfma_f32_16x16x32_bf16 v[24:27], v[204:207], v[162:165], v[24:27]
	v_mfma_f32_16x16x32_bf16 v[16:19], v[204:207], v[170:173], v[16:19]
	v_mfma_f32_16x16x32_bf16 v[20:23], v[196:199], v[170:173], v[20:23]
	v_mfma_f32_16x16x32_bf16 v[12:15], v[196:199], v[180:183], v[12:15]
	v_mfma_f32_16x16x32_bf16 v[8:11], v[204:207], v[180:183], v[8:11]
	v_mfma_f32_16x16x32_bf16 v[0:3], v[204:207], v[188:191], v[0:3]
	v_mfma_f32_16x16x32_bf16 v[4:7], v[196:199], v[188:191], v[4:7]
	v_mfma_f32_16x16x32_bf16 v[28:31], v[200:203], v[166:169], v[28:31]
	v_mfma_f32_16x16x32_bf16 v[24:27], v[208:211], v[166:169], v[24:27]
	v_mfma_f32_16x16x32_bf16 v[16:19], v[208:211], v[176:179], v[16:19]
	v_mfma_f32_16x16x32_bf16 v[20:23], v[200:203], v[176:179], v[20:23]
	v_mfma_f32_16x16x32_bf16 v[12:15], v[200:203], v[184:187], v[12:15]
	v_mfma_f32_16x16x32_bf16 v[8:11], v[208:211], v[184:187], v[8:11]
	v_mfma_f32_16x16x32_bf16 v[0:3], v[208:211], v[192:195], v[0:3]
	v_mfma_f32_16x16x32_bf16 v[4:7], v[200:203], v[192:195], v[4:7]
	s_add_i32 s71, s71, 2
	s_add_i32 s72, s72, 0x8000
	s_cmp_lt_u32 s71, 28
	s_barrier
	s_cbranch_scc1 .LBB0_172
	s_mov_b32 m0, s57
	s_add_i32 s6, s67, 0x7c000
	ds_read_b128 v[142:145], v133
	ds_read_b128 v[146:149], v133 offset:1024
	ds_read_b128 v[150:153], v133 offset:2048
	ds_read_b128 v[154:157], v133 offset:3072
	ds_read_b128 v[162:165], v134
	ds_read_b128 v[166:169], v134 offset:1024
	ds_read_b128 v[170:173], v135
	ds_read_b128 v[176:179], v135 offset:1024
	ds_read_b128 v[180:183], v136
	ds_read_b128 v[184:187], v136 offset:1024
	ds_read_b128 v[188:191], v137
	ds_read_b128 v[192:195], v137 offset:1024
	buffer_load_dwordx4 v130, s[0:3], s6 offen lds
	s_add_i32 s67, s67, 0x7e000
	s_mov_b32 m0, s58
	s_nop 0
	buffer_load_dwordx4 v130, s[0:3], s67 offen lds
	s_waitcnt vmcnt(10)
	s_barrier
	s_waitcnt lgkmcnt(0)
	v_mfma_f32_16x16x32_bf16 v[124:127], v[142:145], v[162:165], v[124:127]
	v_mfma_f32_16x16x32_bf16 v[120:123], v[150:153], v[162:165], v[120:123]
	v_mfma_f32_16x16x32_bf16 v[112:115], v[150:153], v[170:173], v[112:115]
	v_mfma_f32_16x16x32_bf16 v[116:119], v[142:145], v[170:173], v[116:119]
	v_mfma_f32_16x16x32_bf16 v[108:111], v[142:145], v[180:183], v[108:111]
	v_mfma_f32_16x16x32_bf16 v[104:107], v[150:153], v[180:183], v[104:107]
	v_mfma_f32_16x16x32_bf16 v[96:99], v[150:153], v[188:191], v[96:99]
	v_mfma_f32_16x16x32_bf16 v[100:103], v[142:145], v[188:191], v[100:103]
	v_mfma_f32_16x16x32_bf16 v[124:127], v[146:149], v[166:169], v[124:127]
	v_mfma_f32_16x16x32_bf16 v[120:123], v[154:157], v[166:169], v[120:123]
	v_mfma_f32_16x16x32_bf16 v[112:115], v[154:157], v[176:179], v[112:115]
	v_mfma_f32_16x16x32_bf16 v[116:119], v[146:149], v[176:179], v[116:119]
	v_mfma_f32_16x16x32_bf16 v[108:111], v[146:149], v[184:187], v[108:111]
	v_mfma_f32_16x16x32_bf16 v[104:107], v[154:157], v[184:187], v[104:107]
	v_mfma_f32_16x16x32_bf16 v[96:99], v[154:157], v[192:195], v[96:99]
	v_mfma_f32_16x16x32_bf16 v[100:103], v[146:149], v[192:195], v[100:103]
	s_barrier
	ds_read_b128 v[196:199], v138
	ds_read_b128 v[200:203], v138 offset:1024
	ds_read_b128 v[204:207], v138 offset:2048
	ds_read_b128 v[208:211], v138 offset:3072
	s_waitcnt vmcnt(8)
	s_barrier
	s_waitcnt lgkmcnt(0)
	v_mfma_f32_16x16x32_bf16 v[76:79], v[196:199], v[180:183], v[76:79]
	v_mfma_f32_16x16x32_bf16 v[72:75], v[204:207], v[180:183], v[72:75]
	v_mfma_f32_16x16x32_bf16 v[64:67], v[204:207], v[188:191], v[64:67]
	v_mfma_f32_16x16x32_bf16 v[68:71], v[196:199], v[188:191], v[68:71]
	v_mfma_f32_16x16x32_bf16 v[92:95], v[196:199], v[162:165], v[92:95]
	v_mfma_f32_16x16x32_bf16 v[88:91], v[204:207], v[162:165], v[88:91]
	v_mfma_f32_16x16x32_bf16 v[80:83], v[204:207], v[170:173], v[80:83]
	v_mfma_f32_16x16x32_bf16 v[84:87], v[196:199], v[170:173], v[84:87]
	v_mfma_f32_16x16x32_bf16 v[76:79], v[200:203], v[184:187], v[76:79]
	v_mfma_f32_16x16x32_bf16 v[72:75], v[208:211], v[184:187], v[72:75]
	v_mfma_f32_16x16x32_bf16 v[64:67], v[208:211], v[192:195], v[64:67]
	v_mfma_f32_16x16x32_bf16 v[68:71], v[200:203], v[192:195], v[68:71]
	v_mfma_f32_16x16x32_bf16 v[212:215], v[200:203], v[166:169], v[92:95]
	v_mfma_f32_16x16x32_bf16 v[162:165], v[208:211], v[166:169], v[88:91]
	v_mfma_f32_16x16x32_bf16 v[166:169], v[200:203], v[176:179], v[84:87]
	v_mfma_f32_16x16x32_bf16 v[170:173], v[208:211], v[176:179], v[80:83]
	s_barrier
; #define LDA(dst, b, h)                                                                                               \
;   _Pragma("unroll") for (int m = 0; m < 4; ++m) _Pragma("unroll") for (int k = 0; k < 2; ++k) dst[m][k] =            \
;       *reinterpret_cast<const bf16x8*>(SA(b, h) + lds_byte(wr * 64 + m * 16 + fr, k * 32 + fq * 8))
; #define LDB(dst, b, h)                                                                                               \
;   _Pragma("unroll") for (int n = 0; n < 2; ++n) _Pragma("unroll") for (int k = 0; k < 2; ++k) dst[n][k] =            \
;       *reinterpret_cast<const bf16x8*>(SB(b, h) + lds_byte(wc * 32 + n * 16 + fr, k * 32 + fq * 8))
; #define WAIT_V(n) asm volatile("s_waitcnt vmcnt(" #n ")" ::: "memory")
; #define WAIT_L(n) asm volatile("s_waitcnt lgkmcnt(" #n ")" ::: "memory")
; #define BAR __builtin_amdgcn_s_barrier()
; template <int EPI>
; __device__ __forceinline__ void gemm_phase(const u16* __restrict__ A, const u16* __restrict__ Bt, const int K,
;                                            const int nN, char* shm, const EpiArgs& ea) {
;     ...
;       LDB(B0, 0, 0); LDA(At, 0, 0); STAGE(SA(1, 1), rA, brow + HALF, nt - 1);
;       WAIT_V(10); BAR; WAIT_L(0); MMA(0, 0, At, B0); BAR;
;       LDB(B1, 0, 1); WAIT_V(8); BAR; WAIT_L(0); MMA(0, 1, At, B1); BAR;
;       LDA(At, 0, 1); WAIT_V(4); BAR; WAIT_L(0); MMA(1, 0, At, B0); MMA(1, 1, At, B1); BAR;
;     }
;     {
;       LDB(B0, 1, 0); LDA(At, 1, 0); WAIT_V(2); BAR; WAIT_L(0); MMA(0, 0, At, B0); BAR;
	s_nop 0
	ds_read_b128 v[80:83], v134 offset:16384
	ds_read_b128 v[84:87], v134 offset:17408
	ds_read_b128 v[88:91], v135 offset:16384
	ds_read_b128 v[92:95], v135 offset:17408
	ds_read_b128 v[176:179], v136 offset:16384
	ds_read_b128 v[180:183], v136 offset:17408
	ds_read_b128 v[184:187], v137 offset:16384
	ds_read_b128 v[188:191], v137 offset:17408
	s_waitcnt vmcnt(4)
	s_barrier
	s_waitcnt lgkmcnt(0)
	v_mfma_f32_16x16x32_bf16 v[60:63], v[142:145], v[80:83], v[60:63]
	v_mfma_f32_16x16x32_bf16 v[56:59], v[150:153], v[80:83], v[56:59]
	v_mfma_f32_16x16x32_bf16 v[48:51], v[150:153], v[88:91], v[48:51]
	v_mfma_f32_16x16x32_bf16 v[52:55], v[142:145], v[88:91], v[52:55]
	v_mfma_f32_16x16x32_bf16 v[44:47], v[142:145], v[176:179], v[44:47]
	v_mfma_f32_16x16x32_bf16 v[40:43], v[150:153], v[176:179], v[40:43]
	v_mfma_f32_16x16x32_bf16 v[32:35], v[150:153], v[184:187], v[32:35]
	v_mfma_f32_16x16x32_bf16 v[36:39], v[142:145], v[184:187], v[36:39]
	v_mfma_f32_16x16x32_bf16 v[60:63], v[146:149], v[84:87], v[60:63]
	v_mfma_f32_16x16x32_bf16 v[56:59], v[154:157], v[84:87], v[56:59]
	v_mfma_f32_16x16x32_bf16 v[48:51], v[154:157], v[92:95], v[48:51]
	v_mfma_f32_16x16x32_bf16 v[52:55], v[146:149], v[92:95], v[52:55]
	v_mfma_f32_16x16x32_bf16 v[44:47], v[146:149], v[180:183], v[44:47]
	v_mfma_f32_16x16x32_bf16 v[40:43], v[154:157], v[180:183], v[40:43]
	v_mfma_f32_16x16x32_bf16 v[32:35], v[154:157], v[188:191], v[32:35]
	v_mfma_f32_16x16x32_bf16 v[36:39], v[146:149], v[188:191], v[36:39]
	v_mfma_f32_16x16x32_bf16 v[12:15], v[196:199], v[176:179], v[12:15]
	v_mfma_f32_16x16x32_bf16 v[8:11], v[204:207], v[176:179], v[8:11]
	v_mfma_f32_16x16x32_bf16 v[0:3], v[204:207], v[184:187], v[0:3]
	v_mfma_f32_16x16x32_bf16 v[4:7], v[196:199], v[184:187], v[4:7]
	v_mfma_f32_16x16x32_bf16 v[28:31], v[196:199], v[80:83], v[28:31]
	v_mfma_f32_16x16x32_bf16 v[24:27], v[204:207], v[80:83], v[24:27]
	v_mfma_f32_16x16x32_bf16 v[16:19], v[204:207], v[88:91], v[16:19]
	v_mfma_f32_16x16x32_bf16 v[20:23], v[196:199], v[88:91], v[20:23]
	v_mfma_f32_16x16x32_bf16 v[12:15], v[200:203], v[180:183], v[12:15]
	v_mfma_f32_16x16x32_bf16 v[8:11], v[208:211], v[180:183], v[8:11]
	v_mfma_f32_16x16x32_bf16 v[0:3], v[208:211], v[188:191], v[0:3]
	v_mfma_f32_16x16x32_bf16 v[4:7], v[200:203], v[188:191], v[4:7]
	v_mfma_f32_16x16x32_bf16 v[142:145], v[200:203], v[84:87], v[28:31]
	v_mfma_f32_16x16x32_bf16 v[146:149], v[208:211], v[84:87], v[24:27]
	v_mfma_f32_16x16x32_bf16 v[150:153], v[200:203], v[92:95], v[20:23]
	v_mfma_f32_16x16x32_bf16 v[154:157], v[208:211], v[92:95], v[16:19]
	s_barrier
	s_nop 0
	ds_read_b128 v[16:19], v139
	ds_read_b128 v[20:23], v139 offset:1024
	ds_read_b128 v[176:179], v139 offset:2048
	ds_read_b128 v[180:183], v139 offset:3072
	ds_read_b128 v[24:27], v134 offset:32768
	ds_read_b128 v[28:31], v134 offset:33792
	ds_read_b128 v[184:187], v135 offset:32768
	ds_read_b128 v[188:191], v135 offset:33792
	ds_read_b128 v[192:195], v136 offset:32768
	ds_read_b128 v[196:199], v136 offset:33792
	ds_read_b128 v[200:203], v137 offset:32768
	ds_read_b128 v[204:207], v137 offset:33792
	s_waitcnt vmcnt(2)
	s_barrier
	s_waitcnt lgkmcnt(0)
	v_mfma_f32_16x16x32_bf16 v[80:83], v[16:19], v[24:27], v[124:127]
	v_mfma_f32_16x16x32_bf16 v[124:127], v[20:23], v[28:31], v[80:83]
	v_mfma_f32_16x16x32_bf16 v[80:83], v[176:179], v[24:27], v[120:123]
	v_mfma_f32_16x16x32_bf16 v[120:123], v[180:183], v[28:31], v[80:83]
	v_mfma_f32_16x16x32_bf16 v[80:83], v[16:19], v[184:187], v[116:119]
	v_mfma_f32_16x16x32_bf16 v[116:119], v[20:23], v[188:191], v[80:83]
	v_mfma_f32_16x16x32_bf16 v[80:83], v[176:179], v[184:187], v[112:115]
	v_mfma_f32_16x16x32_bf16 v[112:115], v[180:183], v[188:191], v[80:83]
	v_mfma_f32_16x16x32_bf16 v[80:83], v[16:19], v[192:195], v[108:111]
	v_mfma_f32_16x16x32_bf16 v[92:95], v[20:23], v[196:199], v[80:83]
	v_mfma_f32_16x16x32_bf16 v[80:83], v[176:179], v[192:195], v[104:107]
	v_mfma_f32_16x16x32_bf16 v[88:91], v[180:183], v[196:199], v[80:83]
	v_mfma_f32_16x16x32_bf16 v[80:83], v[16:19], v[200:203], v[100:103]
	v_mfma_f32_16x16x32_bf16 v[84:87], v[20:23], v[204:207], v[80:83]
	v_mfma_f32_16x16x32_bf16 v[80:83], v[176:179], v[200:203], v[96:99]
	v_mfma_f32_16x16x32_bf16 v[80:83], v[180:183], v[204:207], v[80:83]
	s_barrier
; #define LDA(dst, b, h)                                                                                               \
;   _Pragma("unroll") for (int m = 0; m < 4; ++m) _Pragma("unroll") for (int k = 0; k < 2; ++k) dst[m][k] =            \
;       *reinterpret_cast<const bf16x8*>(SA(b, h) + lds_byte(wr * 64 + m * 16 + fr, k * 32 + fq * 8))
; #define LDB(dst, b, h)                                                                                               \
;   _Pragma("unroll") for (int n = 0; n < 2; ++n) _Pragma("unroll") for (int k = 0; k < 2; ++k) dst[n][k] =            \
;       *reinterpret_cast<const bf16x8*>(SB(b, h) + lds_byte(wc * 32 + n * 16 + fr, k * 32 + fq * 8))
; #define WAIT_V(n) asm volatile("s_waitcnt vmcnt(" #n ")" ::: "memory")
; #define WAIT_L(n) asm volatile("s_waitcnt lgkmcnt(" #n ")" ::: "memory")
; #define BAR __builtin_amdgcn_s_barrier()
; template <int EPI>
; __device__ __forceinline__ void gemm_phase(const u16* __restrict__ A, const u16* __restrict__ Bt, const int K,
;                                            const int nN, char* shm, const EpiArgs& ea) {
;     ...
;       LDB(B0, 1, 0); LDA(At, 1, 0); WAIT_V(2); BAR; WAIT_L(0); MMA(0, 0, At, B0); BAR;
;       LDB(B1, 1, 1); WAIT_V(0); BAR; WAIT_L(0); MMA(0, 1, At, B1); BAR;
;       LDA(At, 1, 1); BAR; WAIT_L(0); MMA(1, 0, At, B0); MMA(1, 1, At, B1); BAR;
;     }
;     if (wr == 0) BAR;
	ds_read_b128 v[208:211], v140
	ds_read_b128 v[216:219], v140 offset:1024
	ds_read_b128 v[220:223], v140 offset:2048
	ds_read_b128 v[224:227], v140 offset:3072
	s_waitcnt vmcnt(0)
	s_barrier
	s_waitcnt lgkmcnt(0)
	v_mfma_f32_16x16x32_bf16 v[96:99], v[208:211], v[24:27], v[212:215]
	v_mfma_f32_16x16x32_bf16 v[24:27], v[220:223], v[24:27], v[162:165]
	v_mfma_f32_16x16x32_bf16 v[104:107], v[224:227], v[28:31], v[24:27]
	v_mfma_f32_16x16x32_bf16 v[24:27], v[208:211], v[184:187], v[166:169]
	v_mfma_f32_16x16x32_bf16 v[100:103], v[216:219], v[188:191], v[24:27]
	v_mfma_f32_16x16x32_bf16 v[24:27], v[220:223], v[184:187], v[170:173]
	v_mfma_f32_16x16x32_bf16 v[108:111], v[216:219], v[28:31], v[96:99]
	v_mfma_f32_16x16x32_bf16 v[96:99], v[224:227], v[188:191], v[24:27]
	v_mfma_f32_16x16x32_bf16 v[24:27], v[208:211], v[192:195], v[76:79]
	v_mfma_f32_16x16x32_bf16 v[76:79], v[216:219], v[196:199], v[24:27]
	v_mfma_f32_16x16x32_bf16 v[24:27], v[220:223], v[192:195], v[72:75]
	v_mfma_f32_16x16x32_bf16 v[72:75], v[224:227], v[196:199], v[24:27]
	v_mfma_f32_16x16x32_bf16 v[24:27], v[208:211], v[200:203], v[68:71]
	v_mfma_f32_16x16x32_bf16 v[68:71], v[216:219], v[204:207], v[24:27]
	v_mfma_f32_16x16x32_bf16 v[24:27], v[220:223], v[200:203], v[64:67]
	v_mfma_f32_16x16x32_bf16 v[64:67], v[224:227], v[204:207], v[24:27]
	s_barrier
	ds_read_b128 v[162:165], v134 offset:49152
	ds_read_b128 v[166:169], v134 offset:50176
	ds_read_b128 v[170:173], v135 offset:49152
	ds_read_b128 v[184:187], v135 offset:50176
	ds_read_b128 v[188:191], v136 offset:49152
	ds_read_b128 v[192:195], v136 offset:50176
	ds_read_b128 v[196:199], v137 offset:49152
	ds_read_b128 v[200:203], v137 offset:50176
	s_barrier
	s_waitcnt lgkmcnt(0)
	v_mfma_f32_16x16x32_bf16 v[24:27], v[16:19], v[162:165], v[60:63]
	v_mfma_f32_16x16x32_bf16 v[60:63], v[20:23], v[166:169], v[24:27]
	v_mfma_f32_16x16x32_bf16 v[24:27], v[176:179], v[162:165], v[56:59]
	v_mfma_f32_16x16x32_bf16 v[56:59], v[180:183], v[166:169], v[24:27]
	v_mfma_f32_16x16x32_bf16 v[24:27], v[16:19], v[170:173], v[52:55]
	v_mfma_f32_16x16x32_bf16 v[52:55], v[20:23], v[184:187], v[24:27]
	v_mfma_f32_16x16x32_bf16 v[24:27], v[176:179], v[170:173], v[48:51]
	v_mfma_f32_16x16x32_bf16 v[48:51], v[180:183], v[184:187], v[24:27]
	v_mfma_f32_16x16x32_bf16 v[24:27], v[16:19], v[188:191], v[44:47]
	v_mfma_f32_16x16x32_bf16 v[16:19], v[16:19], v[196:199], v[36:39]
	v_mfma_f32_16x16x32_bf16 v[28:31], v[20:23], v[192:195], v[24:27]
	v_mfma_f32_16x16x32_bf16 v[24:27], v[176:179], v[188:191], v[40:43]
	v_mfma_f32_16x16x32_bf16 v[20:23], v[20:23], v[200:203], v[16:19]
	v_mfma_f32_16x16x32_bf16 v[16:19], v[176:179], v[196:199], v[32:35]
	v_mfma_f32_16x16x32_bf16 v[24:27], v[180:183], v[192:195], v[24:27]
	v_mfma_f32_16x16x32_bf16 v[16:19], v[180:183], v[200:203], v[16:19]
	v_mfma_f32_16x16x32_bf16 v[32:35], v[208:211], v[162:165], v[142:145]
	v_mfma_f32_16x16x32_bf16 v[44:47], v[216:219], v[166:169], v[32:35]
	v_mfma_f32_16x16x32_bf16 v[32:35], v[220:223], v[162:165], v[146:149]
	v_mfma_f32_16x16x32_bf16 v[40:43], v[224:227], v[166:169], v[32:35]
	v_mfma_f32_16x16x32_bf16 v[32:35], v[208:211], v[170:173], v[150:153]
	v_mfma_f32_16x16x32_bf16 v[36:39], v[216:219], v[184:187], v[32:35]
	v_mfma_f32_16x16x32_bf16 v[32:35], v[220:223], v[170:173], v[154:157]
	v_mfma_f32_16x16x32_bf16 v[12:15], v[208:211], v[188:191], v[12:15]
	v_mfma_f32_16x16x32_bf16 v[8:11], v[220:223], v[188:191], v[8:11]
	v_mfma_f32_16x16x32_bf16 v[0:3], v[220:223], v[196:199], v[0:3]
	v_mfma_f32_16x16x32_bf16 v[4:7], v[208:211], v[196:199], v[4:7]
	v_mfma_f32_16x16x32_bf16 v[32:35], v[224:227], v[184:187], v[32:35]
	v_mfma_f32_16x16x32_bf16 v[12:15], v[216:219], v[192:195], v[12:15]
	v_mfma_f32_16x16x32_bf16 v[8:11], v[224:227], v[192:195], v[8:11]
	v_mfma_f32_16x16x32_bf16 v[0:3], v[224:227], v[200:203], v[0:3]
	v_mfma_f32_16x16x32_bf16 v[4:7], v[216:219], v[200:203], v[4:7]
	s_andn2_b64 vcc, exec, s[26:27]
	s_barrier
	s_cbranch_vccnz .LBB0_175
	s_barrier

; #define LDA(dst, b, h)                                                                                               \
;   _Pragma("unroll") for (int m = 0; m < 4; ++m) _Pragma("unroll") for (int k = 0; k < 2; ++k) dst[m][k] =            \
;       *reinterpret_cast<const bf16x8*>(SA(b, h) + lds_byte(wr * 64 + m * 16 + fr, k * 32 + fq * 8))
; #define LDB(dst, b, h)                                                                                               \
;   _Pragma("unroll") for (int n = 0; n < 2; ++n) _Pragma("unroll") for (int k = 0; k < 2; ++k) dst[n][k] =            \
;       *reinterpret_cast<const bf16x8*>(SB(b, h) + lds_byte(wc * 32 + n * 16 + fr, k * 32 + fq * 8))
; #define WAIT_V(n) asm volatile("s_waitcnt vmcnt(" #n ")" ::: "memory")
; #define WAIT_L(n) asm volatile("s_waitcnt lgkmcnt(" #n ")" ::: "memory")
; #define BAR __builtin_amdgcn_s_barrier()
; #define SCHED __builtin_amdgcn_sched_barrier(0)
; template <int EPI>
; __device__ __forceinline__ void gemm_phase(const u16* __restrict__ A, const u16* __restrict__ Bt, const int K,
;                                            const int nN, char* shm, const EpiArgs& ea) {
;     ...
;     for (int t = 0; t < nt - 2; t += 2) {
;       LDB(B0, 0, 0); SCHED; LDA(At, 0, 0); STAGE(SA(1, 1), rA, brow + HALF, t + 1);
;       WAIT_V(10); WAIT_L(8); BAR; WAIT_L(0); MMA(0, 0, At, B0); BAR; SCHED;
;       LDB(B1, 0, 1); STAGE(SB(0, 0), rB, bcol, t + 2);
;       WAIT_V(10); BAR; WAIT_L(0); MMA(0, 1, At, B1); BAR;
;       LDA(At, 0, 1); STAGE(SA(0, 0), rA, brow, t + 2);
;       BAR; WAIT_L(0); MMA(1, 0, At, B0); BAR; SCHED;
;       STAGE(SB(0, 1), rB, bcol + HALF, t + 2);
;       WAIT_V(10); BAR; MMA(1, 1, At, B1); BAR;
.LBB0_231:
	ds_read_b128 v[130:133], v138
	ds_read_b128 v[146:149], v138 offset:1024
	ds_read_b128 v[150:153], v138 offset:2048
	ds_read_b128 v[154:157], v138 offset:3072
	s_add_i32 s78, s70, s75
	s_mov_b32 m0, s48
	s_add_i32 s26, s78, 0x4000
	ds_read_b128 v[162:165], v139
	ds_read_b128 v[166:169], v139 offset:1024
	ds_read_b128 v[170:173], v140
	ds_read_b128 v[176:179], v140 offset:1024
	ds_read_b128 v[180:183], v141
	ds_read_b128 v[184:187], v141 offset:1024
	ds_read_b128 v[188:191], v142
	ds_read_b128 v[192:195], v142 offset:1024
	buffer_load_dwordx4 v134, s[0:3], s26 offen lds
	s_add_i32 s26, s78, 0x6000
	s_mov_b32 m0, s49
	s_nop 0
	buffer_load_dwordx4 v134, s[0:3], s26 offen lds
	s_waitcnt vmcnt(10)
	s_waitcnt lgkmcnt(8)
	s_barrier
	s_waitcnt lgkmcnt(0)
	v_mfma_f32_16x16x32_bf16 v[124:127], v[130:133], v[162:165], v[124:127]
	v_mfma_f32_16x16x32_bf16 v[120:123], v[150:153], v[162:165], v[120:123]
	v_mfma_f32_16x16x32_bf16 v[112:115], v[150:153], v[170:173], v[112:115]
	v_mfma_f32_16x16x32_bf16 v[116:119], v[130:133], v[170:173], v[116:119]
	v_mfma_f32_16x16x32_bf16 v[108:111], v[130:133], v[180:183], v[108:111]
	v_mfma_f32_16x16x32_bf16 v[104:107], v[150:153], v[180:183], v[104:107]
	v_mfma_f32_16x16x32_bf16 v[96:99], v[150:153], v[188:191], v[96:99]
	v_mfma_f32_16x16x32_bf16 v[100:103], v[130:133], v[188:191], v[100:103]
	v_mfma_f32_16x16x32_bf16 v[124:127], v[146:149], v[166:169], v[124:127]
	v_mfma_f32_16x16x32_bf16 v[120:123], v[154:157], v[166:169], v[120:123]
	v_mfma_f32_16x16x32_bf16 v[112:115], v[154:157], v[176:179], v[112:115]
	v_mfma_f32_16x16x32_bf16 v[116:119], v[146:149], v[176:179], v[116:119]
	v_mfma_f32_16x16x32_bf16 v[108:111], v[146:149], v[184:187], v[108:111]
	v_mfma_f32_16x16x32_bf16 v[104:107], v[154:157], v[184:187], v[104:107]
	v_mfma_f32_16x16x32_bf16 v[96:99], v[154:157], v[192:195], v[96:99]
	v_mfma_f32_16x16x32_bf16 v[100:103], v[146:149], v[192:195], v[100:103]
	s_barrier
	s_add_i32 s79, s73, s75
	s_mov_b32 m0, s52
	s_add_i32 s80, s79, 0x8000
	s_mov_b32 s26, s2
	s_mov_b32 s27, s3
	ds_read_b128 v[196:199], v143
	ds_read_b128 v[200:203], v143 offset:1024
	ds_read_b128 v[204:207], v143 offset:2048
	ds_read_b128 v[208:211], v143 offset:3072
	buffer_load_dwordx4 v134, s[24:27], s80 offen lds
	s_add_i32 s80, s79, 0xa000
	s_mov_b32 m0, s53
	s_nop 0
	buffer_load_dwordx4 v134, s[24:27], s80 offen lds
	s_waitcnt vmcnt(10)
	s_barrier
	s_waitcnt lgkmcnt(0)
	v_mfma_f32_16x16x32_bf16 v[92:95], v[196:199], v[162:165], v[92:95]
	v_mfma_f32_16x16x32_bf16 v[88:91], v[204:207], v[162:165], v[88:91]
	v_mfma_f32_16x16x32_bf16 v[80:83], v[204:207], v[170:173], v[80:83]
	v_mfma_f32_16x16x32_bf16 v[84:87], v[196:199], v[170:173], v[84:87]
	v_mfma_f32_16x16x32_bf16 v[76:79], v[196:199], v[180:183], v[76:79]
	v_mfma_f32_16x16x32_bf16 v[72:75], v[204:207], v[180:183], v[72:75]
	v_mfma_f32_16x16x32_bf16 v[64:67], v[204:207], v[188:191], v[64:67]
	v_mfma_f32_16x16x32_bf16 v[68:71], v[196:199], v[188:191], v[68:71]
	v_mfma_f32_16x16x32_bf16 v[92:95], v[200:203], v[166:169], v[92:95]
	v_mfma_f32_16x16x32_bf16 v[88:91], v[208:211], v[166:169], v[88:91]
	v_mfma_f32_16x16x32_bf16 v[80:83], v[208:211], v[176:179], v[80:83]
	v_mfma_f32_16x16x32_bf16 v[84:87], v[200:203], v[176:179], v[84:87]
	v_mfma_f32_16x16x32_bf16 v[76:79], v[200:203], v[184:187], v[76:79]
	v_mfma_f32_16x16x32_bf16 v[72:75], v[208:211], v[184:187], v[72:75]
	v_mfma_f32_16x16x32_bf16 v[64:67], v[208:211], v[192:195], v[64:67]
	v_mfma_f32_16x16x32_bf16 v[68:71], v[200:203], v[192:195], v[68:71]
	s_add_i32 s80, s72, s75
	s_mov_b32 m0, s43
	s_add_i32 s81, s80, 0x8000
	s_barrier
	ds_read_b128 v[162:165], v139 offset:16384
	ds_read_b128 v[166:169], v139 offset:17408
	ds_read_b128 v[170:173], v140 offset:16384
	ds_read_b128 v[176:179], v140 offset:17408
	ds_read_b128 v[180:183], v141 offset:16384
	ds_read_b128 v[184:187], v141 offset:17408
	ds_read_b128 v[188:191], v142 offset:16384
	ds_read_b128 v[192:195], v142 offset:17408
	buffer_load_dwordx4 v134, s[0:3], s81 offen lds
	s_add_i32 s81, s80, 0xa000
	s_mov_b32 m0, s54
	s_nop 0
	buffer_load_dwordx4 v134, s[0:3], s81 offen lds
	s_barrier
	s_waitcnt lgkmcnt(0)
	v_mfma_f32_16x16x32_bf16 v[60:63], v[130:133], v[162:165], v[60:63]
	v_mfma_f32_16x16x32_bf16 v[56:59], v[150:153], v[162:165], v[56:59]
	v_mfma_f32_16x16x32_bf16 v[48:51], v[150:153], v[170:173], v[48:51]
	v_mfma_f32_16x16x32_bf16 v[52:55], v[130:133], v[170:173], v[52:55]
	v_mfma_f32_16x16x32_bf16 v[44:47], v[130:133], v[180:183], v[44:47]
	v_mfma_f32_16x16x32_bf16 v[40:43], v[150:153], v[180:183], v[40:43]
	v_mfma_f32_16x16x32_bf16 v[32:35], v[150:153], v[188:191], v[32:35]
	v_mfma_f32_16x16x32_bf16 v[36:39], v[130:133], v[188:191], v[36:39]
	v_mfma_f32_16x16x32_bf16 v[60:63], v[146:149], v[166:169], v[60:63]
	v_mfma_f32_16x16x32_bf16 v[56:59], v[154:157], v[166:169], v[56:59]
	v_mfma_f32_16x16x32_bf16 v[48:51], v[154:157], v[176:179], v[48:51]
	v_mfma_f32_16x16x32_bf16 v[52:55], v[146:149], v[176:179], v[52:55]
	v_mfma_f32_16x16x32_bf16 v[44:47], v[146:149], v[184:187], v[44:47]
	v_mfma_f32_16x16x32_bf16 v[40:43], v[154:157], v[184:187], v[40:43]
	v_mfma_f32_16x16x32_bf16 v[32:35], v[154:157], v[192:195], v[32:35]
	v_mfma_f32_16x16x32_bf16 v[36:39], v[146:149], v[192:195], v[36:39]
	s_barrier
	s_add_i32 s81, s71, s75
	s_mov_b32 m0, s55
	s_add_i32 s82, s81, 0x8000
	buffer_load_dwordx4 v134, s[24:27], s82 offen lds
	s_add_i32 s82, s81, 0xa000
	s_mov_b32 m0, s56
	s_nop 0
	buffer_load_dwordx4 v134, s[24:27], s82 offen lds
	s_waitcnt vmcnt(10)
	s_barrier
; #define LDA(dst, b, h)                                                                                               \
;   _Pragma("unroll") for (int m = 0; m < 4; ++m) _Pragma("unroll") for (int k = 0; k < 2; ++k) dst[m][k] =            \
;       *reinterpret_cast<const bf16x8*>(SA(b, h) + lds_byte(wr * 64 + m * 16 + fr, k * 32 + fq * 8))
; #define LDB(dst, b, h)                                                                                               \
;   _Pragma("unroll") for (int n = 0; n < 2; ++n) _Pragma("unroll") for (int k = 0; k < 2; ++k) dst[n][k] =            \
;       *reinterpret_cast<const bf16x8*>(SB(b, h) + lds_byte(wc * 32 + n * 16 + fr, k * 32 + fq * 8))
; #define WAIT_V(n) asm volatile("s_waitcnt vmcnt(" #n ")" ::: "memory")
; #define WAIT_L(n) asm volatile("s_waitcnt lgkmcnt(" #n ")" ::: "memory")
; #define BAR __builtin_amdgcn_s_barrier()
; #define SCHED __builtin_amdgcn_sched_barrier(0)
; template <int EPI>
; __device__ __forceinline__ void gemm_phase(const u16* __restrict__ A, const u16* __restrict__ Bt, const int K,
;                                            const int nN, char* shm, const EpiArgs& ea) {
;     ...
;       WAIT_V(10); BAR; WAIT_L(0); MMA(0, 1, At, B1); BAR;
;       LDA(At, 0, 1); STAGE(SA(0, 0), rA, brow, t + 2);
;       BAR; WAIT_L(0); MMA(1, 0, At, B0); BAR; SCHED;
;       STAGE(SB(0, 1), rB, bcol + HALF, t + 2);
;       WAIT_V(10); BAR; MMA(1, 1, At, B1); BAR;
;       LDB(B0, 1, 0); SCHED; LDA(At, 1, 0); STAGE(SA(0, 1), rA, brow + HALF, t + 2);
;       WAIT_V(10); WAIT_L(8); BAR; WAIT_L(0); MMA(0, 0, At, B0); BAR; SCHED;
;       LDB(B1, 1, 1); STAGE(SB(1, 0), rB, bcol, t + 3);
;       WAIT_V(10); BAR; WAIT_L(0); MMA(0, 1, At, B1); BAR;
	v_mfma_f32_16x16x32_bf16 v[28:31], v[196:199], v[162:165], v[28:31]
	v_mfma_f32_16x16x32_bf16 v[24:27], v[204:207], v[162:165], v[24:27]
	v_mfma_f32_16x16x32_bf16 v[16:19], v[204:207], v[170:173], v[16:19]
	v_mfma_f32_16x16x32_bf16 v[20:23], v[196:199], v[170:173], v[20:23]
	v_mfma_f32_16x16x32_bf16 v[12:15], v[196:199], v[180:183], v[12:15]
	v_mfma_f32_16x16x32_bf16 v[8:11], v[204:207], v[180:183], v[8:11]
	v_mfma_f32_16x16x32_bf16 v[0:3], v[204:207], v[188:191], v[0:3]
	v_mfma_f32_16x16x32_bf16 v[4:7], v[196:199], v[188:191], v[4:7]
	v_mfma_f32_16x16x32_bf16 v[28:31], v[200:203], v[166:169], v[28:31]
	v_mfma_f32_16x16x32_bf16 v[24:27], v[208:211], v[166:169], v[24:27]
	v_mfma_f32_16x16x32_bf16 v[16:19], v[208:211], v[176:179], v[16:19]
	v_mfma_f32_16x16x32_bf16 v[20:23], v[200:203], v[176:179], v[20:23]
	v_mfma_f32_16x16x32_bf16 v[12:15], v[200:203], v[184:187], v[12:15]
	v_mfma_f32_16x16x32_bf16 v[8:11], v[208:211], v[184:187], v[8:11]
	v_mfma_f32_16x16x32_bf16 v[0:3], v[208:211], v[192:195], v[0:3]
	v_mfma_f32_16x16x32_bf16 v[4:7], v[200:203], v[192:195], v[4:7]
	s_barrier
	ds_read_b128 v[130:133], v144
	ds_read_b128 v[146:149], v144 offset:1024
	ds_read_b128 v[150:153], v144 offset:2048
	ds_read_b128 v[154:157], v144 offset:3072
	s_mov_b32 m0, s57
	s_add_i32 s82, s78, 0x8000
	ds_read_b128 v[162:165], v139 offset:32768
	ds_read_b128 v[166:169], v139 offset:33792
	ds_read_b128 v[170:173], v140 offset:32768
	ds_read_b128 v[176:179], v140 offset:33792
	ds_read_b128 v[180:183], v141 offset:32768
	ds_read_b128 v[184:187], v141 offset:33792
	ds_read_b128 v[188:191], v142 offset:32768
	ds_read_b128 v[192:195], v142 offset:33792
	buffer_load_dwordx4 v134, s[0:3], s82 offen lds
	s_add_i32 s78, s78, 0xa000
	s_mov_b32 m0, s58
	s_nop 0
	buffer_load_dwordx4 v134, s[0:3], s78 offen lds
	s_waitcnt vmcnt(10)
	s_waitcnt lgkmcnt(8)
	s_barrier
	s_waitcnt lgkmcnt(0)
	v_mfma_f32_16x16x32_bf16 v[124:127], v[130:133], v[162:165], v[124:127]
	v_mfma_f32_16x16x32_bf16 v[120:123], v[150:153], v[162:165], v[120:123]
	v_mfma_f32_16x16x32_bf16 v[112:115], v[150:153], v[170:173], v[112:115]
	v_mfma_f32_16x16x32_bf16 v[116:119], v[130:133], v[170:173], v[116:119]
	v_mfma_f32_16x16x32_bf16 v[108:111], v[130:133], v[180:183], v[108:111]
	v_mfma_f32_16x16x32_bf16 v[104:107], v[150:153], v[180:183], v[104:107]
	v_mfma_f32_16x16x32_bf16 v[96:99], v[150:153], v[188:191], v[96:99]
	v_mfma_f32_16x16x32_bf16 v[100:103], v[130:133], v[188:191], v[100:103]
	v_mfma_f32_16x16x32_bf16 v[124:127], v[146:149], v[166:169], v[124:127]
	v_mfma_f32_16x16x32_bf16 v[120:123], v[154:157], v[166:169], v[120:123]
	v_mfma_f32_16x16x32_bf16 v[112:115], v[154:157], v[176:179], v[112:115]
	v_mfma_f32_16x16x32_bf16 v[116:119], v[146:149], v[176:179], v[116:119]
	v_mfma_f32_16x16x32_bf16 v[108:111], v[146:149], v[184:187], v[108:111]
	v_mfma_f32_16x16x32_bf16 v[104:107], v[154:157], v[184:187], v[104:107]
	v_mfma_f32_16x16x32_bf16 v[96:99], v[154:157], v[192:195], v[96:99]
	v_mfma_f32_16x16x32_bf16 v[100:103], v[146:149], v[192:195], v[100:103]
	s_barrier
	s_mov_b32 m0, s59
	s_add_i32 s78, s79, 0xc000
	ds_read_b128 v[196:199], v145
	ds_read_b128 v[200:203], v145 offset:1024
	ds_read_b128 v[204:207], v145 offset:2048
	ds_read_b128 v[208:211], v145 offset:3072
	buffer_load_dwordx4 v134, s[24:27], s78 offen lds
	s_add_i32 s79, s79, 0xe000
	s_mov_b32 m0, s60
	s_nop 0
	buffer_load_dwordx4 v134, s[24:27], s79 offen lds
	s_waitcnt vmcnt(10)
	s_barrier
	s_waitcnt lgkmcnt(0)
	v_mfma_f32_16x16x32_bf16 v[92:95], v[196:199], v[162:165], v[92:95]
	v_mfma_f32_16x16x32_bf16 v[88:91], v[204:207], v[162:165], v[88:91]
	v_mfma_f32_16x16x32_bf16 v[80:83], v[204:207], v[170:173], v[80:83]
	v_mfma_f32_16x16x32_bf16 v[84:87], v[196:199], v[170:173], v[84:87]
	v_mfma_f32_16x16x32_bf16 v[76:79], v[196:199], v[180:183], v[76:79]
	v_mfma_f32_16x16x32_bf16 v[72:75], v[204:207], v[180:183], v[72:75]
	v_mfma_f32_16x16x32_bf16 v[64:67], v[204:207], v[188:191], v[64:67]
	v_mfma_f32_16x16x32_bf16 v[68:71], v[196:199], v[188:191], v[68:71]
	v_mfma_f32_16x16x32_bf16 v[92:95], v[200:203], v[166:169], v[92:95]
	v_mfma_f32_16x16x32_bf16 v[88:91], v[208:211], v[166:169], v[88:91]
	v_mfma_f32_16x16x32_bf16 v[80:83], v[208:211], v[176:179], v[80:83]
	v_mfma_f32_16x16x32_bf16 v[84:87], v[200:203], v[176:179], v[84:87]
	v_mfma_f32_16x16x32_bf16 v[76:79], v[200:203], v[184:187], v[76:79]
	v_mfma_f32_16x16x32_bf16 v[72:75], v[208:211], v[184:187], v[72:75]
	v_mfma_f32_16x16x32_bf16 v[64:67], v[208:211], v[192:195], v[64:67]
	v_mfma_f32_16x16x32_bf16 v[68:71], v[200:203], v[192:195], v[68:71]
	s_mov_b32 m0, s61
	s_add_i32 s78, s80, 0xc000
	s_barrier
	ds_read_b128 v[162:165], v139 offset:49152
	ds_read_b128 v[166:169], v139 offset:50176
	ds_read_b128 v[170:173], v140 offset:49152
	ds_read_b128 v[176:179], v140 offset:50176
	ds_read_b128 v[180:183], v141 offset:49152
	ds_read_b128 v[184:187], v141 offset:50176
	ds_read_b128 v[188:191], v142 offset:49152
	ds_read_b128 v[192:195], v142 offset:50176
	buffer_load_dwordx4 v134, s[0:3], s78 offen lds
	s_add_i32 s80, s80, 0xe000
	s_mov_b32 m0, s62
	s_nop 0
	buffer_load_dwordx4 v134, s[0:3], s80 offen lds
	s_barrier
; #define LDA(dst, b, h)                                                                                               \
;   _Pragma("unroll") for (int m = 0; m < 4; ++m) _Pragma("unroll") for (int k = 0; k < 2; ++k) dst[m][k] =            \
;       *reinterpret_cast<const bf16x8*>(SA(b, h) + lds_byte(wr * 64 + m * 16 + fr, k * 32 + fq * 8))
; #define LDB(dst, b, h)                                                                                               \
;   _Pragma("unroll") for (int n = 0; n < 2; ++n) _Pragma("unroll") for (int k = 0; k < 2; ++k) dst[n][k] =            \
;       *reinterpret_cast<const bf16x8*>(SB(b, h) + lds_byte(wc * 32 + n * 16 + fr, k * 32 + fq * 8))
; #define WAIT_V(n) asm volatile("s_waitcnt vmcnt(" #n ")" ::: "memory")
; #define WAIT_L(n) asm volatile("s_waitcnt lgkmcnt(" #n ")" ::: "memory")
; #define BAR __builtin_amdgcn_s_barrier()
; #define SCHED __builtin_amdgcn_sched_barrier(0)
; template <int EPI>
; __device__ __forceinline__ void gemm_phase(const u16* __restrict__ A, const u16* __restrict__ Bt, const int K,
;                                            const int nN, char* shm, const EpiArgs& ea) {
;     ...
;       WAIT_V(10); BAR; WAIT_L(0); MMA(0, 1, At, B1); BAR;
;       LDA(At, 1, 1); STAGE(SA(1, 0), rA, brow, t + 3);
;       BAR; WAIT_L(0); MMA(1, 0, At, B0); BAR; SCHED;
;       STAGE(SB(1, 1), rB, bcol + HALF, t + 3);
;       WAIT_V(10); BAR; MMA(1, 1, At, B1); BAR;
;     }
;     float eC = 0.f, eB = 0.f;
;     float2 eS = make_float2(0.f, 0.f);
;     if (EPI == EPI_IN || EPI == EPI_SWIGLU_LN) {
;       if (wr == 0) {
;         eC = ea.c1[bcol + tid];
;         eS = *(const float2*)(ea.st_in + (size_t)(brow + tid) * 2);
;       } else {
;         eC = ea.c2[bcol + tid - 256];
;         if (EPI == EPI_IN) eB = ea.bias[bcol + tid - 256];
;       }
;     }
;     {
;       LDB(B0, 0, 0); LDA(At, 0, 0); STAGE(SA(1, 1), rA, brow + HALF, nt - 1);
;       WAIT_V(10); BAR; WAIT_L(0); MMA(0, 0, At, B0); BAR;
;       LDB(B1, 0, 1); WAIT_V(8); BAR; WAIT_L(0); MMA(0, 1, At, B1); BAR;
;       LDA(At, 0, 1); WAIT_V(4); BAR; WAIT_L(0); MMA(1, 0, At, B0); MMA(1, 1, At, B1); BAR;
	s_waitcnt lgkmcnt(0)
	v_mfma_f32_16x16x32_bf16 v[60:63], v[130:133], v[162:165], v[60:63]
	v_mfma_f32_16x16x32_bf16 v[56:59], v[150:153], v[162:165], v[56:59]
	v_mfma_f32_16x16x32_bf16 v[48:51], v[150:153], v[170:173], v[48:51]
	v_mfma_f32_16x16x32_bf16 v[52:55], v[130:133], v[170:173], v[52:55]
	v_mfma_f32_16x16x32_bf16 v[44:47], v[130:133], v[180:183], v[44:47]
	v_mfma_f32_16x16x32_bf16 v[40:43], v[150:153], v[180:183], v[40:43]
	v_mfma_f32_16x16x32_bf16 v[32:35], v[150:153], v[188:191], v[32:35]
	v_mfma_f32_16x16x32_bf16 v[36:39], v[130:133], v[188:191], v[36:39]
	v_mfma_f32_16x16x32_bf16 v[60:63], v[146:149], v[166:169], v[60:63]
	v_mfma_f32_16x16x32_bf16 v[56:59], v[154:157], v[166:169], v[56:59]
	v_mfma_f32_16x16x32_bf16 v[48:51], v[154:157], v[176:179], v[48:51]
	v_mfma_f32_16x16x32_bf16 v[52:55], v[146:149], v[176:179], v[52:55]
	v_mfma_f32_16x16x32_bf16 v[44:47], v[146:149], v[184:187], v[44:47]
	v_mfma_f32_16x16x32_bf16 v[40:43], v[154:157], v[184:187], v[40:43]
	v_mfma_f32_16x16x32_bf16 v[32:35], v[154:157], v[192:195], v[32:35]
	v_mfma_f32_16x16x32_bf16 v[36:39], v[146:149], v[192:195], v[36:39]
	s_barrier
	s_mov_b32 m0, s63
	s_add_i32 s78, s81, 0xc000
	buffer_load_dwordx4 v134, s[24:27], s78 offen lds
	s_add_i32 s81, s81, 0xe000
	s_mov_b32 m0, s64
	s_nop 0
	buffer_load_dwordx4 v134, s[24:27], s81 offen lds
	s_waitcnt vmcnt(10)
	s_barrier
	v_mfma_f32_16x16x32_bf16 v[28:31], v[196:199], v[162:165], v[28:31]
	v_mfma_f32_16x16x32_bf16 v[24:27], v[204:207], v[162:165], v[24:27]
	v_mfma_f32_16x16x32_bf16 v[16:19], v[204:207], v[170:173], v[16:19]
	v_mfma_f32_16x16x32_bf16 v[20:23], v[196:199], v[170:173], v[20:23]
	v_mfma_f32_16x16x32_bf16 v[12:15], v[196:199], v[180:183], v[12:15]
	v_mfma_f32_16x16x32_bf16 v[8:11], v[204:207], v[180:183], v[8:11]
	v_mfma_f32_16x16x32_bf16 v[0:3], v[204:207], v[188:191], v[0:3]
	v_mfma_f32_16x16x32_bf16 v[4:7], v[196:199], v[188:191], v[4:7]
	v_mfma_f32_16x16x32_bf16 v[28:31], v[200:203], v[166:169], v[28:31]
	v_mfma_f32_16x16x32_bf16 v[24:27], v[208:211], v[166:169], v[24:27]
	v_mfma_f32_16x16x32_bf16 v[16:19], v[208:211], v[176:179], v[16:19]
	v_mfma_f32_16x16x32_bf16 v[20:23], v[200:203], v[176:179], v[20:23]
	v_mfma_f32_16x16x32_bf16 v[12:15], v[200:203], v[184:187], v[12:15]
	v_mfma_f32_16x16x32_bf16 v[8:11], v[208:211], v[184:187], v[8:11]
	v_mfma_f32_16x16x32_bf16 v[0:3], v[208:211], v[192:195], v[0:3]
	v_mfma_f32_16x16x32_bf16 v[4:7], v[200:203], v[192:195], v[4:7]
	s_add_i32 s74, s74, 2
	s_add_i32 s75, s75, 0x8000
	s_cmpk_lt_u32 s74, 0x54
	s_barrier
	s_cbranch_scc1 .LBB0_231
	s_mov_b32 m0, s48
	s_add_i32 s26, s70, 0x15c000
	ds_read_b128 v[130:133], v138
	ds_read_b128 v[146:149], v138 offset:1024
	ds_read_b128 v[150:153], v138 offset:2048
	ds_read_b128 v[154:157], v138 offset:3072
	ds_read_b128 v[162:165], v139
	ds_read_b128 v[166:169], v139 offset:1024
	ds_read_b128 v[170:173], v140
	ds_read_b128 v[176:179], v140 offset:1024
	ds_read_b128 v[180:183], v141
	ds_read_b128 v[184:187], v141 offset:1024
	ds_read_b128 v[188:191], v142
	ds_read_b128 v[192:195], v142 offset:1024
	buffer_load_dwordx4 v134, s[0:3], s26 offen lds
	s_add_i32 s70, s70, 0x15e000
	s_mov_b32 m0, s49
	s_nop 0
	buffer_load_dwordx4 v134, s[0:3], s70 offen lds
	s_waitcnt vmcnt(10)
	s_barrier
	s_waitcnt lgkmcnt(0)
	v_mfma_f32_16x16x32_bf16 v[124:127], v[130:133], v[162:165], v[124:127]
	v_mfma_f32_16x16x32_bf16 v[116:119], v[130:133], v[170:173], v[116:119]
	v_mfma_f32_16x16x32_bf16 v[112:115], v[150:153], v[170:173], v[112:115]
	v_mfma_f32_16x16x32_bf16 v[96:99], v[150:153], v[188:191], v[96:99]
	v_mfma_f32_16x16x32_bf16 v[100:103], v[130:133], v[188:191], v[100:103]
	v_mfma_f32_16x16x32_bf16 v[124:127], v[146:149], v[166:169], v[124:127]
	v_mfma_f32_16x16x32_bf16 v[120:123], v[150:153], v[162:165], v[120:123]
	v_mfma_f32_16x16x32_bf16 v[116:119], v[146:149], v[176:179], v[116:119]
	v_mfma_f32_16x16x32_bf16 v[112:115], v[154:157], v[176:179], v[112:115]
	v_mfma_f32_16x16x32_bf16 v[108:111], v[130:133], v[180:183], v[108:111]
	v_mfma_f32_16x16x32_bf16 v[104:107], v[150:153], v[180:183], v[104:107]
	v_mfma_f32_16x16x32_bf16 v[100:103], v[146:149], v[192:195], v[100:103]
	v_mfma_f32_16x16x32_bf16 v[96:99], v[154:157], v[192:195], v[96:99]
	v_mfma_f32_16x16x32_bf16 v[196:199], v[154:157], v[166:169], v[120:123]
	v_mfma_f32_16x16x32_bf16 v[200:203], v[146:149], v[184:187], v[108:111]
	v_mfma_f32_16x16x32_bf16 v[204:207], v[154:157], v[184:187], v[104:107]
	s_barrier
	s_nop 0
	ds_read_b128 v[104:107], v143
	ds_read_b128 v[108:111], v143 offset:1024
	ds_read_b128 v[120:123], v143 offset:2048
	ds_read_b128 v[208:211], v143 offset:3072
	s_waitcnt vmcnt(8)
	s_barrier
	s_waitcnt lgkmcnt(0)
	v_mfma_f32_16x16x32_bf16 v[84:87], v[104:107], v[170:173], v[84:87]
	v_mfma_f32_16x16x32_bf16 v[80:83], v[120:123], v[170:173], v[80:83]
	v_mfma_f32_16x16x32_bf16 v[68:71], v[104:107], v[188:191], v[68:71]
	v_mfma_f32_16x16x32_bf16 v[92:95], v[104:107], v[162:165], v[92:95]
	v_mfma_f32_16x16x32_bf16 v[88:91], v[120:123], v[162:165], v[88:91]
	v_mfma_f32_16x16x32_bf16 v[84:87], v[108:111], v[176:179], v[84:87]
	v_mfma_f32_16x16x32_bf16 v[80:83], v[208:211], v[176:179], v[80:83]
	v_mfma_f32_16x16x32_bf16 v[76:79], v[104:107], v[180:183], v[76:79]
	v_mfma_f32_16x16x32_bf16 v[72:75], v[120:123], v[180:183], v[72:75]
	v_mfma_f32_16x16x32_bf16 v[68:71], v[108:111], v[192:195], v[68:71]
	v_mfma_f32_16x16x32_bf16 v[64:67], v[120:123], v[188:191], v[64:67]
	v_mfma_f32_16x16x32_bf16 v[212:215], v[108:111], v[166:169], v[92:95]
	v_mfma_f32_16x16x32_bf16 v[162:165], v[208:211], v[166:169], v[88:91]
	v_mfma_f32_16x16x32_bf16 v[166:169], v[108:111], v[184:187], v[76:79]
	v_mfma_f32_16x16x32_bf16 v[170:173], v[208:211], v[184:187], v[72:75]
	v_mfma_f32_16x16x32_bf16 v[176:179], v[208:211], v[192:195], v[64:67]
	s_barrier
; #define LDA(dst, b, h)                                                                                               \
;   _Pragma("unroll") for (int m = 0; m < 4; ++m) _Pragma("unroll") for (int k = 0; k < 2; ++k) dst[m][k] =            \
;       *reinterpret_cast<const bf16x8*>(SA(b, h) + lds_byte(wr * 64 + m * 16 + fr, k * 32 + fq * 8))
; #define LDB(dst, b, h)                                                                                               \
;   _Pragma("unroll") for (int n = 0; n < 2; ++n) _Pragma("unroll") for (int k = 0; k < 2; ++k) dst[n][k] =            \
;       *reinterpret_cast<const bf16x8*>(SB(b, h) + lds_byte(wc * 32 + n * 16 + fr, k * 32 + fq * 8))
; #define WAIT_V(n) asm volatile("s_waitcnt vmcnt(" #n ")" ::: "memory")
; #define WAIT_L(n) asm volatile("s_waitcnt lgkmcnt(" #n ")" ::: "memory")
; #define BAR __builtin_amdgcn_s_barrier()
; template <int EPI>
; __device__ __forceinline__ void gemm_phase(const u16* __restrict__ A, const u16* __restrict__ Bt, const int K,
;                                            const int nN, char* shm, const EpiArgs& ea) {
;     ...
;       LDB(B0, 0, 0); LDA(At, 0, 0); STAGE(SA(1, 1), rA, brow + HALF, nt - 1);
;       WAIT_V(10); BAR; WAIT_L(0); MMA(0, 0, At, B0); BAR;
;       LDB(B1, 0, 1); WAIT_V(8); BAR; WAIT_L(0); MMA(0, 1, At, B1); BAR;
;       LDA(At, 0, 1); WAIT_V(4); BAR; WAIT_L(0); MMA(1, 0, At, B0); MMA(1, 1, At, B1); BAR;
;     }
;     {
;       LDB(B0, 1, 0); LDA(At, 1, 0); WAIT_V(2); BAR; WAIT_L(0); MMA(0, 0, At, B0); BAR;
	s_nop 0
	ds_read_b128 v[64:67], v139 offset:16384
	ds_read_b128 v[72:75], v139 offset:17408
	ds_read_b128 v[76:79], v140 offset:16384
	ds_read_b128 v[88:91], v140 offset:17408
	ds_read_b128 v[92:95], v141 offset:16384
	ds_read_b128 v[180:183], v141 offset:17408
	ds_read_b128 v[184:187], v142 offset:16384
	ds_read_b128 v[188:191], v142 offset:17408
	s_waitcnt vmcnt(4)
	s_barrier
	s_waitcnt lgkmcnt(0)
	v_mfma_f32_16x16x32_bf16 v[60:63], v[130:133], v[64:67], v[60:63]
	v_mfma_f32_16x16x32_bf16 v[52:55], v[130:133], v[76:79], v[52:55]
	v_mfma_f32_16x16x32_bf16 v[48:51], v[150:153], v[76:79], v[48:51]
	v_mfma_f32_16x16x32_bf16 v[32:35], v[150:153], v[184:187], v[32:35]
	v_mfma_f32_16x16x32_bf16 v[36:39], v[130:133], v[184:187], v[36:39]
	v_mfma_f32_16x16x32_bf16 v[60:63], v[146:149], v[72:75], v[60:63]
	v_mfma_f32_16x16x32_bf16 v[56:59], v[150:153], v[64:67], v[56:59]
	v_mfma_f32_16x16x32_bf16 v[52:55], v[146:149], v[88:91], v[52:55]
	v_mfma_f32_16x16x32_bf16 v[48:51], v[154:157], v[88:91], v[48:51]
	v_mfma_f32_16x16x32_bf16 v[44:47], v[130:133], v[92:95], v[44:47]
	v_mfma_f32_16x16x32_bf16 v[40:43], v[150:153], v[92:95], v[40:43]
	v_mfma_f32_16x16x32_bf16 v[36:39], v[146:149], v[188:191], v[36:39]
	v_mfma_f32_16x16x32_bf16 v[32:35], v[154:157], v[188:191], v[32:35]
	v_mfma_f32_16x16x32_bf16 v[192:195], v[154:157], v[72:75], v[56:59]
	v_mfma_f32_16x16x32_bf16 v[216:219], v[146:149], v[180:183], v[44:47]
	v_mfma_f32_16x16x32_bf16 v[220:223], v[154:157], v[180:183], v[40:43]
	v_mfma_f32_16x16x32_bf16 v[20:23], v[104:107], v[76:79], v[20:23]
	v_mfma_f32_16x16x32_bf16 v[16:19], v[120:123], v[76:79], v[16:19]
	v_mfma_f32_16x16x32_bf16 v[4:7], v[104:107], v[184:187], v[4:7]
	v_mfma_f32_16x16x32_bf16 v[28:31], v[104:107], v[64:67], v[28:31]
	v_mfma_f32_16x16x32_bf16 v[24:27], v[120:123], v[64:67], v[24:27]
	v_mfma_f32_16x16x32_bf16 v[20:23], v[108:111], v[88:91], v[20:23]
	v_mfma_f32_16x16x32_bf16 v[16:19], v[208:211], v[88:91], v[16:19]
	v_mfma_f32_16x16x32_bf16 v[12:15], v[104:107], v[92:95], v[12:15]
	v_mfma_f32_16x16x32_bf16 v[8:11], v[120:123], v[92:95], v[8:11]
	v_mfma_f32_16x16x32_bf16 v[4:7], v[108:111], v[188:191], v[4:7]
	v_mfma_f32_16x16x32_bf16 v[0:3], v[120:123], v[184:187], v[0:3]
	v_mfma_f32_16x16x32_bf16 v[130:133], v[108:111], v[72:75], v[28:31]
	v_mfma_f32_16x16x32_bf16 v[146:149], v[208:211], v[72:75], v[24:27]
	v_mfma_f32_16x16x32_bf16 v[150:153], v[108:111], v[180:183], v[12:15]
	v_mfma_f32_16x16x32_bf16 v[154:157], v[208:211], v[180:183], v[8:11]
	v_mfma_f32_16x16x32_bf16 v[180:183], v[208:211], v[188:191], v[0:3]
	s_barrier
	s_nop 0
	ds_read_b128 v[0:3], v144
	ds_read_b128 v[8:11], v144 offset:1024
	ds_read_b128 v[12:15], v144 offset:2048
	ds_read_b128 v[184:187], v144 offset:3072
	ds_read_b128 v[24:27], v139 offset:32768
	ds_read_b128 v[28:31], v139 offset:33792
	ds_read_b128 v[40:43], v140 offset:32768
	ds_read_b128 v[44:47], v140 offset:33792
	ds_read_b128 v[56:59], v141 offset:32768
	ds_read_b128 v[64:67], v141 offset:33792
	ds_read_b128 v[188:191], v142 offset:32768
	ds_read_b128 v[208:211], v142 offset:33792
	s_waitcnt vmcnt(2)
	s_barrier
	s_waitcnt lgkmcnt(0)
	v_mfma_f32_16x16x32_bf16 v[72:75], v[0:3], v[24:27], v[124:127]
	v_mfma_f32_16x16x32_bf16 v[120:123], v[8:11], v[28:31], v[72:75]
	v_mfma_f32_16x16x32_bf16 v[72:75], v[12:15], v[24:27], v[196:199]
	v_mfma_f32_16x16x32_bf16 v[124:127], v[184:187], v[28:31], v[72:75]
	v_mfma_f32_16x16x32_bf16 v[72:75], v[0:3], v[40:43], v[116:119]
	v_mfma_f32_16x16x32_bf16 v[104:107], v[8:11], v[44:47], v[72:75]
	v_mfma_f32_16x16x32_bf16 v[72:75], v[12:15], v[40:43], v[112:115]
	v_mfma_f32_16x16x32_bf16 v[108:111], v[184:187], v[44:47], v[72:75]
	v_mfma_f32_16x16x32_bf16 v[72:75], v[0:3], v[56:59], v[200:203]
	v_mfma_f32_16x16x32_bf16 v[88:91], v[8:11], v[64:67], v[72:75]
	v_mfma_f32_16x16x32_bf16 v[72:75], v[12:15], v[56:59], v[204:207]
	v_mfma_f32_16x16x32_bf16 v[92:95], v[184:187], v[64:67], v[72:75]
	v_mfma_f32_16x16x32_bf16 v[72:75], v[0:3], v[188:191], v[100:103]
	v_mfma_f32_16x16x32_bf16 v[76:79], v[12:15], v[188:191], v[96:99]
	v_mfma_f32_16x16x32_bf16 v[72:75], v[8:11], v[208:211], v[72:75]
	v_mfma_f32_16x16x32_bf16 v[76:79], v[184:187], v[208:211], v[76:79]
	s_barrier
; #define LDA(dst, b, h)                                                                                               \
;   _Pragma("unroll") for (int m = 0; m < 4; ++m) _Pragma("unroll") for (int k = 0; k < 2; ++k) dst[m][k] =            \
;       *reinterpret_cast<const bf16x8*>(SA(b, h) + lds_byte(wr * 64 + m * 16 + fr, k * 32 + fq * 8))
; #define LDB(dst, b, h)                                                                                               \
;   _Pragma("unroll") for (int n = 0; n < 2; ++n) _Pragma("unroll") for (int k = 0; k < 2; ++k) dst[n][k] =            \
;       *reinterpret_cast<const bf16x8*>(SB(b, h) + lds_byte(wc * 32 + n * 16 + fr, k * 32 + fq * 8))
; #define WAIT_V(n) asm volatile("s_waitcnt vmcnt(" #n ")" ::: "memory")
; #define WAIT_L(n) asm volatile("s_waitcnt lgkmcnt(" #n ")" ::: "memory")
; #define BAR __builtin_amdgcn_s_barrier()
; template <int EPI>
; __device__ __forceinline__ void gemm_phase(const u16* __restrict__ A, const u16* __restrict__ Bt, const int K,
;                                            const int nN, char* shm, const EpiArgs& ea) {
;     ...
;       LDB(B0, 1, 0); LDA(At, 1, 0); WAIT_V(2); BAR; WAIT_L(0); MMA(0, 0, At, B0); BAR;
;       LDB(B1, 1, 1); WAIT_V(0); BAR; WAIT_L(0); MMA(0, 1, At, B1); BAR;
;       LDA(At, 1, 1); BAR; WAIT_L(0); MMA(1, 0, At, B0); MMA(1, 1, At, B1); BAR;
;     }
;     if (wr == 0) BAR;
	ds_read_b128 v[196:199], v145
	ds_read_b128 v[200:203], v145 offset:1024
	ds_read_b128 v[204:207], v145 offset:2048
	ds_read_b128 v[224:227], v145 offset:3072
	s_waitcnt vmcnt(0)
	s_barrier
	s_waitcnt lgkmcnt(0)
	v_mfma_f32_16x16x32_bf16 v[96:99], v[196:199], v[24:27], v[212:215]
	v_mfma_f32_16x16x32_bf16 v[24:27], v[204:207], v[24:27], v[162:165]
	v_mfma_f32_16x16x32_bf16 v[116:119], v[224:227], v[28:31], v[24:27]
	v_mfma_f32_16x16x32_bf16 v[24:27], v[196:199], v[40:43], v[84:87]
	v_mfma_f32_16x16x32_bf16 v[112:115], v[200:203], v[28:31], v[96:99]
	v_mfma_f32_16x16x32_bf16 v[96:99], v[200:203], v[44:47], v[24:27]
	v_mfma_f32_16x16x32_bf16 v[24:27], v[204:207], v[40:43], v[80:83]
	v_mfma_f32_16x16x32_bf16 v[100:103], v[224:227], v[44:47], v[24:27]
	v_mfma_f32_16x16x32_bf16 v[24:27], v[196:199], v[56:59], v[166:169]
	v_mfma_f32_16x16x32_bf16 v[80:83], v[200:203], v[64:67], v[24:27]
	v_mfma_f32_16x16x32_bf16 v[24:27], v[204:207], v[56:59], v[170:173]
	v_mfma_f32_16x16x32_bf16 v[84:87], v[224:227], v[64:67], v[24:27]
	v_mfma_f32_16x16x32_bf16 v[24:27], v[196:199], v[188:191], v[68:71]
	v_mfma_f32_16x16x32_bf16 v[64:67], v[200:203], v[208:211], v[24:27]
	v_mfma_f32_16x16x32_bf16 v[24:27], v[204:207], v[188:191], v[176:179]
	v_mfma_f32_16x16x32_bf16 v[68:71], v[224:227], v[208:211], v[24:27]
	s_barrier
	ds_read_b128 v[162:165], v139 offset:49152
	ds_read_b128 v[166:169], v139 offset:50176
	ds_read_b128 v[170:173], v140 offset:49152
	ds_read_b128 v[176:179], v140 offset:50176
	ds_read_b128 v[188:191], v141 offset:49152
	ds_read_b128 v[208:211], v141 offset:50176
	ds_read_b128 v[212:215], v142 offset:49152
	ds_read_b128 v[228:231], v142 offset:50176
	s_barrier
	s_waitcnt lgkmcnt(0)
	v_mfma_f32_16x16x32_bf16 v[24:27], v[0:3], v[162:165], v[60:63]
	v_mfma_f32_16x16x32_bf16 v[56:59], v[8:11], v[166:169], v[24:27]
	v_mfma_f32_16x16x32_bf16 v[24:27], v[12:15], v[162:165], v[192:195]
	v_mfma_f32_16x16x32_bf16 v[60:63], v[184:187], v[166:169], v[24:27]
	v_mfma_f32_16x16x32_bf16 v[24:27], v[0:3], v[170:173], v[52:55]
	v_mfma_f32_16x16x32_bf16 v[40:43], v[8:11], v[176:179], v[24:27]
	v_mfma_f32_16x16x32_bf16 v[24:27], v[12:15], v[170:173], v[48:51]
	v_mfma_f32_16x16x32_bf16 v[44:47], v[184:187], v[176:179], v[24:27]
	v_mfma_f32_16x16x32_bf16 v[24:27], v[0:3], v[188:191], v[216:219]
	v_mfma_f32_16x16x32_bf16 v[0:3], v[0:3], v[212:215], v[36:39]
	v_mfma_f32_16x16x32_bf16 v[24:27], v[8:11], v[208:211], v[24:27]
	v_mfma_f32_16x16x32_bf16 v[28:31], v[12:15], v[188:191], v[220:223]
	v_mfma_f32_16x16x32_bf16 v[8:11], v[8:11], v[228:231], v[0:3]
	v_mfma_f32_16x16x32_bf16 v[0:3], v[12:15], v[212:215], v[32:35]
	v_mfma_f32_16x16x32_bf16 v[28:31], v[184:187], v[208:211], v[28:31]
	v_mfma_f32_16x16x32_bf16 v[12:15], v[184:187], v[228:231], v[0:3]
	v_mfma_f32_16x16x32_bf16 v[0:3], v[196:199], v[162:165], v[130:133]
	v_mfma_f32_16x16x32_bf16 v[48:51], v[200:203], v[166:169], v[0:3]
	v_mfma_f32_16x16x32_bf16 v[0:3], v[204:207], v[162:165], v[146:149]
	v_mfma_f32_16x16x32_bf16 v[52:55], v[224:227], v[166:169], v[0:3]
	v_mfma_f32_16x16x32_bf16 v[0:3], v[196:199], v[170:173], v[20:23]
	v_mfma_f32_16x16x32_bf16 v[32:35], v[200:203], v[176:179], v[0:3]
	v_mfma_f32_16x16x32_bf16 v[0:3], v[204:207], v[170:173], v[16:19]
	v_mfma_f32_16x16x32_bf16 v[36:39], v[224:227], v[176:179], v[0:3]
	v_mfma_f32_16x16x32_bf16 v[0:3], v[196:199], v[188:191], v[150:153]
	v_mfma_f32_16x16x32_bf16 v[16:19], v[200:203], v[208:211], v[0:3]
	v_mfma_f32_16x16x32_bf16 v[0:3], v[204:207], v[188:191], v[154:157]
	v_mfma_f32_16x16x32_bf16 v[20:23], v[224:227], v[208:211], v[0:3]
	v_mfma_f32_16x16x32_bf16 v[0:3], v[196:199], v[212:215], v[4:7]
	v_mfma_f32_16x16x32_bf16 v[4:7], v[204:207], v[212:215], v[180:183]
	v_mfma_f32_16x16x32_bf16 v[0:3], v[200:203], v[228:231], v[0:3]
	v_mfma_f32_16x16x32_bf16 v[4:7], v[224:227], v[228:231], v[4:7]
	s_andn2_b64 vcc, exec, s[30:31]
	s_barrier
	s_cbranch_vccnz .LBB0_234
	s_barrier

; #define LDA(dst, b, h)                                                                                               \
;   _Pragma("unroll") for (int m = 0; m < 4; ++m) _Pragma("unroll") for (int k = 0; k < 2; ++k) dst[m][k] =            \
;       *reinterpret_cast<const bf16x8*>(SA(b, h) + lds_byte(wr * 64 + m * 16 + fr, k * 32 + fq * 8))
; #define LDB(dst, b, h)                                                                                               \
;   _Pragma("unroll") for (int n = 0; n < 2; ++n) _Pragma("unroll") for (int k = 0; k < 2; ++k) dst[n][k] =            \
;       *reinterpret_cast<const bf16x8*>(SB(b, h) + lds_byte(wc * 32 + n * 16 + fr, k * 32 + fq * 8))
; #define WAIT_V(n) asm volatile("s_waitcnt vmcnt(" #n ")" ::: "memory")
; #define WAIT_L(n) asm volatile("s_waitcnt lgkmcnt(" #n ")" ::: "memory")
; #define BAR __builtin_amdgcn_s_barrier()
; #define SCHED __builtin_amdgcn_sched_barrier(0)
; template <int EPI>
; __device__ __forceinline__ void gemm_phase(const u16* __restrict__ A, const u16* __restrict__ Bt, const int K,
;                                            const int nN, char* shm, const EpiArgs& ea) {
;     ...
;     for (int t = 0; t < nt - 2; t += 2) {
;       LDB(B0, 0, 0); SCHED; LDA(At, 0, 0); STAGE(SA(1, 1), rA, brow + HALF, t + 1);
;       WAIT_V(10); WAIT_L(8); BAR; WAIT_L(0); MMA(0, 0, At, B0); BAR; SCHED;
;       LDB(B1, 0, 1); STAGE(SB(0, 0), rB, bcol, t + 2);
;       WAIT_V(10); BAR; WAIT_L(0); MMA(0, 1, At, B1); BAR;
;       LDA(At, 0, 1); STAGE(SA(0, 0), rA, brow, t + 2);
;       BAR; WAIT_L(0); MMA(1, 0, At, B0); BAR; SCHED;
;       STAGE(SB(0, 1), rB, bcol + HALF, t + 2);
;       WAIT_V(10); BAR; MMA(1, 1, At, B1); BAR;
.LBB0_306:
	ds_read_b128 v[128:131], v168
	ds_read_b128 v[132:135], v168 offset:1024
	ds_read_b128 v[136:139], v168 offset:2048
	ds_read_b128 v[140:143], v168 offset:3072
	s_add_i32 s79, s72, s78
	s_mov_b32 m0, s52
	s_add_i32 s26, s79, 0x4000
	ds_read_b128 v[144:147], v169
	ds_read_b128 v[148:151], v169 offset:1024
	ds_read_b128 v[152:155], v170
	ds_read_b128 v[156:159], v170 offset:1024
	ds_read_b128 v[180:183], v171
	ds_read_b128 v[184:187], v171 offset:1024
	ds_read_b128 v[188:191], v172
	ds_read_b128 v[192:195], v172 offset:1024
	buffer_load_dwordx4 v161, s[0:3], s26 offen lds
	s_add_i32 s26, s79, 0x6000
	s_mov_b32 m0, s53
	s_nop 0
	buffer_load_dwordx4 v161, s[0:3], s26 offen lds
	s_waitcnt vmcnt(10)
	s_waitcnt lgkmcnt(8)
	s_barrier
	s_waitcnt lgkmcnt(0)
	v_mfma_f32_16x16x32_bf16 v[124:127], v[128:131], v[144:147], v[124:127]
	v_mfma_f32_16x16x32_bf16 v[120:123], v[136:139], v[144:147], v[120:123]
	v_mfma_f32_16x16x32_bf16 v[112:115], v[136:139], v[152:155], v[112:115]
	v_mfma_f32_16x16x32_bf16 v[116:119], v[128:131], v[152:155], v[116:119]
	v_mfma_f32_16x16x32_bf16 v[108:111], v[128:131], v[180:183], v[108:111]
	v_mfma_f32_16x16x32_bf16 v[104:107], v[136:139], v[180:183], v[104:107]
	v_mfma_f32_16x16x32_bf16 v[96:99], v[136:139], v[188:191], v[96:99]
	v_mfma_f32_16x16x32_bf16 v[100:103], v[128:131], v[188:191], v[100:103]
	v_mfma_f32_16x16x32_bf16 v[124:127], v[132:135], v[148:151], v[124:127]
	v_mfma_f32_16x16x32_bf16 v[120:123], v[140:143], v[148:151], v[120:123]
	v_mfma_f32_16x16x32_bf16 v[112:115], v[140:143], v[156:159], v[112:115]
	v_mfma_f32_16x16x32_bf16 v[116:119], v[132:135], v[156:159], v[116:119]
	v_mfma_f32_16x16x32_bf16 v[108:111], v[132:135], v[184:187], v[108:111]
	v_mfma_f32_16x16x32_bf16 v[104:107], v[140:143], v[184:187], v[104:107]
	v_mfma_f32_16x16x32_bf16 v[96:99], v[140:143], v[192:195], v[96:99]
	v_mfma_f32_16x16x32_bf16 v[100:103], v[132:135], v[192:195], v[100:103]
	s_barrier
	s_add_i32 s80, s74, s78
	s_mov_b32 m0, s54
	s_add_i32 s81, s80, 0x8000
	s_mov_b32 s26, s2
	s_mov_b32 s27, s3
	ds_read_b128 v[196:199], v173
	ds_read_b128 v[200:203], v173 offset:1024
	ds_read_b128 v[204:207], v173 offset:2048
	ds_read_b128 v[208:211], v173 offset:3072
	buffer_load_dwordx4 v161, s[24:27], s81 offen lds
	s_add_i32 s81, s80, 0xa000
	s_mov_b32 m0, s55
	s_nop 0
	buffer_load_dwordx4 v161, s[24:27], s81 offen lds
	s_waitcnt vmcnt(10)
	s_barrier
	s_waitcnt lgkmcnt(0)
	v_mfma_f32_16x16x32_bf16 v[92:95], v[196:199], v[144:147], v[92:95]
	v_mfma_f32_16x16x32_bf16 v[88:91], v[204:207], v[144:147], v[88:91]
	v_mfma_f32_16x16x32_bf16 v[80:83], v[204:207], v[152:155], v[80:83]
	v_mfma_f32_16x16x32_bf16 v[84:87], v[196:199], v[152:155], v[84:87]
	v_mfma_f32_16x16x32_bf16 v[76:79], v[196:199], v[180:183], v[76:79]
	v_mfma_f32_16x16x32_bf16 v[72:75], v[204:207], v[180:183], v[72:75]
	v_mfma_f32_16x16x32_bf16 v[64:67], v[204:207], v[188:191], v[64:67]
	v_mfma_f32_16x16x32_bf16 v[68:71], v[196:199], v[188:191], v[68:71]
	v_mfma_f32_16x16x32_bf16 v[92:95], v[200:203], v[148:151], v[92:95]
	v_mfma_f32_16x16x32_bf16 v[88:91], v[208:211], v[148:151], v[88:91]
	v_mfma_f32_16x16x32_bf16 v[80:83], v[208:211], v[156:159], v[80:83]
	v_mfma_f32_16x16x32_bf16 v[84:87], v[200:203], v[156:159], v[84:87]
	v_mfma_f32_16x16x32_bf16 v[76:79], v[200:203], v[184:187], v[76:79]
	v_mfma_f32_16x16x32_bf16 v[72:75], v[208:211], v[184:187], v[72:75]
	v_mfma_f32_16x16x32_bf16 v[64:67], v[208:211], v[192:195], v[64:67]
	v_mfma_f32_16x16x32_bf16 v[68:71], v[200:203], v[192:195], v[68:71]
	s_add_i32 s81, s73, s78
	s_mov_b32 m0, s49
	s_add_i32 s82, s81, 0x8000
	s_barrier
	ds_read_b128 v[144:147], v169 offset:16384
	ds_read_b128 v[148:151], v169 offset:17408
	ds_read_b128 v[152:155], v170 offset:16384
	ds_read_b128 v[156:159], v170 offset:17408
	ds_read_b128 v[180:183], v171 offset:16384
	ds_read_b128 v[184:187], v171 offset:17408
	ds_read_b128 v[188:191], v172 offset:16384
	ds_read_b128 v[192:195], v172 offset:17408
	buffer_load_dwordx4 v161, s[0:3], s82 offen lds
	s_add_i32 s82, s81, 0xa000
	s_mov_b32 m0, s56
	s_nop 0
	buffer_load_dwordx4 v161, s[0:3], s82 offen lds
	s_barrier
	s_waitcnt lgkmcnt(0)
	v_mfma_f32_16x16x32_bf16 v[60:63], v[128:131], v[144:147], v[60:63]
	v_mfma_f32_16x16x32_bf16 v[56:59], v[136:139], v[144:147], v[56:59]
	v_mfma_f32_16x16x32_bf16 v[48:51], v[136:139], v[152:155], v[48:51]
	v_mfma_f32_16x16x32_bf16 v[52:55], v[128:131], v[152:155], v[52:55]
	v_mfma_f32_16x16x32_bf16 v[44:47], v[128:131], v[180:183], v[44:47]
	v_mfma_f32_16x16x32_bf16 v[40:43], v[136:139], v[180:183], v[40:43]
	v_mfma_f32_16x16x32_bf16 v[32:35], v[136:139], v[188:191], v[32:35]
	v_mfma_f32_16x16x32_bf16 v[36:39], v[128:131], v[188:191], v[36:39]
	v_mfma_f32_16x16x32_bf16 v[60:63], v[132:135], v[148:151], v[60:63]
	v_mfma_f32_16x16x32_bf16 v[56:59], v[140:143], v[148:151], v[56:59]
	v_mfma_f32_16x16x32_bf16 v[48:51], v[140:143], v[156:159], v[48:51]
	v_mfma_f32_16x16x32_bf16 v[52:55], v[132:135], v[156:159], v[52:55]
	v_mfma_f32_16x16x32_bf16 v[44:47], v[132:135], v[184:187], v[44:47]
	v_mfma_f32_16x16x32_bf16 v[40:43], v[140:143], v[184:187], v[40:43]
	v_mfma_f32_16x16x32_bf16 v[32:35], v[140:143], v[192:195], v[32:35]
	v_mfma_f32_16x16x32_bf16 v[36:39], v[132:135], v[192:195], v[36:39]
	s_barrier
	s_add_i32 s82, s43, s78
	s_mov_b32 m0, s57
	s_add_i32 s83, s82, 0x8000
	buffer_load_dwordx4 v161, s[24:27], s83 offen lds
	s_add_i32 s83, s82, 0xa000
	s_mov_b32 m0, s58
	s_nop 0
	buffer_load_dwordx4 v161, s[24:27], s83 offen lds
	s_waitcnt vmcnt(10)
	s_barrier
; #define LDA(dst, b, h)                                                                                               \
;   _Pragma("unroll") for (int m = 0; m < 4; ++m) _Pragma("unroll") for (int k = 0; k < 2; ++k) dst[m][k] =            \
;       *reinterpret_cast<const bf16x8*>(SA(b, h) + lds_byte(wr * 64 + m * 16 + fr, k * 32 + fq * 8))
; #define LDB(dst, b, h)                                                                                               \
;   _Pragma("unroll") for (int n = 0; n < 2; ++n) _Pragma("unroll") for (int k = 0; k < 2; ++k) dst[n][k] =            \
;       *reinterpret_cast<const bf16x8*>(SB(b, h) + lds_byte(wc * 32 + n * 16 + fr, k * 32 + fq * 8))
; #define WAIT_V(n) asm volatile("s_waitcnt vmcnt(" #n ")" ::: "memory")
; #define WAIT_L(n) asm volatile("s_waitcnt lgkmcnt(" #n ")" ::: "memory")
; #define BAR __builtin_amdgcn_s_barrier()
; #define SCHED __builtin_amdgcn_sched_barrier(0)
; template <int EPI>
; __device__ __forceinline__ void gemm_phase(const u16* __restrict__ A, const u16* __restrict__ Bt, const int K,
;                                            const int nN, char* shm, const EpiArgs& ea) {
;     ...
;       WAIT_V(10); BAR; WAIT_L(0); MMA(0, 1, At, B1); BAR;
;       LDA(At, 0, 1); STAGE(SA(0, 0), rA, brow, t + 2);
;       BAR; WAIT_L(0); MMA(1, 0, At, B0); BAR; SCHED;
;       STAGE(SB(0, 1), rB, bcol + HALF, t + 2);
;       WAIT_V(10); BAR; MMA(1, 1, At, B1); BAR;
;       LDB(B0, 1, 0); SCHED; LDA(At, 1, 0); STAGE(SA(0, 1), rA, brow + HALF, t + 2);
;       WAIT_V(10); WAIT_L(8); BAR; WAIT_L(0); MMA(0, 0, At, B0); BAR; SCHED;
;       LDB(B1, 1, 1); STAGE(SB(1, 0), rB, bcol, t + 3);
;       WAIT_V(10); BAR; WAIT_L(0); MMA(0, 1, At, B1); BAR;
	v_mfma_f32_16x16x32_bf16 v[28:31], v[196:199], v[144:147], v[28:31]
	v_mfma_f32_16x16x32_bf16 v[24:27], v[204:207], v[144:147], v[24:27]
	v_mfma_f32_16x16x32_bf16 v[16:19], v[204:207], v[152:155], v[16:19]
	v_mfma_f32_16x16x32_bf16 v[20:23], v[196:199], v[152:155], v[20:23]
	v_mfma_f32_16x16x32_bf16 v[12:15], v[196:199], v[180:183], v[12:15]
	v_mfma_f32_16x16x32_bf16 v[8:11], v[204:207], v[180:183], v[8:11]
	v_mfma_f32_16x16x32_bf16 v[0:3], v[204:207], v[188:191], v[0:3]
	v_mfma_f32_16x16x32_bf16 v[4:7], v[196:199], v[188:191], v[4:7]
	v_mfma_f32_16x16x32_bf16 v[28:31], v[200:203], v[148:151], v[28:31]
	v_mfma_f32_16x16x32_bf16 v[24:27], v[208:211], v[148:151], v[24:27]
	v_mfma_f32_16x16x32_bf16 v[16:19], v[208:211], v[156:159], v[16:19]
	v_mfma_f32_16x16x32_bf16 v[20:23], v[200:203], v[156:159], v[20:23]
	v_mfma_f32_16x16x32_bf16 v[12:15], v[200:203], v[184:187], v[12:15]
	v_mfma_f32_16x16x32_bf16 v[8:11], v[208:211], v[184:187], v[8:11]
	v_mfma_f32_16x16x32_bf16 v[0:3], v[208:211], v[192:195], v[0:3]
	v_mfma_f32_16x16x32_bf16 v[4:7], v[200:203], v[192:195], v[4:7]
	s_barrier
	ds_read_b128 v[128:131], v176
	ds_read_b128 v[132:135], v176 offset:1024
	ds_read_b128 v[136:139], v176 offset:2048
	ds_read_b128 v[140:143], v176 offset:3072
	s_mov_b32 m0, s59
	s_add_i32 s83, s79, 0x8000
	ds_read_b128 v[144:147], v169 offset:32768
	ds_read_b128 v[148:151], v169 offset:33792
	ds_read_b128 v[152:155], v170 offset:32768
	ds_read_b128 v[156:159], v170 offset:33792
	ds_read_b128 v[180:183], v171 offset:32768
	ds_read_b128 v[184:187], v171 offset:33792
	ds_read_b128 v[188:191], v172 offset:32768
	ds_read_b128 v[192:195], v172 offset:33792
	buffer_load_dwordx4 v161, s[0:3], s83 offen lds
	s_add_i32 s79, s79, 0xa000
	s_mov_b32 m0, s60
	s_nop 0
	buffer_load_dwordx4 v161, s[0:3], s79 offen lds
	s_waitcnt vmcnt(10)
	s_waitcnt lgkmcnt(8)
	s_barrier
	s_waitcnt lgkmcnt(0)
	v_mfma_f32_16x16x32_bf16 v[124:127], v[128:131], v[144:147], v[124:127]
	v_mfma_f32_16x16x32_bf16 v[120:123], v[136:139], v[144:147], v[120:123]
	v_mfma_f32_16x16x32_bf16 v[112:115], v[136:139], v[152:155], v[112:115]
	v_mfma_f32_16x16x32_bf16 v[116:119], v[128:131], v[152:155], v[116:119]
	v_mfma_f32_16x16x32_bf16 v[108:111], v[128:131], v[180:183], v[108:111]
	v_mfma_f32_16x16x32_bf16 v[104:107], v[136:139], v[180:183], v[104:107]
	v_mfma_f32_16x16x32_bf16 v[96:99], v[136:139], v[188:191], v[96:99]
	v_mfma_f32_16x16x32_bf16 v[100:103], v[128:131], v[188:191], v[100:103]
	v_mfma_f32_16x16x32_bf16 v[124:127], v[132:135], v[148:151], v[124:127]
	v_mfma_f32_16x16x32_bf16 v[120:123], v[140:143], v[148:151], v[120:123]
	v_mfma_f32_16x16x32_bf16 v[112:115], v[140:143], v[156:159], v[112:115]
	v_mfma_f32_16x16x32_bf16 v[116:119], v[132:135], v[156:159], v[116:119]
	v_mfma_f32_16x16x32_bf16 v[108:111], v[132:135], v[184:187], v[108:111]
	v_mfma_f32_16x16x32_bf16 v[104:107], v[140:143], v[184:187], v[104:107]
	v_mfma_f32_16x16x32_bf16 v[96:99], v[140:143], v[192:195], v[96:99]
	v_mfma_f32_16x16x32_bf16 v[100:103], v[132:135], v[192:195], v[100:103]
	s_barrier
	s_mov_b32 m0, s61
	s_add_i32 s79, s80, 0xc000
	ds_read_b128 v[196:199], v177
	ds_read_b128 v[200:203], v177 offset:1024
	ds_read_b128 v[204:207], v177 offset:2048
	ds_read_b128 v[208:211], v177 offset:3072
	buffer_load_dwordx4 v161, s[24:27], s79 offen lds
	s_add_i32 s80, s80, 0xe000
	s_mov_b32 m0, s62
	s_nop 0
	buffer_load_dwordx4 v161, s[24:27], s80 offen lds
	s_waitcnt vmcnt(10)
	s_barrier
	s_waitcnt lgkmcnt(0)
	v_mfma_f32_16x16x32_bf16 v[92:95], v[196:199], v[144:147], v[92:95]
	v_mfma_f32_16x16x32_bf16 v[88:91], v[204:207], v[144:147], v[88:91]
	v_mfma_f32_16x16x32_bf16 v[80:83], v[204:207], v[152:155], v[80:83]
	v_mfma_f32_16x16x32_bf16 v[84:87], v[196:199], v[152:155], v[84:87]
	v_mfma_f32_16x16x32_bf16 v[76:79], v[196:199], v[180:183], v[76:79]
	v_mfma_f32_16x16x32_bf16 v[72:75], v[204:207], v[180:183], v[72:75]
	v_mfma_f32_16x16x32_bf16 v[64:67], v[204:207], v[188:191], v[64:67]
	v_mfma_f32_16x16x32_bf16 v[68:71], v[196:199], v[188:191], v[68:71]
	v_mfma_f32_16x16x32_bf16 v[92:95], v[200:203], v[148:151], v[92:95]
	v_mfma_f32_16x16x32_bf16 v[88:91], v[208:211], v[148:151], v[88:91]
	v_mfma_f32_16x16x32_bf16 v[80:83], v[208:211], v[156:159], v[80:83]
	v_mfma_f32_16x16x32_bf16 v[84:87], v[200:203], v[156:159], v[84:87]
	v_mfma_f32_16x16x32_bf16 v[76:79], v[200:203], v[184:187], v[76:79]
	v_mfma_f32_16x16x32_bf16 v[72:75], v[208:211], v[184:187], v[72:75]
	v_mfma_f32_16x16x32_bf16 v[64:67], v[208:211], v[192:195], v[64:67]
	v_mfma_f32_16x16x32_bf16 v[68:71], v[200:203], v[192:195], v[68:71]
	s_mov_b32 m0, s63
	s_add_i32 s79, s81, 0xc000
	s_barrier
; #define LDA(dst, b, h)                                                                                               \
;   _Pragma("unroll") for (int m = 0; m < 4; ++m) _Pragma("unroll") for (int k = 0; k < 2; ++k) dst[m][k] =            \
;       *reinterpret_cast<const bf16x8*>(SA(b, h) + lds_byte(wr * 64 + m * 16 + fr, k * 32 + fq * 8))
; #define LDB(dst, b, h)                                                                                               \
;   _Pragma("unroll") for (int n = 0; n < 2; ++n) _Pragma("unroll") for (int k = 0; k < 2; ++k) dst[n][k] =            \
;       *reinterpret_cast<const bf16x8*>(SB(b, h) + lds_byte(wc * 32 + n * 16 + fr, k * 32 + fq * 8))
; #define WAIT_V(n) asm volatile("s_waitcnt vmcnt(" #n ")" ::: "memory")
; #define WAIT_L(n) asm volatile("s_waitcnt lgkmcnt(" #n ")" ::: "memory")
; #define BAR __builtin_amdgcn_s_barrier()
; #define SCHED __builtin_amdgcn_sched_barrier(0)
; template <int EPI>
; __device__ __forceinline__ void gemm_phase(const u16* __restrict__ A, const u16* __restrict__ Bt, const int K,
;                                            const int nN, char* shm, const EpiArgs& ea) {
;     ...
;       LDB(B1, 1, 1); STAGE(SB(1, 0), rB, bcol, t + 3);
;       WAIT_V(10); BAR; WAIT_L(0); MMA(0, 1, At, B1); BAR;
;       LDA(At, 1, 1); STAGE(SA(1, 0), rA, brow, t + 3);
;       BAR; WAIT_L(0); MMA(1, 0, At, B0); BAR; SCHED;
;       STAGE(SB(1, 1), rB, bcol + HALF, t + 3);
;       WAIT_V(10); BAR; MMA(1, 1, At, B1); BAR;
;     }
;     float eC = 0.f, eB = 0.f;
;     float2 eS = make_float2(0.f, 0.f);
;     if (EPI == EPI_IN || EPI == EPI_SWIGLU_LN) {
;       if (wr == 0) {
;         eC = ea.c1[bcol + tid];
;         eS = *(const float2*)(ea.st_in + (size_t)(brow + tid) * 2);
;       } else {
;         eC = ea.c2[bcol + tid - 256];
;         if (EPI == EPI_IN) eB = ea.bias[bcol + tid - 256];
	ds_read_b128 v[144:147], v169 offset:49152
	ds_read_b128 v[148:151], v169 offset:50176
	ds_read_b128 v[152:155], v170 offset:49152
	ds_read_b128 v[156:159], v170 offset:50176
	ds_read_b128 v[180:183], v171 offset:49152
	ds_read_b128 v[184:187], v171 offset:50176
	ds_read_b128 v[188:191], v172 offset:49152
	ds_read_b128 v[192:195], v172 offset:50176
	buffer_load_dwordx4 v161, s[0:3], s79 offen lds
	s_add_i32 s81, s81, 0xe000
	s_mov_b32 m0, s64
	s_nop 0
	buffer_load_dwordx4 v161, s[0:3], s81 offen lds
	s_barrier
	s_waitcnt lgkmcnt(0)
	v_mfma_f32_16x16x32_bf16 v[60:63], v[128:131], v[144:147], v[60:63]
	v_mfma_f32_16x16x32_bf16 v[56:59], v[136:139], v[144:147], v[56:59]
	v_mfma_f32_16x16x32_bf16 v[48:51], v[136:139], v[152:155], v[48:51]
	v_mfma_f32_16x16x32_bf16 v[52:55], v[128:131], v[152:155], v[52:55]
	v_mfma_f32_16x16x32_bf16 v[44:47], v[128:131], v[180:183], v[44:47]
	v_mfma_f32_16x16x32_bf16 v[40:43], v[136:139], v[180:183], v[40:43]
	v_mfma_f32_16x16x32_bf16 v[32:35], v[136:139], v[188:191], v[32:35]
	v_mfma_f32_16x16x32_bf16 v[36:39], v[128:131], v[188:191], v[36:39]
	v_mfma_f32_16x16x32_bf16 v[60:63], v[132:135], v[148:151], v[60:63]
	v_mfma_f32_16x16x32_bf16 v[56:59], v[140:143], v[148:151], v[56:59]
	v_mfma_f32_16x16x32_bf16 v[48:51], v[140:143], v[156:159], v[48:51]
	v_mfma_f32_16x16x32_bf16 v[52:55], v[132:135], v[156:159], v[52:55]
	v_mfma_f32_16x16x32_bf16 v[44:47], v[132:135], v[184:187], v[44:47]
	v_mfma_f32_16x16x32_bf16 v[40:43], v[140:143], v[184:187], v[40:43]
	v_mfma_f32_16x16x32_bf16 v[32:35], v[140:143], v[192:195], v[32:35]
	v_mfma_f32_16x16x32_bf16 v[36:39], v[132:135], v[192:195], v[36:39]
	s_barrier
	s_mov_b32 m0, s65
	s_add_i32 s79, s82, 0xc000
	buffer_load_dwordx4 v161, s[24:27], s79 offen lds
	s_add_i32 s82, s82, 0xe000
	s_mov_b32 m0, s66
	s_nop 0
	buffer_load_dwordx4 v161, s[24:27], s82 offen lds
	s_waitcnt vmcnt(10)
	s_barrier
	v_mfma_f32_16x16x32_bf16 v[28:31], v[196:199], v[144:147], v[28:31]
	v_mfma_f32_16x16x32_bf16 v[24:27], v[204:207], v[144:147], v[24:27]
	v_mfma_f32_16x16x32_bf16 v[16:19], v[204:207], v[152:155], v[16:19]
	v_mfma_f32_16x16x32_bf16 v[20:23], v[196:199], v[152:155], v[20:23]
	v_mfma_f32_16x16x32_bf16 v[12:15], v[196:199], v[180:183], v[12:15]
	v_mfma_f32_16x16x32_bf16 v[8:11], v[204:207], v[180:183], v[8:11]
	v_mfma_f32_16x16x32_bf16 v[0:3], v[204:207], v[188:191], v[0:3]
	v_mfma_f32_16x16x32_bf16 v[4:7], v[196:199], v[188:191], v[4:7]
	v_mfma_f32_16x16x32_bf16 v[28:31], v[200:203], v[148:151], v[28:31]
	v_mfma_f32_16x16x32_bf16 v[24:27], v[208:211], v[148:151], v[24:27]
	v_mfma_f32_16x16x32_bf16 v[16:19], v[208:211], v[156:159], v[16:19]
	v_mfma_f32_16x16x32_bf16 v[20:23], v[200:203], v[156:159], v[20:23]
	v_mfma_f32_16x16x32_bf16 v[12:15], v[200:203], v[184:187], v[12:15]
	v_mfma_f32_16x16x32_bf16 v[8:11], v[208:211], v[184:187], v[8:11]
	v_mfma_f32_16x16x32_bf16 v[0:3], v[208:211], v[192:195], v[0:3]
	v_mfma_f32_16x16x32_bf16 v[4:7], v[200:203], v[192:195], v[4:7]
	s_add_i32 s75, s75, 2
	s_add_i32 s78, s78, 0x8000
	s_cmp_lt_u32 s75, 28
	s_barrier
	s_cbranch_scc1 .LBB0_306
	s_mov_b64 s[26:27], -1
	s_and_b64 vcc, exec, s[38:39]
	s_cbranch_vccz .LBB0_309
	s_ashr_i32 s43, s42, 31
	v_lshl_add_u64 v[128:129], v[174:175], 0, s[42:43]
	v_lshl_add_u64 v[128:129], v[128:129], 2, s[50:51]
	global_load_dword v150, v[128:129], off offset:-1024
	v_add_u32_e32 v128, s42, v163
	v_ashrrev_i32_e32 v129, 31, v128
	v_lshl_add_u64 v[128:129], v[128:129], 2, s[18:19]
	s_mov_b64 s[26:27], 0

; #define LDA(dst, b, h)                                                                                               \
;   _Pragma("unroll") for (int m = 0; m < 4; ++m) _Pragma("unroll") for (int k = 0; k < 2; ++k) dst[m][k] =            \
;       *reinterpret_cast<const bf16x8*>(SA(b, h) + lds_byte(wr * 64 + m * 16 + fr, k * 32 + fq * 8))
; #define LDB(dst, b, h)                                                                                               \
;   _Pragma("unroll") for (int n = 0; n < 2; ++n) _Pragma("unroll") for (int k = 0; k < 2; ++k) dst[n][k] =            \
;       *reinterpret_cast<const bf16x8*>(SB(b, h) + lds_byte(wc * 32 + n * 16 + fr, k * 32 + fq * 8))
; #define WAIT_V(n) asm volatile("s_waitcnt vmcnt(" #n ")" ::: "memory")
; #define WAIT_L(n) asm volatile("s_waitcnt lgkmcnt(" #n ")" ::: "memory")
; #define BAR __builtin_amdgcn_s_barrier()
; template <int EPI>
; __device__ __forceinline__ void gemm_phase(const u16* __restrict__ A, const u16* __restrict__ Bt, const int K,
;                                            const int nN, char* shm, const EpiArgs& ea) {
;     ...
;     {
;       LDB(B0, 0, 0); LDA(At, 0, 0); STAGE(SA(1, 1), rA, brow + HALF, nt - 1);
;       WAIT_V(10); BAR; WAIT_L(0); MMA(0, 0, At, B0); BAR;
;       LDB(B1, 0, 1); WAIT_V(8); BAR; WAIT_L(0); MMA(0, 1, At, B1); BAR;
;       LDA(At, 0, 1); WAIT_V(4); BAR; WAIT_L(0); MMA(1, 0, At, B0); MMA(1, 1, At, B1); BAR;
;     }
.LBB0_311:
	s_mov_b32 m0, s52
	s_add_i32 s26, s72, 0x7c000
	global_load_dword v151, v[128:129], off
	ds_read_b128 v[128:131], v168
	ds_read_b128 v[132:135], v168 offset:1024
	ds_read_b128 v[136:139], v168 offset:2048
	ds_read_b128 v[140:143], v168 offset:3072
	ds_read_b128 v[144:147], v169
	ds_read_b128 v[152:155], v169 offset:1024
	ds_read_b128 v[156:159], v170
	ds_read_b128 v[180:183], v170 offset:1024
	ds_read_b128 v[184:187], v171
	ds_read_b128 v[188:191], v171 offset:1024
	ds_read_b128 v[192:195], v172
	ds_read_b128 v[196:199], v172 offset:1024
	buffer_load_dwordx4 v161, s[0:3], s26 offen lds
	s_add_i32 s72, s72, 0x7e000
	s_mov_b32 m0, s53
	s_nop 0
	buffer_load_dwordx4 v161, s[0:3], s72 offen lds
	s_waitcnt vmcnt(10)
	s_barrier
	s_waitcnt lgkmcnt(0)
	v_mfma_f32_16x16x32_bf16 v[124:127], v[128:131], v[144:147], v[124:127]
	v_mfma_f32_16x16x32_bf16 v[120:123], v[136:139], v[144:147], v[120:123]
	v_mfma_f32_16x16x32_bf16 v[112:115], v[136:139], v[156:159], v[112:115]
	v_mfma_f32_16x16x32_bf16 v[116:119], v[128:131], v[156:159], v[116:119]
	v_mfma_f32_16x16x32_bf16 v[108:111], v[128:131], v[184:187], v[108:111]
	v_mfma_f32_16x16x32_bf16 v[104:107], v[136:139], v[184:187], v[104:107]
	v_mfma_f32_16x16x32_bf16 v[96:99], v[136:139], v[192:195], v[96:99]
	v_mfma_f32_16x16x32_bf16 v[100:103], v[128:131], v[192:195], v[100:103]
	v_mfma_f32_16x16x32_bf16 v[124:127], v[132:135], v[152:155], v[124:127]
	v_mfma_f32_16x16x32_bf16 v[120:123], v[140:143], v[152:155], v[120:123]
	v_mfma_f32_16x16x32_bf16 v[112:115], v[140:143], v[180:183], v[112:115]
	v_mfma_f32_16x16x32_bf16 v[116:119], v[132:135], v[180:183], v[116:119]
	v_mfma_f32_16x16x32_bf16 v[108:111], v[132:135], v[188:191], v[108:111]
	v_mfma_f32_16x16x32_bf16 v[104:107], v[140:143], v[188:191], v[104:107]
	v_mfma_f32_16x16x32_bf16 v[96:99], v[140:143], v[196:199], v[96:99]
	v_mfma_f32_16x16x32_bf16 v[100:103], v[132:135], v[196:199], v[100:103]
	s_barrier
	ds_read_b128 v[200:203], v173
	ds_read_b128 v[204:207], v173 offset:1024
	ds_read_b128 v[208:211], v173 offset:2048
	ds_read_b128 v[212:215], v173 offset:3072
	s_waitcnt vmcnt(8)
	s_barrier
	s_waitcnt lgkmcnt(0)
	v_mfma_f32_16x16x32_bf16 v[92:95], v[200:203], v[144:147], v[92:95]
	v_mfma_f32_16x16x32_bf16 v[88:91], v[208:211], v[144:147], v[88:91]
	v_mfma_f32_16x16x32_bf16 v[80:83], v[208:211], v[156:159], v[80:83]
	v_mfma_f32_16x16x32_bf16 v[84:87], v[200:203], v[156:159], v[84:87]
	v_mfma_f32_16x16x32_bf16 v[76:79], v[200:203], v[184:187], v[76:79]
	v_mfma_f32_16x16x32_bf16 v[72:75], v[208:211], v[184:187], v[72:75]
	v_mfma_f32_16x16x32_bf16 v[64:67], v[208:211], v[192:195], v[64:67]
	v_mfma_f32_16x16x32_bf16 v[68:71], v[200:203], v[192:195], v[68:71]
	v_mfma_f32_16x16x32_bf16 v[92:95], v[204:207], v[152:155], v[92:95]
	v_mfma_f32_16x16x32_bf16 v[88:91], v[212:215], v[152:155], v[88:91]
	v_mfma_f32_16x16x32_bf16 v[80:83], v[212:215], v[180:183], v[80:83]
	v_mfma_f32_16x16x32_bf16 v[84:87], v[204:207], v[180:183], v[84:87]
	v_mfma_f32_16x16x32_bf16 v[76:79], v[204:207], v[188:191], v[76:79]
	v_mfma_f32_16x16x32_bf16 v[72:75], v[212:215], v[188:191], v[72:75]
	v_mfma_f32_16x16x32_bf16 v[64:67], v[212:215], v[196:199], v[64:67]
	v_mfma_f32_16x16x32_bf16 v[68:71], v[204:207], v[196:199], v[68:71]
	s_barrier
	ds_read_b128 v[144:147], v169 offset:16384
	ds_read_b128 v[152:155], v169 offset:17408
	ds_read_b128 v[156:159], v170 offset:16384
	ds_read_b128 v[180:183], v170 offset:17408
	ds_read_b128 v[184:187], v171 offset:16384
	ds_read_b128 v[188:191], v171 offset:17408
	ds_read_b128 v[192:195], v172 offset:16384
	ds_read_b128 v[196:199], v172 offset:17408
	s_waitcnt vmcnt(4)
	s_barrier
	s_waitcnt lgkmcnt(0)
	v_mfma_f32_16x16x32_bf16 v[60:63], v[128:131], v[144:147], v[60:63]
	v_mfma_f32_16x16x32_bf16 v[56:59], v[136:139], v[144:147], v[56:59]
	v_mfma_f32_16x16x32_bf16 v[40:43], v[136:139], v[184:187], v[40:43]
	v_mfma_f32_16x16x32_bf16 v[60:63], v[132:135], v[152:155], v[60:63]
	v_mfma_f32_16x16x32_bf16 v[56:59], v[140:143], v[152:155], v[56:59]
	v_mfma_f32_16x16x32_bf16 v[52:55], v[128:131], v[156:159], v[52:55]
	v_mfma_f32_16x16x32_bf16 v[48:51], v[136:139], v[156:159], v[48:51]
	v_mfma_f32_16x16x32_bf16 v[44:47], v[128:131], v[184:187], v[44:47]
	v_mfma_f32_16x16x32_bf16 v[40:43], v[140:143], v[188:191], v[40:43]
	v_mfma_f32_16x16x32_bf16 v[36:39], v[128:131], v[192:195], v[36:39]
	v_mfma_f32_16x16x32_bf16 v[32:35], v[136:139], v[192:195], v[32:35]
	v_mfma_f32_16x16x32_bf16 v[52:55], v[132:135], v[180:183], v[52:55]
	v_mfma_f32_16x16x32_bf16 v[216:219], v[140:143], v[180:183], v[48:51]
	v_mfma_f32_16x16x32_bf16 v[44:47], v[132:135], v[188:191], v[44:47]
	v_mfma_f32_16x16x32_bf16 v[220:223], v[132:135], v[196:199], v[36:39]
	v_mfma_f32_16x16x32_bf16 v[32:35], v[140:143], v[196:199], v[32:35]
	v_mfma_f32_16x16x32_bf16 v[16:19], v[208:211], v[156:159], v[16:19]
	v_mfma_f32_16x16x32_bf16 v[4:7], v[200:203], v[192:195], v[4:7]
	v_mfma_f32_16x16x32_bf16 v[0:3], v[208:211], v[192:195], v[0:3]
	v_mfma_f32_16x16x32_bf16 v[24:27], v[208:211], v[144:147], v[24:27]
	v_mfma_f32_16x16x32_bf16 v[28:31], v[200:203], v[144:147], v[28:31]
	v_mfma_f32_16x16x32_bf16 v[20:23], v[200:203], v[156:159], v[20:23]
	v_mfma_f32_16x16x32_bf16 v[16:19], v[212:215], v[180:183], v[16:19]
	v_mfma_f32_16x16x32_bf16 v[12:15], v[200:203], v[184:187], v[12:15]
	v_mfma_f32_16x16x32_bf16 v[8:11], v[208:211], v[184:187], v[8:11]
	v_mfma_f32_16x16x32_bf16 v[4:7], v[204:207], v[196:199], v[4:7]
	v_mfma_f32_16x16x32_bf16 v[0:3], v[212:215], v[196:199], v[0:3]
	v_mfma_f32_16x16x32_bf16 v[224:227], v[204:207], v[152:155], v[28:31]
	v_mfma_f32_16x16x32_bf16 v[24:27], v[212:215], v[152:155], v[24:27]
	v_mfma_f32_16x16x32_bf16 v[20:23], v[204:207], v[180:183], v[20:23]
	v_mfma_f32_16x16x32_bf16 v[152:155], v[204:207], v[188:191], v[12:15]
	v_mfma_f32_16x16x32_bf16 v[156:159], v[212:215], v[188:191], v[8:11]
	s_barrier
; #define LDA(dst, b, h)                                                                                               \
;   _Pragma("unroll") for (int m = 0; m < 4; ++m) _Pragma("unroll") for (int k = 0; k < 2; ++k) dst[m][k] =            \
;       *reinterpret_cast<const bf16x8*>(SA(b, h) + lds_byte(wr * 64 + m * 16 + fr, k * 32 + fq * 8))
; #define LDB(dst, b, h)                                                                                               \
;   _Pragma("unroll") for (int n = 0; n < 2; ++n) _Pragma("unroll") for (int k = 0; k < 2; ++k) dst[n][k] =            \
;       *reinterpret_cast<const bf16x8*>(SB(b, h) + lds_byte(wc * 32 + n * 16 + fr, k * 32 + fq * 8))
; #define WAIT_V(n) asm volatile("s_waitcnt vmcnt(" #n ")" ::: "memory")
; #define WAIT_L(n) asm volatile("s_waitcnt lgkmcnt(" #n ")" ::: "memory")
; #define BAR __builtin_amdgcn_s_barrier()
; template <int EPI>
; __device__ __forceinline__ void gemm_phase(const u16* __restrict__ A, const u16* __restrict__ Bt, const int K,
;                                            const int nN, char* shm, const EpiArgs& ea) {
;     ...
;     {
;       LDB(B0, 1, 0); LDA(At, 1, 0); WAIT_V(2); BAR; WAIT_L(0); MMA(0, 0, At, B0); BAR;
;       LDB(B1, 1, 1); WAIT_V(0); BAR; WAIT_L(0); MMA(0, 1, At, B1); BAR;
;       LDA(At, 1, 1); BAR; WAIT_L(0); MMA(1, 0, At, B0); MMA(1, 1, At, B1); BAR;
;     }
;     if (wr == 0) BAR;
	s_nop 0
	ds_read_b128 v[8:11], v176
	ds_read_b128 v[12:15], v176 offset:1024
	ds_read_b128 v[180:183], v176 offset:2048
	ds_read_b128 v[184:187], v176 offset:3072
	ds_read_b128 v[128:131], v169 offset:32768
	ds_read_b128 v[132:135], v169 offset:33792
	ds_read_b128 v[188:191], v170 offset:32768
	ds_read_b128 v[192:195], v170 offset:33792
	ds_read_b128 v[196:199], v171 offset:32768
	ds_read_b128 v[200:203], v171 offset:33792
	ds_read_b128 v[204:207], v172 offset:32768
	ds_read_b128 v[208:211], v172 offset:33792
	s_waitcnt vmcnt(2)
	s_barrier
	s_waitcnt lgkmcnt(0)
	v_mfma_f32_16x16x32_bf16 v[48:51], v[8:11], v[188:191], v[116:119]
	v_mfma_f32_16x16x32_bf16 v[140:143], v[12:15], v[192:195], v[48:51]
	v_mfma_f32_16x16x32_bf16 v[48:51], v[180:183], v[188:191], v[112:115]
	v_mfma_f32_16x16x32_bf16 v[136:139], v[184:187], v[192:195], v[48:51]
	v_mfma_f32_16x16x32_bf16 v[48:51], v[8:11], v[196:199], v[108:111]
	v_mfma_f32_16x16x32_bf16 v[28:31], v[8:11], v[128:131], v[124:127]
	v_mfma_f32_16x16x32_bf16 v[124:127], v[12:15], v[200:203], v[48:51]
	v_mfma_f32_16x16x32_bf16 v[48:51], v[180:183], v[196:199], v[104:107]
	v_mfma_f32_16x16x32_bf16 v[36:39], v[180:183], v[128:131], v[120:123]
	v_mfma_f32_16x16x32_bf16 v[120:123], v[184:187], v[200:203], v[48:51]
	v_mfma_f32_16x16x32_bf16 v[48:51], v[8:11], v[204:207], v[100:103]
	v_mfma_f32_16x16x32_bf16 v[108:111], v[12:15], v[208:211], v[48:51]
	v_mfma_f32_16x16x32_bf16 v[48:51], v[180:183], v[204:207], v[96:99]
	v_mfma_f32_16x16x32_bf16 v[28:31], v[12:15], v[132:135], v[28:31]
	v_mfma_f32_16x16x32_bf16 v[36:39], v[184:187], v[132:135], v[36:39]
	v_mfma_f32_16x16x32_bf16 v[104:107], v[184:187], v[208:211], v[48:51]
	s_barrier
	ds_read_b128 v[212:215], v177
	ds_read_b128 v[228:231], v177 offset:1024
	ds_read_b128 v[232:235], v177 offset:2048
	ds_read_b128 v[236:239], v177 offset:3072
	s_waitcnt vmcnt(0)
	s_barrier
	s_waitcnt lgkmcnt(0)
	v_mfma_f32_16x16x32_bf16 v[48:51], v[212:215], v[128:131], v[92:95]
	v_mfma_f32_16x16x32_bf16 v[88:91], v[232:235], v[128:131], v[88:91]
	v_mfma_f32_16x16x32_bf16 v[84:87], v[212:215], v[188:191], v[84:87]
	v_mfma_f32_16x16x32_bf16 v[80:83], v[232:235], v[188:191], v[80:83]
	v_mfma_f32_16x16x32_bf16 v[72:75], v[232:235], v[196:199], v[72:75]
	v_mfma_f32_16x16x32_bf16 v[76:79], v[212:215], v[196:199], v[76:79]
	v_mfma_f32_16x16x32_bf16 v[68:71], v[212:215], v[204:207], v[68:71]
	v_mfma_f32_16x16x32_bf16 v[64:67], v[232:235], v[204:207], v[64:67]
	v_mfma_f32_16x16x32_bf16 v[48:51], v[228:231], v[132:135], v[48:51]
	v_mfma_f32_16x16x32_bf16 v[144:147], v[236:239], v[132:135], v[88:91]
	v_mfma_f32_16x16x32_bf16 v[132:135], v[228:231], v[192:195], v[84:87]
	v_mfma_f32_16x16x32_bf16 v[128:131], v[236:239], v[192:195], v[80:83]
	v_mfma_f32_16x16x32_bf16 v[116:119], v[228:231], v[200:203], v[76:79]
	v_mfma_f32_16x16x32_bf16 v[112:115], v[236:239], v[200:203], v[72:75]
	v_mfma_f32_16x16x32_bf16 v[100:103], v[228:231], v[208:211], v[68:71]
	v_mfma_f32_16x16x32_bf16 v[96:99], v[236:239], v[208:211], v[64:67]
	s_barrier
	s_nop 0
	ds_read_b128 v[64:67], v169 offset:49152
	ds_read_b128 v[68:71], v169 offset:50176
	ds_read_b128 v[188:191], v170 offset:49152
	ds_read_b128 v[192:195], v170 offset:50176
	ds_read_b128 v[196:199], v171 offset:49152
	ds_read_b128 v[200:203], v171 offset:50176
	ds_read_b128 v[204:207], v172 offset:49152
	ds_read_b128 v[208:211], v172 offset:50176
	s_barrier
	s_waitcnt lgkmcnt(0)
	v_mfma_f32_16x16x32_bf16 v[60:63], v[8:11], v[64:67], v[60:63]
	v_mfma_f32_16x16x32_bf16 v[52:55], v[8:11], v[188:191], v[52:55]
	v_mfma_f32_16x16x32_bf16 v[44:47], v[8:11], v[196:199], v[44:47]
	v_mfma_f32_16x16x32_bf16 v[8:11], v[8:11], v[204:207], v[220:223]
	v_mfma_f32_16x16x32_bf16 v[92:95], v[12:15], v[68:71], v[60:63]
	v_mfma_f32_16x16x32_bf16 v[56:59], v[180:183], v[64:67], v[56:59]
	v_mfma_f32_16x16x32_bf16 v[76:79], v[12:15], v[192:195], v[52:55]
	v_mfma_f32_16x16x32_bf16 v[52:55], v[180:183], v[188:191], v[216:219]
	v_mfma_f32_16x16x32_bf16 v[60:63], v[12:15], v[200:203], v[44:47]
	v_mfma_f32_16x16x32_bf16 v[40:43], v[180:183], v[196:199], v[40:43]
	v_mfma_f32_16x16x32_bf16 v[12:15], v[12:15], v[208:211], v[8:11]
	v_mfma_f32_16x16x32_bf16 v[8:11], v[180:183], v[204:207], v[32:35]
	v_mfma_f32_16x16x32_bf16 v[88:91], v[184:187], v[68:71], v[56:59]
	v_mfma_f32_16x16x32_bf16 v[72:75], v[184:187], v[192:195], v[52:55]
	v_mfma_f32_16x16x32_bf16 v[56:59], v[184:187], v[200:203], v[40:43]
	v_mfma_f32_16x16x32_bf16 v[8:11], v[184:187], v[208:211], v[8:11]
	v_mfma_f32_16x16x32_bf16 v[16:19], v[232:235], v[188:191], v[16:19]
	v_mfma_f32_16x16x32_bf16 v[32:35], v[212:215], v[64:67], v[224:227]
	v_mfma_f32_16x16x32_bf16 v[24:27], v[232:235], v[64:67], v[24:27]
	v_mfma_f32_16x16x32_bf16 v[64:67], v[236:239], v[192:195], v[16:19]
	v_mfma_f32_16x16x32_bf16 v[16:19], v[212:215], v[196:199], v[152:155]
	v_mfma_f32_16x16x32_bf16 v[20:23], v[212:215], v[188:191], v[20:23]
	v_mfma_f32_16x16x32_bf16 v[40:43], v[228:231], v[200:203], v[16:19]
	v_mfma_f32_16x16x32_bf16 v[16:19], v[232:235], v[196:199], v[156:159]
	v_mfma_f32_16x16x32_bf16 v[4:7], v[212:215], v[204:207], v[4:7]
	v_mfma_f32_16x16x32_bf16 v[0:3], v[232:235], v[204:207], v[0:3]
	v_mfma_f32_16x16x32_bf16 v[84:87], v[228:231], v[68:71], v[32:35]
	v_mfma_f32_16x16x32_bf16 v[80:83], v[236:239], v[68:71], v[24:27]
	v_mfma_f32_16x16x32_bf16 v[68:71], v[228:231], v[192:195], v[20:23]
	v_mfma_f32_16x16x32_bf16 v[16:19], v[236:239], v[200:203], v[16:19]
	v_mfma_f32_16x16x32_bf16 v[4:7], v[228:231], v[208:211], v[4:7]
	v_mfma_f32_16x16x32_bf16 v[0:3], v[236:239], v[208:211], v[0:3]
	s_andn2_b64 vcc, exec, s[36:37]
	s_barrier
	s_cbranch_vccz .LBB0_380
	s_andn2_b64 vcc, exec, s[4:5]
	s_cbranch_vccz .LBB0_381

; #define LDA(dst, b, h)                                                                                               \
;   _Pragma("unroll") for (int m = 0; m < 4; ++m) _Pragma("unroll") for (int k = 0; k < 2; ++k) dst[m][k] =            \
;       *reinterpret_cast<const bf16x8*>(SA(b, h) + lds_byte(wr * 64 + m * 16 + fr, k * 32 + fq * 8))
; #define LDB(dst, b, h)                                                                                               \
;   _Pragma("unroll") for (int n = 0; n < 2; ++n) _Pragma("unroll") for (int k = 0; k < 2; ++k) dst[n][k] =            \
;       *reinterpret_cast<const bf16x8*>(SB(b, h) + lds_byte(wc * 32 + n * 16 + fr, k * 32 + fq * 8))
; #define WAIT_V(n) asm volatile("s_waitcnt vmcnt(" #n ")" ::: "memory")
; #define WAIT_L(n) asm volatile("s_waitcnt lgkmcnt(" #n ")" ::: "memory")
; #define BAR __builtin_amdgcn_s_barrier()
; #define SCHED __builtin_amdgcn_sched_barrier(0)
; template <int EPI>
; __device__ __forceinline__ void gemm_phase(const u16* __restrict__ A, const u16* __restrict__ Bt, const int K,
;                                            const int nN, char* shm, const EpiArgs& ea) {
;     ...
;       LDB(B0, 0, 0); SCHED; LDA(At, 0, 0); STAGE(SA(1, 1), rA, brow + HALF, t + 1);
;       WAIT_V(10); WAIT_L(8); BAR; WAIT_L(0); MMA(0, 0, At, B0); BAR; SCHED;
;       LDB(B1, 0, 1); STAGE(SB(0, 0), rB, bcol, t + 2);
;       WAIT_V(10); BAR; WAIT_L(0); MMA(0, 1, At, B1); BAR;
;       LDA(At, 0, 1); STAGE(SA(0, 0), rA, brow, t + 2);
;       BAR; WAIT_L(0); MMA(1, 0, At, B0); BAR; SCHED;
;       STAGE(SB(0, 1), rB, bcol + HALF, t + 2);
;       WAIT_V(10); BAR; MMA(1, 1, At, B1); BAR;
.LBB0_492:
	ds_read_b128 v[130:133], v146
	ds_read_b128 v[134:137], v146 offset:1024
	ds_read_b128 v[138:141], v146 offset:2048
	ds_read_b128 v[154:157], v146 offset:3072
	s_add_i32 s65, s59, s64
	s_mov_b32 m0, s34
	s_add_i32 s10, s65, 0x4000
	ds_read_b128 v[158:161], v147
	ds_read_b128 v[162:165], v147 offset:1024
	ds_read_b128 v[166:169], v148
	ds_read_b128 v[170:173], v148 offset:1024
	ds_read_b128 v[176:179], v149
	ds_read_b128 v[180:183], v149 offset:1024
	ds_read_b128 v[184:187], v150
	ds_read_b128 v[188:191], v150 offset:1024
	buffer_load_dwordx4 v142, s[0:3], s10 offen lds
	s_add_i32 s10, s65, 0x6000
	s_mov_b32 m0, s35
	s_nop 0
	buffer_load_dwordx4 v142, s[0:3], s10 offen lds
	s_waitcnt vmcnt(10)
	s_waitcnt lgkmcnt(8)
	s_barrier
	s_waitcnt lgkmcnt(0)
	v_mfma_f32_16x16x32_bf16 v[124:127], v[130:133], v[158:161], v[124:127]
	v_mfma_f32_16x16x32_bf16 v[120:123], v[138:141], v[158:161], v[120:123]
	v_mfma_f32_16x16x32_bf16 v[112:115], v[138:141], v[166:169], v[112:115]
	v_mfma_f32_16x16x32_bf16 v[116:119], v[130:133], v[166:169], v[116:119]
	v_mfma_f32_16x16x32_bf16 v[108:111], v[130:133], v[176:179], v[108:111]
	v_mfma_f32_16x16x32_bf16 v[104:107], v[138:141], v[176:179], v[104:107]
	v_mfma_f32_16x16x32_bf16 v[96:99], v[138:141], v[184:187], v[96:99]
	v_mfma_f32_16x16x32_bf16 v[100:103], v[130:133], v[184:187], v[100:103]
	v_mfma_f32_16x16x32_bf16 v[124:127], v[134:137], v[162:165], v[124:127]
	v_mfma_f32_16x16x32_bf16 v[120:123], v[154:157], v[162:165], v[120:123]
	v_mfma_f32_16x16x32_bf16 v[112:115], v[154:157], v[170:173], v[112:115]
	v_mfma_f32_16x16x32_bf16 v[116:119], v[134:137], v[170:173], v[116:119]
	v_mfma_f32_16x16x32_bf16 v[108:111], v[134:137], v[180:183], v[108:111]
	v_mfma_f32_16x16x32_bf16 v[104:107], v[154:157], v[180:183], v[104:107]
	v_mfma_f32_16x16x32_bf16 v[96:99], v[154:157], v[188:191], v[96:99]
	v_mfma_f32_16x16x32_bf16 v[100:103], v[134:137], v[188:191], v[100:103]
	s_barrier
	s_add_i32 s66, s62, s64
	s_mov_b32 m0, s36
	s_add_i32 s67, s66, 0x8000
	s_mov_b32 s10, s2
	s_mov_b32 s11, s3
	ds_read_b128 v[192:195], v151
	ds_read_b128 v[196:199], v151 offset:1024
	ds_read_b128 v[200:203], v151 offset:2048
	ds_read_b128 v[204:207], v151 offset:3072
	buffer_load_dwordx4 v142, s[8:11], s67 offen lds
	s_add_i32 s67, s66, 0xa000
	s_mov_b32 m0, s37
	s_nop 0
	buffer_load_dwordx4 v142, s[8:11], s67 offen lds
	s_waitcnt vmcnt(10)
	s_barrier
	s_waitcnt lgkmcnt(0)
	v_mfma_f32_16x16x32_bf16 v[92:95], v[192:195], v[158:161], v[92:95]
	v_mfma_f32_16x16x32_bf16 v[88:91], v[200:203], v[158:161], v[88:91]
	v_mfma_f32_16x16x32_bf16 v[80:83], v[200:203], v[166:169], v[80:83]
	v_mfma_f32_16x16x32_bf16 v[84:87], v[192:195], v[166:169], v[84:87]
	v_mfma_f32_16x16x32_bf16 v[76:79], v[192:195], v[176:179], v[76:79]
	v_mfma_f32_16x16x32_bf16 v[72:75], v[200:203], v[176:179], v[72:75]
	v_mfma_f32_16x16x32_bf16 v[64:67], v[200:203], v[184:187], v[64:67]
	v_mfma_f32_16x16x32_bf16 v[68:71], v[192:195], v[184:187], v[68:71]
	v_mfma_f32_16x16x32_bf16 v[92:95], v[196:199], v[162:165], v[92:95]
	v_mfma_f32_16x16x32_bf16 v[88:91], v[204:207], v[162:165], v[88:91]
	v_mfma_f32_16x16x32_bf16 v[80:83], v[204:207], v[170:173], v[80:83]
	v_mfma_f32_16x16x32_bf16 v[84:87], v[196:199], v[170:173], v[84:87]
	v_mfma_f32_16x16x32_bf16 v[76:79], v[196:199], v[180:183], v[76:79]
	v_mfma_f32_16x16x32_bf16 v[72:75], v[204:207], v[180:183], v[72:75]
	v_mfma_f32_16x16x32_bf16 v[64:67], v[204:207], v[188:191], v[64:67]
	v_mfma_f32_16x16x32_bf16 v[68:71], v[196:199], v[188:191], v[68:71]
	s_add_i32 s67, s61, s64
	s_mov_b32 m0, s27
	s_add_i32 s68, s67, 0x8000
	s_barrier
	ds_read_b128 v[158:161], v147 offset:16384
	ds_read_b128 v[162:165], v147 offset:17408
	ds_read_b128 v[166:169], v148 offset:16384
	ds_read_b128 v[170:173], v148 offset:17408
	ds_read_b128 v[176:179], v149 offset:16384
	ds_read_b128 v[180:183], v149 offset:17408
	ds_read_b128 v[184:187], v150 offset:16384
	ds_read_b128 v[188:191], v150 offset:17408
	buffer_load_dwordx4 v142, s[0:3], s68 offen lds
	s_add_i32 s68, s67, 0xa000
	s_mov_b32 m0, s38
	s_nop 0
	buffer_load_dwordx4 v142, s[0:3], s68 offen lds
	s_barrier
	s_waitcnt lgkmcnt(0)
	v_mfma_f32_16x16x32_bf16 v[60:63], v[130:133], v[158:161], v[60:63]
	v_mfma_f32_16x16x32_bf16 v[56:59], v[138:141], v[158:161], v[56:59]
	v_mfma_f32_16x16x32_bf16 v[48:51], v[138:141], v[166:169], v[48:51]
	v_mfma_f32_16x16x32_bf16 v[52:55], v[130:133], v[166:169], v[52:55]
	v_mfma_f32_16x16x32_bf16 v[44:47], v[130:133], v[176:179], v[44:47]
	v_mfma_f32_16x16x32_bf16 v[40:43], v[138:141], v[176:179], v[40:43]
	v_mfma_f32_16x16x32_bf16 v[32:35], v[138:141], v[184:187], v[32:35]
	v_mfma_f32_16x16x32_bf16 v[36:39], v[130:133], v[184:187], v[36:39]
	v_mfma_f32_16x16x32_bf16 v[60:63], v[134:137], v[162:165], v[60:63]
	v_mfma_f32_16x16x32_bf16 v[56:59], v[154:157], v[162:165], v[56:59]
	v_mfma_f32_16x16x32_bf16 v[48:51], v[154:157], v[170:173], v[48:51]
	v_mfma_f32_16x16x32_bf16 v[52:55], v[134:137], v[170:173], v[52:55]
	v_mfma_f32_16x16x32_bf16 v[44:47], v[134:137], v[180:183], v[44:47]
	v_mfma_f32_16x16x32_bf16 v[40:43], v[154:157], v[180:183], v[40:43]
	v_mfma_f32_16x16x32_bf16 v[32:35], v[154:157], v[188:191], v[32:35]
	v_mfma_f32_16x16x32_bf16 v[36:39], v[134:137], v[188:191], v[36:39]
	s_barrier
	s_add_i32 s68, s60, s64
	s_mov_b32 m0, s39
	s_add_i32 s69, s68, 0x8000
	buffer_load_dwordx4 v142, s[8:11], s69 offen lds
	s_add_i32 s69, s68, 0xa000
	s_mov_b32 m0, s40
	s_nop 0
	buffer_load_dwordx4 v142, s[8:11], s69 offen lds
	s_waitcnt vmcnt(10)
	s_barrier
; #define LDA(dst, b, h)                                                                                               \
;   _Pragma("unroll") for (int m = 0; m < 4; ++m) _Pragma("unroll") for (int k = 0; k < 2; ++k) dst[m][k] =            \
;       *reinterpret_cast<const bf16x8*>(SA(b, h) + lds_byte(wr * 64 + m * 16 + fr, k * 32 + fq * 8))
; #define LDB(dst, b, h)                                                                                               \
;   _Pragma("unroll") for (int n = 0; n < 2; ++n) _Pragma("unroll") for (int k = 0; k < 2; ++k) dst[n][k] =            \
;       *reinterpret_cast<const bf16x8*>(SB(b, h) + lds_byte(wc * 32 + n * 16 + fr, k * 32 + fq * 8))
; #define WAIT_V(n) asm volatile("s_waitcnt vmcnt(" #n ")" ::: "memory")
; #define WAIT_L(n) asm volatile("s_waitcnt lgkmcnt(" #n ")" ::: "memory")
; #define BAR __builtin_amdgcn_s_barrier()
; #define SCHED __builtin_amdgcn_sched_barrier(0)
; template <int EPI>
; __device__ __forceinline__ void gemm_phase(const u16* __restrict__ A, const u16* __restrict__ Bt, const int K,
;                                            const int nN, char* shm, const EpiArgs& ea) {
;     ...
;       WAIT_V(10); BAR; MMA(1, 1, At, B1); BAR;
;       LDB(B0, 1, 0); SCHED; LDA(At, 1, 0); STAGE(SA(0, 1), rA, brow + HALF, t + 2);
;       WAIT_V(10); WAIT_L(8); BAR; WAIT_L(0); MMA(0, 0, At, B0); BAR; SCHED;
;       LDB(B1, 1, 1); STAGE(SB(1, 0), rB, bcol, t + 3);
;       WAIT_V(10); BAR; WAIT_L(0); MMA(0, 1, At, B1); BAR;
;       LDA(At, 1, 1); STAGE(SA(1, 0), rA, brow, t + 3);
;       BAR; WAIT_L(0); MMA(1, 0, At, B0); BAR; SCHED;
	v_mfma_f32_16x16x32_bf16 v[28:31], v[192:195], v[158:161], v[28:31]
	v_mfma_f32_16x16x32_bf16 v[24:27], v[200:203], v[158:161], v[24:27]
	v_mfma_f32_16x16x32_bf16 v[16:19], v[200:203], v[166:169], v[16:19]
	v_mfma_f32_16x16x32_bf16 v[20:23], v[192:195], v[166:169], v[20:23]
	v_mfma_f32_16x16x32_bf16 v[12:15], v[192:195], v[176:179], v[12:15]
	v_mfma_f32_16x16x32_bf16 v[8:11], v[200:203], v[176:179], v[8:11]
	v_mfma_f32_16x16x32_bf16 v[0:3], v[200:203], v[184:187], v[0:3]
	v_mfma_f32_16x16x32_bf16 v[4:7], v[192:195], v[184:187], v[4:7]
	v_mfma_f32_16x16x32_bf16 v[28:31], v[196:199], v[162:165], v[28:31]
	v_mfma_f32_16x16x32_bf16 v[24:27], v[204:207], v[162:165], v[24:27]
	v_mfma_f32_16x16x32_bf16 v[16:19], v[204:207], v[170:173], v[16:19]
	v_mfma_f32_16x16x32_bf16 v[20:23], v[196:199], v[170:173], v[20:23]
	v_mfma_f32_16x16x32_bf16 v[12:15], v[196:199], v[180:183], v[12:15]
	v_mfma_f32_16x16x32_bf16 v[8:11], v[204:207], v[180:183], v[8:11]
	v_mfma_f32_16x16x32_bf16 v[0:3], v[204:207], v[188:191], v[0:3]
	v_mfma_f32_16x16x32_bf16 v[4:7], v[196:199], v[188:191], v[4:7]
	s_barrier
	ds_read_b128 v[130:133], v152
	ds_read_b128 v[134:137], v152 offset:1024
	ds_read_b128 v[138:141], v152 offset:2048
	ds_read_b128 v[154:157], v152 offset:3072
	s_mov_b32 m0, s41
	s_add_i32 s69, s65, 0x8000
	ds_read_b128 v[158:161], v147 offset:32768
	ds_read_b128 v[162:165], v147 offset:33792
	ds_read_b128 v[166:169], v148 offset:32768
	ds_read_b128 v[170:173], v148 offset:33792
	ds_read_b128 v[176:179], v149 offset:32768
	ds_read_b128 v[180:183], v149 offset:33792
	ds_read_b128 v[184:187], v150 offset:32768
	ds_read_b128 v[188:191], v150 offset:33792
	buffer_load_dwordx4 v142, s[0:3], s69 offen lds
	s_add_i32 s65, s65, 0xa000
	s_mov_b32 m0, s42
	s_nop 0
	buffer_load_dwordx4 v142, s[0:3], s65 offen lds
	s_waitcnt vmcnt(10)
	s_waitcnt lgkmcnt(8)
	s_barrier
	s_waitcnt lgkmcnt(0)
	v_mfma_f32_16x16x32_bf16 v[124:127], v[130:133], v[158:161], v[124:127]
	v_mfma_f32_16x16x32_bf16 v[120:123], v[138:141], v[158:161], v[120:123]
	v_mfma_f32_16x16x32_bf16 v[112:115], v[138:141], v[166:169], v[112:115]
	v_mfma_f32_16x16x32_bf16 v[116:119], v[130:133], v[166:169], v[116:119]
	v_mfma_f32_16x16x32_bf16 v[108:111], v[130:133], v[176:179], v[108:111]
	v_mfma_f32_16x16x32_bf16 v[104:107], v[138:141], v[176:179], v[104:107]
	v_mfma_f32_16x16x32_bf16 v[96:99], v[138:141], v[184:187], v[96:99]
	v_mfma_f32_16x16x32_bf16 v[100:103], v[130:133], v[184:187], v[100:103]
	v_mfma_f32_16x16x32_bf16 v[124:127], v[134:137], v[162:165], v[124:127]
	v_mfma_f32_16x16x32_bf16 v[120:123], v[154:157], v[162:165], v[120:123]
	v_mfma_f32_16x16x32_bf16 v[112:115], v[154:157], v[170:173], v[112:115]
	v_mfma_f32_16x16x32_bf16 v[116:119], v[134:137], v[170:173], v[116:119]
	v_mfma_f32_16x16x32_bf16 v[108:111], v[134:137], v[180:183], v[108:111]
	v_mfma_f32_16x16x32_bf16 v[104:107], v[154:157], v[180:183], v[104:107]
	v_mfma_f32_16x16x32_bf16 v[96:99], v[154:157], v[188:191], v[96:99]
	v_mfma_f32_16x16x32_bf16 v[100:103], v[134:137], v[188:191], v[100:103]
	s_barrier
	s_mov_b32 m0, s43
	s_add_i32 s65, s66, 0xc000
	ds_read_b128 v[192:195], v153
	ds_read_b128 v[196:199], v153 offset:1024
	ds_read_b128 v[200:203], v153 offset:2048
	ds_read_b128 v[204:207], v153 offset:3072
	buffer_load_dwordx4 v142, s[8:11], s65 offen lds
	s_add_i32 s66, s66, 0xe000
	s_mov_b32 m0, s48
	s_nop 0
	buffer_load_dwordx4 v142, s[8:11], s66 offen lds
	s_waitcnt vmcnt(10)
	s_barrier
	s_waitcnt lgkmcnt(0)
	v_mfma_f32_16x16x32_bf16 v[92:95], v[192:195], v[158:161], v[92:95]
	v_mfma_f32_16x16x32_bf16 v[88:91], v[200:203], v[158:161], v[88:91]
	v_mfma_f32_16x16x32_bf16 v[80:83], v[200:203], v[166:169], v[80:83]
	v_mfma_f32_16x16x32_bf16 v[84:87], v[192:195], v[166:169], v[84:87]
	v_mfma_f32_16x16x32_bf16 v[76:79], v[192:195], v[176:179], v[76:79]
	v_mfma_f32_16x16x32_bf16 v[72:75], v[200:203], v[176:179], v[72:75]
	v_mfma_f32_16x16x32_bf16 v[64:67], v[200:203], v[184:187], v[64:67]
	v_mfma_f32_16x16x32_bf16 v[68:71], v[192:195], v[184:187], v[68:71]
	v_mfma_f32_16x16x32_bf16 v[92:95], v[196:199], v[162:165], v[92:95]
	v_mfma_f32_16x16x32_bf16 v[88:91], v[204:207], v[162:165], v[88:91]
	v_mfma_f32_16x16x32_bf16 v[80:83], v[204:207], v[170:173], v[80:83]
	v_mfma_f32_16x16x32_bf16 v[84:87], v[196:199], v[170:173], v[84:87]
	v_mfma_f32_16x16x32_bf16 v[76:79], v[196:199], v[180:183], v[76:79]
	v_mfma_f32_16x16x32_bf16 v[72:75], v[204:207], v[180:183], v[72:75]
	v_mfma_f32_16x16x32_bf16 v[64:67], v[204:207], v[188:191], v[64:67]
	v_mfma_f32_16x16x32_bf16 v[68:71], v[196:199], v[188:191], v[68:71]
	s_mov_b32 m0, s49
	s_add_i32 s65, s67, 0xc000
	s_barrier
	ds_read_b128 v[158:161], v147 offset:49152
	ds_read_b128 v[162:165], v147 offset:50176
	ds_read_b128 v[166:169], v148 offset:49152
	ds_read_b128 v[170:173], v148 offset:50176
	ds_read_b128 v[176:179], v149 offset:49152
	ds_read_b128 v[180:183], v149 offset:50176
	ds_read_b128 v[184:187], v150 offset:49152
	ds_read_b128 v[188:191], v150 offset:50176
	buffer_load_dwordx4 v142, s[0:3], s65 offen lds
	s_add_i32 s67, s67, 0xe000
	s_mov_b32 m0, s50
	s_nop 0
	buffer_load_dwordx4 v142, s[0:3], s67 offen lds
	s_barrier
; #define LDA(dst, b, h)                                                                                               \
;   _Pragma("unroll") for (int m = 0; m < 4; ++m) _Pragma("unroll") for (int k = 0; k < 2; ++k) dst[m][k] =            \
;       *reinterpret_cast<const bf16x8*>(SA(b, h) + lds_byte(wr * 64 + m * 16 + fr, k * 32 + fq * 8))
; #define LDB(dst, b, h)                                                                                               \
;   _Pragma("unroll") for (int n = 0; n < 2; ++n) _Pragma("unroll") for (int k = 0; k < 2; ++k) dst[n][k] =            \
;       *reinterpret_cast<const bf16x8*>(SB(b, h) + lds_byte(wc * 32 + n * 16 + fr, k * 32 + fq * 8))
; #define WAIT_V(n) asm volatile("s_waitcnt vmcnt(" #n ")" ::: "memory")
; #define WAIT_L(n) asm volatile("s_waitcnt lgkmcnt(" #n ")" ::: "memory")
; #define BAR __builtin_amdgcn_s_barrier()
; #define SCHED __builtin_amdgcn_sched_barrier(0)
; template <int EPI>
; __device__ __forceinline__ void gemm_phase(const u16* __restrict__ A, const u16* __restrict__ Bt, const int K,
;                                            const int nN, char* shm, const EpiArgs& ea) {
;     ...
;       BAR; WAIT_L(0); MMA(1, 0, At, B0); BAR; SCHED;
;       STAGE(SB(1, 1), rB, bcol + HALF, t + 3);
;       WAIT_V(10); BAR; MMA(1, 1, At, B1); BAR;
;     }
;     float eC = 0.f, eB = 0.f;
;     float2 eS = make_float2(0.f, 0.f);
;     if (EPI == EPI_IN || EPI == EPI_SWIGLU_LN) {
;       if (wr == 0) {
;         eC = ea.c1[bcol + tid];
;         eS = *(const float2*)(ea.st_in + (size_t)(brow + tid) * 2);
;       } else {
;         eC = ea.c2[bcol + tid - 256];
;         if (EPI == EPI_IN) eB = ea.bias[bcol + tid - 256];
;       }
;     }
;     {
;       LDB(B0, 0, 0); LDA(At, 0, 0); STAGE(SA(1, 1), rA, brow + HALF, nt - 1);
;       WAIT_V(10); BAR; WAIT_L(0); MMA(0, 0, At, B0); BAR;
;       LDB(B1, 0, 1); WAIT_V(8); BAR; WAIT_L(0); MMA(0, 1, At, B1); BAR;
;       LDA(At, 0, 1); WAIT_V(4); BAR; WAIT_L(0); MMA(1, 0, At, B0); MMA(1, 1, At, B1); BAR;
	s_waitcnt lgkmcnt(0)
	v_mfma_f32_16x16x32_bf16 v[60:63], v[130:133], v[158:161], v[60:63]
	v_mfma_f32_16x16x32_bf16 v[56:59], v[138:141], v[158:161], v[56:59]
	v_mfma_f32_16x16x32_bf16 v[48:51], v[138:141], v[166:169], v[48:51]
	v_mfma_f32_16x16x32_bf16 v[52:55], v[130:133], v[166:169], v[52:55]
	v_mfma_f32_16x16x32_bf16 v[44:47], v[130:133], v[176:179], v[44:47]
	v_mfma_f32_16x16x32_bf16 v[40:43], v[138:141], v[176:179], v[40:43]
	v_mfma_f32_16x16x32_bf16 v[32:35], v[138:141], v[184:187], v[32:35]
	v_mfma_f32_16x16x32_bf16 v[36:39], v[130:133], v[184:187], v[36:39]
	v_mfma_f32_16x16x32_bf16 v[60:63], v[134:137], v[162:165], v[60:63]
	v_mfma_f32_16x16x32_bf16 v[56:59], v[154:157], v[162:165], v[56:59]
	v_mfma_f32_16x16x32_bf16 v[48:51], v[154:157], v[170:173], v[48:51]
	v_mfma_f32_16x16x32_bf16 v[52:55], v[134:137], v[170:173], v[52:55]
	v_mfma_f32_16x16x32_bf16 v[44:47], v[134:137], v[180:183], v[44:47]
	v_mfma_f32_16x16x32_bf16 v[40:43], v[154:157], v[180:183], v[40:43]
	v_mfma_f32_16x16x32_bf16 v[32:35], v[154:157], v[188:191], v[32:35]
	v_mfma_f32_16x16x32_bf16 v[36:39], v[134:137], v[188:191], v[36:39]
	s_barrier
	s_mov_b32 m0, s51
	s_add_i32 s65, s68, 0xc000
	buffer_load_dwordx4 v142, s[8:11], s65 offen lds
	s_add_i32 s68, s68, 0xe000
	s_mov_b32 m0, s52
	s_nop 0
	buffer_load_dwordx4 v142, s[8:11], s68 offen lds
	s_waitcnt vmcnt(10)
	s_barrier
	v_mfma_f32_16x16x32_bf16 v[28:31], v[192:195], v[158:161], v[28:31]
	v_mfma_f32_16x16x32_bf16 v[24:27], v[200:203], v[158:161], v[24:27]
	v_mfma_f32_16x16x32_bf16 v[16:19], v[200:203], v[166:169], v[16:19]
	v_mfma_f32_16x16x32_bf16 v[20:23], v[192:195], v[166:169], v[20:23]
	v_mfma_f32_16x16x32_bf16 v[12:15], v[192:195], v[176:179], v[12:15]
	v_mfma_f32_16x16x32_bf16 v[8:11], v[200:203], v[176:179], v[8:11]
	v_mfma_f32_16x16x32_bf16 v[0:3], v[200:203], v[184:187], v[0:3]
	v_mfma_f32_16x16x32_bf16 v[4:7], v[192:195], v[184:187], v[4:7]
	v_mfma_f32_16x16x32_bf16 v[28:31], v[196:199], v[162:165], v[28:31]
	v_mfma_f32_16x16x32_bf16 v[24:27], v[204:207], v[162:165], v[24:27]
	v_mfma_f32_16x16x32_bf16 v[16:19], v[204:207], v[170:173], v[16:19]
	v_mfma_f32_16x16x32_bf16 v[20:23], v[196:199], v[170:173], v[20:23]
	v_mfma_f32_16x16x32_bf16 v[12:15], v[196:199], v[180:183], v[12:15]
	v_mfma_f32_16x16x32_bf16 v[8:11], v[204:207], v[180:183], v[8:11]
	v_mfma_f32_16x16x32_bf16 v[0:3], v[204:207], v[188:191], v[0:3]
	v_mfma_f32_16x16x32_bf16 v[4:7], v[196:199], v[188:191], v[4:7]
	s_add_i32 s63, s63, 2
	s_add_i32 s64, s64, 0x8000
	s_cmp_lt_u32 s63, 28
	s_barrier
	s_cbranch_scc1 .LBB0_492
	s_mov_b32 m0, s34
	s_add_i32 s10, s59, 0x7c000
	ds_read_b128 v[130:133], v146
	ds_read_b128 v[134:137], v146 offset:1024
	ds_read_b128 v[138:141], v146 offset:2048
	ds_read_b128 v[154:157], v146 offset:3072
	ds_read_b128 v[158:161], v147
	ds_read_b128 v[162:165], v147 offset:1024
	ds_read_b128 v[166:169], v148
	ds_read_b128 v[170:173], v148 offset:1024
	ds_read_b128 v[176:179], v149
	ds_read_b128 v[180:183], v149 offset:1024
	ds_read_b128 v[184:187], v150
	ds_read_b128 v[188:191], v150 offset:1024
	buffer_load_dwordx4 v142, s[0:3], s10 offen lds
	s_add_i32 s59, s59, 0x7e000
	s_mov_b32 m0, s35
	s_nop 0
	buffer_load_dwordx4 v142, s[0:3], s59 offen lds
	s_waitcnt vmcnt(10)
	s_barrier
	s_waitcnt lgkmcnt(0)
	v_mfma_f32_16x16x32_bf16 v[124:127], v[130:133], v[158:161], v[124:127]
	v_mfma_f32_16x16x32_bf16 v[120:123], v[138:141], v[158:161], v[120:123]
	v_mfma_f32_16x16x32_bf16 v[112:115], v[138:141], v[166:169], v[112:115]
	v_mfma_f32_16x16x32_bf16 v[116:119], v[130:133], v[166:169], v[116:119]
	v_mfma_f32_16x16x32_bf16 v[100:103], v[130:133], v[184:187], v[100:103]
	v_mfma_f32_16x16x32_bf16 v[96:99], v[138:141], v[184:187], v[96:99]
	v_mfma_f32_16x16x32_bf16 v[124:127], v[134:137], v[162:165], v[124:127]
	v_mfma_f32_16x16x32_bf16 v[120:123], v[154:157], v[162:165], v[120:123]
	v_mfma_f32_16x16x32_bf16 v[112:115], v[154:157], v[170:173], v[112:115]
	v_mfma_f32_16x16x32_bf16 v[116:119], v[134:137], v[170:173], v[116:119]
	v_mfma_f32_16x16x32_bf16 v[108:111], v[130:133], v[176:179], v[108:111]
	v_mfma_f32_16x16x32_bf16 v[104:107], v[138:141], v[176:179], v[104:107]
	v_mfma_f32_16x16x32_bf16 v[100:103], v[134:137], v[188:191], v[100:103]
	v_mfma_f32_16x16x32_bf16 v[96:99], v[154:157], v[188:191], v[96:99]
	v_mfma_f32_16x16x32_bf16 v[192:195], v[134:137], v[180:183], v[108:111]
	v_mfma_f32_16x16x32_bf16 v[196:199], v[154:157], v[180:183], v[104:107]
	s_barrier
	s_nop 0
	ds_read_b128 v[104:107], v151
	ds_read_b128 v[108:111], v151 offset:1024
	ds_read_b128 v[200:203], v151 offset:2048
	ds_read_b128 v[204:207], v151 offset:3072
	s_waitcnt vmcnt(8)
	s_barrier
	s_waitcnt lgkmcnt(0)
	v_mfma_f32_16x16x32_bf16 v[84:87], v[104:107], v[166:169], v[84:87]
	v_mfma_f32_16x16x32_bf16 v[80:83], v[200:203], v[166:169], v[80:83]
	v_mfma_f32_16x16x32_bf16 v[64:67], v[200:203], v[184:187], v[64:67]
	v_mfma_f32_16x16x32_bf16 v[68:71], v[104:107], v[184:187], v[68:71]
	v_mfma_f32_16x16x32_bf16 v[92:95], v[104:107], v[158:161], v[92:95]
	v_mfma_f32_16x16x32_bf16 v[88:91], v[200:203], v[158:161], v[88:91]
	v_mfma_f32_16x16x32_bf16 v[84:87], v[108:111], v[170:173], v[84:87]
	v_mfma_f32_16x16x32_bf16 v[80:83], v[204:207], v[170:173], v[80:83]
	v_mfma_f32_16x16x32_bf16 v[76:79], v[104:107], v[176:179], v[76:79]
	v_mfma_f32_16x16x32_bf16 v[72:75], v[200:203], v[176:179], v[72:75]
	v_mfma_f32_16x16x32_bf16 v[68:71], v[108:111], v[188:191], v[68:71]
	v_mfma_f32_16x16x32_bf16 v[64:67], v[204:207], v[188:191], v[64:67]
	v_mfma_f32_16x16x32_bf16 v[208:211], v[108:111], v[162:165], v[92:95]
	v_mfma_f32_16x16x32_bf16 v[158:161], v[204:207], v[162:165], v[88:91]
	v_mfma_f32_16x16x32_bf16 v[162:165], v[108:111], v[180:183], v[76:79]
	v_mfma_f32_16x16x32_bf16 v[166:169], v[204:207], v[180:183], v[72:75]
	s_barrier
; #define LDA(dst, b, h)                                                                                               \
;   _Pragma("unroll") for (int m = 0; m < 4; ++m) _Pragma("unroll") for (int k = 0; k < 2; ++k) dst[m][k] =            \
;       *reinterpret_cast<const bf16x8*>(SA(b, h) + lds_byte(wr * 64 + m * 16 + fr, k * 32 + fq * 8))
; #define LDB(dst, b, h)                                                                                               \
;   _Pragma("unroll") for (int n = 0; n < 2; ++n) _Pragma("unroll") for (int k = 0; k < 2; ++k) dst[n][k] =            \
;       *reinterpret_cast<const bf16x8*>(SB(b, h) + lds_byte(wc * 32 + n * 16 + fr, k * 32 + fq * 8))
; #define WAIT_V(n) asm volatile("s_waitcnt vmcnt(" #n ")" ::: "memory")
; #define WAIT_L(n) asm volatile("s_waitcnt lgkmcnt(" #n ")" ::: "memory")
; #define BAR __builtin_amdgcn_s_barrier()
; template <int EPI>
; __device__ __forceinline__ void gemm_phase(const u16* __restrict__ A, const u16* __restrict__ Bt, const int K,
;                                            const int nN, char* shm, const EpiArgs& ea) {
;     ...
;       LDB(B1, 0, 1); WAIT_V(8); BAR; WAIT_L(0); MMA(0, 1, At, B1); BAR;
;       LDA(At, 0, 1); WAIT_V(4); BAR; WAIT_L(0); MMA(1, 0, At, B0); MMA(1, 1, At, B1); BAR;
;     }
;     {
;       LDB(B0, 1, 0); LDA(At, 1, 0); WAIT_V(2); BAR; WAIT_L(0); MMA(0, 0, At, B0); BAR;
	s_nop 0
	ds_read_b128 v[72:75], v147 offset:16384
	ds_read_b128 v[76:79], v147 offset:17408
	ds_read_b128 v[88:91], v148 offset:16384
	ds_read_b128 v[92:95], v148 offset:17408
	ds_read_b128 v[170:173], v149 offset:16384
	ds_read_b128 v[176:179], v149 offset:17408
	ds_read_b128 v[180:183], v150 offset:16384
	ds_read_b128 v[184:187], v150 offset:17408
	s_waitcnt vmcnt(4)
	s_barrier
	s_waitcnt lgkmcnt(0)
	v_mfma_f32_16x16x32_bf16 v[60:63], v[130:133], v[72:75], v[60:63]
	v_mfma_f32_16x16x32_bf16 v[52:55], v[130:133], v[88:91], v[52:55]
	v_mfma_f32_16x16x32_bf16 v[48:51], v[138:141], v[88:91], v[48:51]
	v_mfma_f32_16x16x32_bf16 v[32:35], v[138:141], v[180:183], v[32:35]
	v_mfma_f32_16x16x32_bf16 v[36:39], v[130:133], v[180:183], v[36:39]
	v_mfma_f32_16x16x32_bf16 v[60:63], v[134:137], v[76:79], v[60:63]
	v_mfma_f32_16x16x32_bf16 v[56:59], v[138:141], v[72:75], v[56:59]
	v_mfma_f32_16x16x32_bf16 v[52:55], v[134:137], v[92:95], v[52:55]
	v_mfma_f32_16x16x32_bf16 v[48:51], v[154:157], v[92:95], v[48:51]
	v_mfma_f32_16x16x32_bf16 v[44:47], v[130:133], v[170:173], v[44:47]
	v_mfma_f32_16x16x32_bf16 v[40:43], v[138:141], v[170:173], v[40:43]
	v_mfma_f32_16x16x32_bf16 v[36:39], v[134:137], v[184:187], v[36:39]
	v_mfma_f32_16x16x32_bf16 v[32:35], v[154:157], v[184:187], v[32:35]
	v_mfma_f32_16x16x32_bf16 v[188:191], v[154:157], v[76:79], v[56:59]
	v_mfma_f32_16x16x32_bf16 v[212:215], v[134:137], v[176:179], v[44:47]
	v_mfma_f32_16x16x32_bf16 v[216:219], v[154:157], v[176:179], v[40:43]
	v_mfma_f32_16x16x32_bf16 v[20:23], v[104:107], v[88:91], v[20:23]
	v_mfma_f32_16x16x32_bf16 v[16:19], v[200:203], v[88:91], v[16:19]
	v_mfma_f32_16x16x32_bf16 v[0:3], v[200:203], v[180:183], v[0:3]
	v_mfma_f32_16x16x32_bf16 v[4:7], v[104:107], v[180:183], v[4:7]
	v_mfma_f32_16x16x32_bf16 v[28:31], v[104:107], v[72:75], v[28:31]
	v_mfma_f32_16x16x32_bf16 v[24:27], v[200:203], v[72:75], v[24:27]
	v_mfma_f32_16x16x32_bf16 v[20:23], v[108:111], v[92:95], v[20:23]
	v_mfma_f32_16x16x32_bf16 v[16:19], v[204:207], v[92:95], v[16:19]
	v_mfma_f32_16x16x32_bf16 v[12:15], v[104:107], v[170:173], v[12:15]
	v_mfma_f32_16x16x32_bf16 v[8:11], v[200:203], v[170:173], v[8:11]
	v_mfma_f32_16x16x32_bf16 v[4:7], v[108:111], v[184:187], v[4:7]
	v_mfma_f32_16x16x32_bf16 v[0:3], v[204:207], v[184:187], v[0:3]
	v_mfma_f32_16x16x32_bf16 v[130:133], v[108:111], v[76:79], v[28:31]
	v_mfma_f32_16x16x32_bf16 v[134:137], v[204:207], v[76:79], v[24:27]
	v_mfma_f32_16x16x32_bf16 v[138:141], v[108:111], v[176:179], v[12:15]
	v_mfma_f32_16x16x32_bf16 v[154:157], v[204:207], v[176:179], v[8:11]
	s_barrier
	s_nop 0
	ds_read_b128 v[8:11], v152
	ds_read_b128 v[12:15], v152 offset:1024
	ds_read_b128 v[170:173], v152 offset:2048
	ds_read_b128 v[176:179], v152 offset:3072
	ds_read_b128 v[24:27], v147 offset:32768
	ds_read_b128 v[28:31], v147 offset:33792
	ds_read_b128 v[40:43], v148 offset:32768
	ds_read_b128 v[44:47], v148 offset:33792
	ds_read_b128 v[56:59], v149 offset:32768
	ds_read_b128 v[180:183], v149 offset:33792
	ds_read_b128 v[184:187], v150 offset:32768
	ds_read_b128 v[200:203], v150 offset:33792
	s_waitcnt vmcnt(2)
	s_barrier
	s_waitcnt lgkmcnt(0)
	v_mfma_f32_16x16x32_bf16 v[72:75], v[8:11], v[24:27], v[124:127]
	v_mfma_f32_16x16x32_bf16 v[124:127], v[12:15], v[28:31], v[72:75]
	v_mfma_f32_16x16x32_bf16 v[72:75], v[170:173], v[24:27], v[120:123]
	v_mfma_f32_16x16x32_bf16 v[120:123], v[176:179], v[28:31], v[72:75]
	v_mfma_f32_16x16x32_bf16 v[72:75], v[8:11], v[40:43], v[116:119]
	v_mfma_f32_16x16x32_bf16 v[104:107], v[12:15], v[44:47], v[72:75]
	v_mfma_f32_16x16x32_bf16 v[72:75], v[170:173], v[40:43], v[112:115]
	v_mfma_f32_16x16x32_bf16 v[108:111], v[176:179], v[44:47], v[72:75]
	v_mfma_f32_16x16x32_bf16 v[72:75], v[8:11], v[56:59], v[192:195]
	v_mfma_f32_16x16x32_bf16 v[88:91], v[12:15], v[180:183], v[72:75]
	v_mfma_f32_16x16x32_bf16 v[72:75], v[170:173], v[56:59], v[196:199]
	v_mfma_f32_16x16x32_bf16 v[92:95], v[176:179], v[180:183], v[72:75]
	v_mfma_f32_16x16x32_bf16 v[72:75], v[8:11], v[184:187], v[100:103]
	v_mfma_f32_16x16x32_bf16 v[76:79], v[170:173], v[184:187], v[96:99]
	v_mfma_f32_16x16x32_bf16 v[72:75], v[12:15], v[200:203], v[72:75]
	v_mfma_f32_16x16x32_bf16 v[76:79], v[176:179], v[200:203], v[76:79]
	s_barrier
; #define LDA(dst, b, h)                                                                                               \
;   _Pragma("unroll") for (int m = 0; m < 4; ++m) _Pragma("unroll") for (int k = 0; k < 2; ++k) dst[m][k] =            \
;       *reinterpret_cast<const bf16x8*>(SA(b, h) + lds_byte(wr * 64 + m * 16 + fr, k * 32 + fq * 8))
; #define LDB(dst, b, h)                                                                                               \
;   _Pragma("unroll") for (int n = 0; n < 2; ++n) _Pragma("unroll") for (int k = 0; k < 2; ++k) dst[n][k] =            \
;       *reinterpret_cast<const bf16x8*>(SB(b, h) + lds_byte(wc * 32 + n * 16 + fr, k * 32 + fq * 8))
; #define WAIT_V(n) asm volatile("s_waitcnt vmcnt(" #n ")" ::: "memory")
; #define WAIT_L(n) asm volatile("s_waitcnt lgkmcnt(" #n ")" ::: "memory")
; #define BAR __builtin_amdgcn_s_barrier()
; template <int EPI>
; __device__ __forceinline__ void gemm_phase(const u16* __restrict__ A, const u16* __restrict__ Bt, const int K,
;                                            const int nN, char* shm, const EpiArgs& ea) {
;     ...
;       LDB(B0, 1, 0); LDA(At, 1, 0); WAIT_V(2); BAR; WAIT_L(0); MMA(0, 0, At, B0); BAR;
;       LDB(B1, 1, 1); WAIT_V(0); BAR; WAIT_L(0); MMA(0, 1, At, B1); BAR;
;       LDA(At, 1, 1); BAR; WAIT_L(0); MMA(1, 0, At, B0); MMA(1, 1, At, B1); BAR;
;     }
;     if (wr == 0) BAR;
;     if (has_next) STAGE7(brow2, bcol2);
	ds_read_b128 v[192:195], v153
	ds_read_b128 v[196:199], v153 offset:1024
	ds_read_b128 v[204:207], v153 offset:2048
	ds_read_b128 v[220:223], v153 offset:3072
	s_waitcnt vmcnt(0)
	s_barrier
	s_waitcnt lgkmcnt(0)
	v_mfma_f32_16x16x32_bf16 v[96:99], v[192:195], v[24:27], v[208:211]
	v_mfma_f32_16x16x32_bf16 v[24:27], v[204:207], v[24:27], v[158:161]
	v_mfma_f32_16x16x32_bf16 v[112:115], v[220:223], v[28:31], v[24:27]
	v_mfma_f32_16x16x32_bf16 v[24:27], v[192:195], v[40:43], v[84:87]
	v_mfma_f32_16x16x32_bf16 v[100:103], v[196:199], v[44:47], v[24:27]
	v_mfma_f32_16x16x32_bf16 v[24:27], v[204:207], v[40:43], v[80:83]
	v_mfma_f32_16x16x32_bf16 v[116:119], v[196:199], v[28:31], v[96:99]
	v_mfma_f32_16x16x32_bf16 v[96:99], v[220:223], v[44:47], v[24:27]
	v_mfma_f32_16x16x32_bf16 v[24:27], v[192:195], v[56:59], v[162:165]
	v_mfma_f32_16x16x32_bf16 v[84:87], v[196:199], v[180:183], v[24:27]
	v_mfma_f32_16x16x32_bf16 v[24:27], v[204:207], v[56:59], v[166:169]
	v_mfma_f32_16x16x32_bf16 v[80:83], v[220:223], v[180:183], v[24:27]
	v_mfma_f32_16x16x32_bf16 v[24:27], v[192:195], v[184:187], v[68:71]
	v_mfma_f32_16x16x32_bf16 v[68:71], v[196:199], v[200:203], v[24:27]
	v_mfma_f32_16x16x32_bf16 v[24:27], v[204:207], v[184:187], v[64:67]
	v_mfma_f32_16x16x32_bf16 v[64:67], v[220:223], v[200:203], v[24:27]
	s_barrier
	ds_read_b128 v[158:161], v147 offset:49152
	ds_read_b128 v[162:165], v147 offset:50176
	ds_read_b128 v[166:169], v148 offset:49152
	ds_read_b128 v[180:183], v148 offset:50176
	ds_read_b128 v[184:187], v149 offset:49152
	ds_read_b128 v[200:203], v149 offset:50176
	ds_read_b128 v[208:211], v150 offset:49152
	ds_read_b128 v[224:227], v150 offset:50176
	s_barrier
	s_waitcnt lgkmcnt(0)
	v_mfma_f32_16x16x32_bf16 v[24:27], v[8:11], v[158:161], v[60:63]
	v_mfma_f32_16x16x32_bf16 v[56:59], v[12:15], v[162:165], v[24:27]
	v_mfma_f32_16x16x32_bf16 v[24:27], v[170:173], v[158:161], v[188:191]
	v_mfma_f32_16x16x32_bf16 v[60:63], v[176:179], v[162:165], v[24:27]
	v_mfma_f32_16x16x32_bf16 v[24:27], v[8:11], v[166:169], v[52:55]
	v_mfma_f32_16x16x32_bf16 v[40:43], v[12:15], v[180:183], v[24:27]
	v_mfma_f32_16x16x32_bf16 v[24:27], v[170:173], v[166:169], v[48:51]
	v_mfma_f32_16x16x32_bf16 v[44:47], v[176:179], v[180:183], v[24:27]
	v_mfma_f32_16x16x32_bf16 v[24:27], v[8:11], v[184:187], v[212:215]
	v_mfma_f32_16x16x32_bf16 v[8:11], v[8:11], v[208:211], v[36:39]
	v_mfma_f32_16x16x32_bf16 v[24:27], v[12:15], v[200:203], v[24:27]
	v_mfma_f32_16x16x32_bf16 v[28:31], v[170:173], v[184:187], v[216:219]
	v_mfma_f32_16x16x32_bf16 v[8:11], v[12:15], v[224:227], v[8:11]
	v_mfma_f32_16x16x32_bf16 v[12:15], v[170:173], v[208:211], v[32:35]
	v_mfma_f32_16x16x32_bf16 v[28:31], v[176:179], v[200:203], v[28:31]
	v_mfma_f32_16x16x32_bf16 v[12:15], v[176:179], v[224:227], v[12:15]
	v_mfma_f32_16x16x32_bf16 v[32:35], v[192:195], v[158:161], v[130:133]
	v_mfma_f32_16x16x32_bf16 v[52:55], v[196:199], v[162:165], v[32:35]
	v_mfma_f32_16x16x32_bf16 v[32:35], v[204:207], v[158:161], v[134:137]
	v_mfma_f32_16x16x32_bf16 v[16:19], v[204:207], v[166:169], v[16:19]
	v_mfma_f32_16x16x32_bf16 v[48:51], v[220:223], v[162:165], v[32:35]
	v_mfma_f32_16x16x32_bf16 v[20:23], v[192:195], v[166:169], v[20:23]
	v_mfma_f32_16x16x32_bf16 v[32:35], v[220:223], v[180:183], v[16:19]
	v_mfma_f32_16x16x32_bf16 v[16:19], v[192:195], v[184:187], v[138:141]
	v_mfma_f32_16x16x32_bf16 v[36:39], v[196:199], v[180:183], v[20:23]
	v_mfma_f32_16x16x32_bf16 v[20:23], v[196:199], v[200:203], v[16:19]
	v_mfma_f32_16x16x32_bf16 v[16:19], v[204:207], v[184:187], v[154:157]
	v_mfma_f32_16x16x32_bf16 v[4:7], v[192:195], v[208:211], v[4:7]
	v_mfma_f32_16x16x32_bf16 v[0:3], v[204:207], v[208:211], v[0:3]
	v_mfma_f32_16x16x32_bf16 v[16:19], v[220:223], v[200:203], v[16:19]
	v_mfma_f32_16x16x32_bf16 v[4:7], v[196:199], v[224:227], v[4:7]
	v_mfma_f32_16x16x32_bf16 v[0:3], v[220:223], v[224:227], v[0:3]
	s_andn2_b64 vcc, exec, s[18:19]
	s_barrier
	s_cbranch_vccnz .LBB0_495
	s_barrier

; #define LDA(dst, b, h)                                                                                               \
;   _Pragma("unroll") for (int m = 0; m < 4; ++m) _Pragma("unroll") for (int k = 0; k < 2; ++k) dst[m][k] =            \
;       *reinterpret_cast<const bf16x8*>(SA(b, h) + lds_byte(wr * 64 + m * 16 + fr, k * 32 + fq * 8))
; #define LDB(dst, b, h)                                                                                               \
;   _Pragma("unroll") for (int n = 0; n < 2; ++n) _Pragma("unroll") for (int k = 0; k < 2; ++k) dst[n][k] =            \
;       *reinterpret_cast<const bf16x8*>(SB(b, h) + lds_byte(wc * 32 + n * 16 + fr, k * 32 + fq * 8))
; #define WAIT_V(n) asm volatile("s_waitcnt vmcnt(" #n ")" ::: "memory")
; #define WAIT_L(n) asm volatile("s_waitcnt lgkmcnt(" #n ")" ::: "memory")
; #define BAR __builtin_amdgcn_s_barrier()
; #define SCHED __builtin_amdgcn_sched_barrier(0)
; template <int EPI>
; __device__ __forceinline__ void gemm_phase(const u16* __restrict__ A, const u16* __restrict__ Bt, const int K,
;                                            const int nN, char* shm, const EpiArgs& ea) {
;     ...
;       LDB(B0, 0, 0); SCHED; LDA(At, 0, 0); STAGE(SA(1, 1), rA, brow + HALF, t + 1);
;       WAIT_V(10); WAIT_L(8); BAR; WAIT_L(0); MMA(0, 0, At, B0); BAR; SCHED;
;       LDB(B1, 0, 1); STAGE(SB(0, 0), rB, bcol, t + 2);
;       WAIT_V(10); BAR; WAIT_L(0); MMA(0, 1, At, B1); BAR;
;       LDA(At, 0, 1); STAGE(SA(0, 0), rA, brow, t + 2);
;       BAR; WAIT_L(0); MMA(1, 0, At, B0); BAR; SCHED;
;       STAGE(SB(0, 1), rB, bcol + HALF, t + 2);
;       WAIT_V(10); BAR; MMA(1, 1, At, B1); BAR;
.LBB0_565:
	ds_read_b128 v[128:131], v183
	ds_read_b128 v[132:135], v183 offset:1024
	ds_read_b128 v[136:139], v183 offset:2048
	ds_read_b128 v[140:143], v183 offset:3072
	s_add_i32 s64, s58, s63
	s_mov_b32 m0, s46
	s_add_i32 s6, s64, 0x4000
	ds_read_b128 v[144:147], v184
	ds_read_b128 v[148:151], v184 offset:1024
	ds_read_b128 v[152:155], v185
	ds_read_b128 v[156:159], v185 offset:1024
	ds_read_b128 v[160:163], v186
	ds_read_b128 v[164:167], v186 offset:1024
	ds_read_b128 v[168:171], v187
	ds_read_b128 v[192:195], v187 offset:1024
	buffer_load_dwordx4 v175, s[0:3], s6 offen lds
	s_add_i32 s6, s64, 0x6000
	s_mov_b32 m0, s47
	s_nop 0
	buffer_load_dwordx4 v175, s[0:3], s6 offen lds
	s_waitcnt vmcnt(10)
	s_waitcnt lgkmcnt(8)
	s_barrier
	s_waitcnt lgkmcnt(0)
	v_mfma_f32_16x16x32_bf16 v[124:127], v[128:131], v[144:147], v[124:127]
	v_mfma_f32_16x16x32_bf16 v[120:123], v[136:139], v[144:147], v[120:123]
	v_mfma_f32_16x16x32_bf16 v[112:115], v[136:139], v[152:155], v[112:115]
	v_mfma_f32_16x16x32_bf16 v[116:119], v[128:131], v[152:155], v[116:119]
	v_mfma_f32_16x16x32_bf16 v[108:111], v[128:131], v[160:163], v[108:111]
	v_mfma_f32_16x16x32_bf16 v[104:107], v[136:139], v[160:163], v[104:107]
	v_mfma_f32_16x16x32_bf16 v[96:99], v[136:139], v[168:171], v[96:99]
	v_mfma_f32_16x16x32_bf16 v[100:103], v[128:131], v[168:171], v[100:103]
	v_mfma_f32_16x16x32_bf16 v[124:127], v[132:135], v[148:151], v[124:127]
	v_mfma_f32_16x16x32_bf16 v[120:123], v[140:143], v[148:151], v[120:123]
	v_mfma_f32_16x16x32_bf16 v[112:115], v[140:143], v[156:159], v[112:115]
	v_mfma_f32_16x16x32_bf16 v[116:119], v[132:135], v[156:159], v[116:119]
	v_mfma_f32_16x16x32_bf16 v[108:111], v[132:135], v[164:167], v[108:111]
	v_mfma_f32_16x16x32_bf16 v[104:107], v[140:143], v[164:167], v[104:107]
	v_mfma_f32_16x16x32_bf16 v[96:99], v[140:143], v[192:195], v[96:99]
	v_mfma_f32_16x16x32_bf16 v[100:103], v[132:135], v[192:195], v[100:103]
	s_barrier
	s_add_i32 s65, s61, s63
	s_mov_b32 m0, s30
	s_add_i32 s66, s65, 0x8000
	s_mov_b32 s6, s2
	s_mov_b32 s7, s3
	ds_read_b128 v[196:199], v188
	ds_read_b128 v[200:203], v188 offset:1024
	ds_read_b128 v[204:207], v188 offset:2048
	ds_read_b128 v[208:211], v188 offset:3072
	buffer_load_dwordx4 v175, s[4:7], s66 offen lds
	s_add_i32 s66, s65, 0xa000
	s_mov_b32 m0, s31
	s_nop 0
	buffer_load_dwordx4 v175, s[4:7], s66 offen lds
	s_waitcnt vmcnt(10)
	s_barrier
	s_waitcnt lgkmcnt(0)
	v_mfma_f32_16x16x32_bf16 v[92:95], v[196:199], v[144:147], v[92:95]
	v_mfma_f32_16x16x32_bf16 v[88:91], v[204:207], v[144:147], v[88:91]
	v_mfma_f32_16x16x32_bf16 v[80:83], v[204:207], v[152:155], v[80:83]
	v_mfma_f32_16x16x32_bf16 v[84:87], v[196:199], v[152:155], v[84:87]
	v_mfma_f32_16x16x32_bf16 v[76:79], v[196:199], v[160:163], v[76:79]
	v_mfma_f32_16x16x32_bf16 v[72:75], v[204:207], v[160:163], v[72:75]
	v_mfma_f32_16x16x32_bf16 v[64:67], v[204:207], v[168:171], v[64:67]
	v_mfma_f32_16x16x32_bf16 v[68:71], v[196:199], v[168:171], v[68:71]
	v_mfma_f32_16x16x32_bf16 v[92:95], v[200:203], v[148:151], v[92:95]
	v_mfma_f32_16x16x32_bf16 v[88:91], v[208:211], v[148:151], v[88:91]
	v_mfma_f32_16x16x32_bf16 v[80:83], v[208:211], v[156:159], v[80:83]
	v_mfma_f32_16x16x32_bf16 v[84:87], v[200:203], v[156:159], v[84:87]
	v_mfma_f32_16x16x32_bf16 v[76:79], v[200:203], v[164:167], v[76:79]
	v_mfma_f32_16x16x32_bf16 v[72:75], v[208:211], v[164:167], v[72:75]
	v_mfma_f32_16x16x32_bf16 v[64:67], v[208:211], v[192:195], v[64:67]
	v_mfma_f32_16x16x32_bf16 v[68:71], v[200:203], v[192:195], v[68:71]
	s_add_i32 s66, s60, s63
	s_mov_b32 m0, s33
	s_add_i32 s67, s66, 0x8000
	s_barrier
	ds_read_b128 v[144:147], v184 offset:16384
	ds_read_b128 v[148:151], v184 offset:17408
	ds_read_b128 v[152:155], v185 offset:16384
	ds_read_b128 v[156:159], v185 offset:17408
	ds_read_b128 v[160:163], v186 offset:16384
	ds_read_b128 v[164:167], v186 offset:17408
	ds_read_b128 v[168:171], v187 offset:16384
	ds_read_b128 v[192:195], v187 offset:17408
	buffer_load_dwordx4 v175, s[0:3], s67 offen lds
	s_add_i32 s67, s66, 0xa000
	s_mov_b32 m0, s34
	s_nop 0
	buffer_load_dwordx4 v175, s[0:3], s67 offen lds
	s_barrier
	s_waitcnt lgkmcnt(0)
	v_mfma_f32_16x16x32_bf16 v[60:63], v[128:131], v[144:147], v[60:63]
	v_mfma_f32_16x16x32_bf16 v[56:59], v[136:139], v[144:147], v[56:59]
	v_mfma_f32_16x16x32_bf16 v[48:51], v[136:139], v[152:155], v[48:51]
	v_mfma_f32_16x16x32_bf16 v[52:55], v[128:131], v[152:155], v[52:55]
	v_mfma_f32_16x16x32_bf16 v[44:47], v[128:131], v[160:163], v[44:47]
	v_mfma_f32_16x16x32_bf16 v[40:43], v[136:139], v[160:163], v[40:43]
	v_mfma_f32_16x16x32_bf16 v[32:35], v[136:139], v[168:171], v[32:35]
	v_mfma_f32_16x16x32_bf16 v[36:39], v[128:131], v[168:171], v[36:39]
	v_mfma_f32_16x16x32_bf16 v[60:63], v[132:135], v[148:151], v[60:63]
	v_mfma_f32_16x16x32_bf16 v[56:59], v[140:143], v[148:151], v[56:59]
	v_mfma_f32_16x16x32_bf16 v[48:51], v[140:143], v[156:159], v[48:51]
	v_mfma_f32_16x16x32_bf16 v[52:55], v[132:135], v[156:159], v[52:55]
	v_mfma_f32_16x16x32_bf16 v[44:47], v[132:135], v[164:167], v[44:47]
	v_mfma_f32_16x16x32_bf16 v[40:43], v[140:143], v[164:167], v[40:43]
	v_mfma_f32_16x16x32_bf16 v[32:35], v[140:143], v[192:195], v[32:35]
	v_mfma_f32_16x16x32_bf16 v[36:39], v[132:135], v[192:195], v[36:39]
	s_barrier
	s_add_i32 s67, s59, s63
	s_mov_b32 m0, s35
	s_add_i32 s68, s67, 0x8000
	buffer_load_dwordx4 v175, s[4:7], s68 offen lds
	s_add_i32 s68, s67, 0xa000
	s_mov_b32 m0, s36
	s_nop 0
	buffer_load_dwordx4 v175, s[4:7], s68 offen lds
	s_waitcnt vmcnt(10)
	s_barrier
; #define LDA(dst, b, h)                                                                                               \
;   _Pragma("unroll") for (int m = 0; m < 4; ++m) _Pragma("unroll") for (int k = 0; k < 2; ++k) dst[m][k] =            \
;       *reinterpret_cast<const bf16x8*>(SA(b, h) + lds_byte(wr * 64 + m * 16 + fr, k * 32 + fq * 8))
; #define LDB(dst, b, h)                                                                                               \
;   _Pragma("unroll") for (int n = 0; n < 2; ++n) _Pragma("unroll") for (int k = 0; k < 2; ++k) dst[n][k] =            \
;       *reinterpret_cast<const bf16x8*>(SB(b, h) + lds_byte(wc * 32 + n * 16 + fr, k * 32 + fq * 8))
; #define WAIT_V(n) asm volatile("s_waitcnt vmcnt(" #n ")" ::: "memory")
; #define WAIT_L(n) asm volatile("s_waitcnt lgkmcnt(" #n ")" ::: "memory")
; #define BAR __builtin_amdgcn_s_barrier()
; #define SCHED __builtin_amdgcn_sched_barrier(0)
; template <int EPI>
; __device__ __forceinline__ void gemm_phase(const u16* __restrict__ A, const u16* __restrict__ Bt, const int K,
;                                            const int nN, char* shm, const EpiArgs& ea) {
;     ...
;       WAIT_V(10); BAR; MMA(1, 1, At, B1); BAR;
;       LDB(B0, 1, 0); SCHED; LDA(At, 1, 0); STAGE(SA(0, 1), rA, brow + HALF, t + 2);
;       WAIT_V(10); WAIT_L(8); BAR; WAIT_L(0); MMA(0, 0, At, B0); BAR; SCHED;
;       LDB(B1, 1, 1); STAGE(SB(1, 0), rB, bcol, t + 3);
;       WAIT_V(10); BAR; WAIT_L(0); MMA(0, 1, At, B1); BAR;
	v_mfma_f32_16x16x32_bf16 v[28:31], v[196:199], v[144:147], v[28:31]
	v_mfma_f32_16x16x32_bf16 v[24:27], v[204:207], v[144:147], v[24:27]
	v_mfma_f32_16x16x32_bf16 v[16:19], v[204:207], v[152:155], v[16:19]
	v_mfma_f32_16x16x32_bf16 v[20:23], v[196:199], v[152:155], v[20:23]
	v_mfma_f32_16x16x32_bf16 v[12:15], v[196:199], v[160:163], v[12:15]
	v_mfma_f32_16x16x32_bf16 v[8:11], v[204:207], v[160:163], v[8:11]
	v_mfma_f32_16x16x32_bf16 v[0:3], v[204:207], v[168:171], v[0:3]
	v_mfma_f32_16x16x32_bf16 v[4:7], v[196:199], v[168:171], v[4:7]
	v_mfma_f32_16x16x32_bf16 v[28:31], v[200:203], v[148:151], v[28:31]
	v_mfma_f32_16x16x32_bf16 v[24:27], v[208:211], v[148:151], v[24:27]
	v_mfma_f32_16x16x32_bf16 v[16:19], v[208:211], v[156:159], v[16:19]
	v_mfma_f32_16x16x32_bf16 v[20:23], v[200:203], v[156:159], v[20:23]
	v_mfma_f32_16x16x32_bf16 v[12:15], v[200:203], v[164:167], v[12:15]
	v_mfma_f32_16x16x32_bf16 v[8:11], v[208:211], v[164:167], v[8:11]
	v_mfma_f32_16x16x32_bf16 v[0:3], v[208:211], v[192:195], v[0:3]
	v_mfma_f32_16x16x32_bf16 v[4:7], v[200:203], v[192:195], v[4:7]
	s_barrier
	ds_read_b128 v[128:131], v189
	ds_read_b128 v[132:135], v189 offset:1024
	ds_read_b128 v[136:139], v189 offset:2048
	ds_read_b128 v[140:143], v189 offset:3072
	s_mov_b32 m0, s37
	s_add_i32 s68, s64, 0x8000
	ds_read_b128 v[144:147], v184 offset:32768
	ds_read_b128 v[148:151], v184 offset:33792
	ds_read_b128 v[152:155], v185 offset:32768
	ds_read_b128 v[156:159], v185 offset:33792
	ds_read_b128 v[160:163], v186 offset:32768
	ds_read_b128 v[164:167], v186 offset:33792
	ds_read_b128 v[168:171], v187 offset:32768
	ds_read_b128 v[192:195], v187 offset:33792
	buffer_load_dwordx4 v175, s[0:3], s68 offen lds
	s_add_i32 s64, s64, 0xa000
	s_mov_b32 m0, s38
	s_nop 0
	buffer_load_dwordx4 v175, s[0:3], s64 offen lds
	s_waitcnt vmcnt(10)
	s_waitcnt lgkmcnt(8)
	s_barrier
	s_waitcnt lgkmcnt(0)
	v_mfma_f32_16x16x32_bf16 v[124:127], v[128:131], v[144:147], v[124:127]
	v_mfma_f32_16x16x32_bf16 v[120:123], v[136:139], v[144:147], v[120:123]
	v_mfma_f32_16x16x32_bf16 v[112:115], v[136:139], v[152:155], v[112:115]
	v_mfma_f32_16x16x32_bf16 v[116:119], v[128:131], v[152:155], v[116:119]
	v_mfma_f32_16x16x32_bf16 v[108:111], v[128:131], v[160:163], v[108:111]
	v_mfma_f32_16x16x32_bf16 v[104:107], v[136:139], v[160:163], v[104:107]
	v_mfma_f32_16x16x32_bf16 v[96:99], v[136:139], v[168:171], v[96:99]
	v_mfma_f32_16x16x32_bf16 v[100:103], v[128:131], v[168:171], v[100:103]
	v_mfma_f32_16x16x32_bf16 v[124:127], v[132:135], v[148:151], v[124:127]
	v_mfma_f32_16x16x32_bf16 v[120:123], v[140:143], v[148:151], v[120:123]
	v_mfma_f32_16x16x32_bf16 v[112:115], v[140:143], v[156:159], v[112:115]
	v_mfma_f32_16x16x32_bf16 v[116:119], v[132:135], v[156:159], v[116:119]
	v_mfma_f32_16x16x32_bf16 v[108:111], v[132:135], v[164:167], v[108:111]
	v_mfma_f32_16x16x32_bf16 v[104:107], v[140:143], v[164:167], v[104:107]
	v_mfma_f32_16x16x32_bf16 v[96:99], v[140:143], v[192:195], v[96:99]
	v_mfma_f32_16x16x32_bf16 v[100:103], v[132:135], v[192:195], v[100:103]
	s_barrier
	s_mov_b32 m0, s39
	s_add_i32 s64, s65, 0xc000
	ds_read_b128 v[196:199], v190
	ds_read_b128 v[200:203], v190 offset:1024
	ds_read_b128 v[204:207], v190 offset:2048
	ds_read_b128 v[208:211], v190 offset:3072
	buffer_load_dwordx4 v175, s[4:7], s64 offen lds
	s_add_i32 s65, s65, 0xe000
	s_mov_b32 m0, s40
	s_nop 0
	buffer_load_dwordx4 v175, s[4:7], s65 offen lds
	s_waitcnt vmcnt(10)
	s_barrier
; #define LDA(dst, b, h)                                                                                               \
;   _Pragma("unroll") for (int m = 0; m < 4; ++m) _Pragma("unroll") for (int k = 0; k < 2; ++k) dst[m][k] =            \
;       *reinterpret_cast<const bf16x8*>(SA(b, h) + lds_byte(wr * 64 + m * 16 + fr, k * 32 + fq * 8))
; #define WAIT_V(n) asm volatile("s_waitcnt vmcnt(" #n ")" ::: "memory")
; #define WAIT_L(n) asm volatile("s_waitcnt lgkmcnt(" #n ")" ::: "memory")
; #define BAR __builtin_amdgcn_s_barrier()
; #define SCHED __builtin_amdgcn_sched_barrier(0)
; template <int EPI>
; __device__ __forceinline__ void gemm_phase(const u16* __restrict__ A, const u16* __restrict__ Bt, const int K,
;                                            const int nN, char* shm, const EpiArgs& ea) {
;     ...
;       WAIT_V(10); BAR; WAIT_L(0); MMA(0, 1, At, B1); BAR;
;       LDA(At, 1, 1); STAGE(SA(1, 0), rA, brow, t + 3);
;       BAR; WAIT_L(0); MMA(1, 0, At, B0); BAR; SCHED;
;       STAGE(SB(1, 1), rB, bcol + HALF, t + 3);
;       WAIT_V(10); BAR; MMA(1, 1, At, B1); BAR;
;     }
;     float eC = 0.f, eB = 0.f;
;     float2 eS = make_float2(0.f, 0.f);
;     if (EPI == EPI_IN || EPI == EPI_SWIGLU_LN) {
;       if (wr == 0) {
;         eC = ea.c1[bcol + tid];
;         eS = *(const float2*)(ea.st_in + (size_t)(brow + tid) * 2);
	s_waitcnt lgkmcnt(0)
	v_mfma_f32_16x16x32_bf16 v[92:95], v[196:199], v[144:147], v[92:95]
	v_mfma_f32_16x16x32_bf16 v[88:91], v[204:207], v[144:147], v[88:91]
	v_mfma_f32_16x16x32_bf16 v[80:83], v[204:207], v[152:155], v[80:83]
	v_mfma_f32_16x16x32_bf16 v[84:87], v[196:199], v[152:155], v[84:87]
	v_mfma_f32_16x16x32_bf16 v[76:79], v[196:199], v[160:163], v[76:79]
	v_mfma_f32_16x16x32_bf16 v[72:75], v[204:207], v[160:163], v[72:75]
	v_mfma_f32_16x16x32_bf16 v[64:67], v[204:207], v[168:171], v[64:67]
	v_mfma_f32_16x16x32_bf16 v[68:71], v[196:199], v[168:171], v[68:71]
	v_mfma_f32_16x16x32_bf16 v[92:95], v[200:203], v[148:151], v[92:95]
	v_mfma_f32_16x16x32_bf16 v[88:91], v[208:211], v[148:151], v[88:91]
	v_mfma_f32_16x16x32_bf16 v[80:83], v[208:211], v[156:159], v[80:83]
	v_mfma_f32_16x16x32_bf16 v[84:87], v[200:203], v[156:159], v[84:87]
	v_mfma_f32_16x16x32_bf16 v[76:79], v[200:203], v[164:167], v[76:79]
	v_mfma_f32_16x16x32_bf16 v[72:75], v[208:211], v[164:167], v[72:75]
	v_mfma_f32_16x16x32_bf16 v[64:67], v[208:211], v[192:195], v[64:67]
	v_mfma_f32_16x16x32_bf16 v[68:71], v[200:203], v[192:195], v[68:71]
	s_mov_b32 m0, s41
	s_add_i32 s64, s66, 0xc000
	s_barrier
	ds_read_b128 v[144:147], v184 offset:49152
	ds_read_b128 v[148:151], v184 offset:50176
	ds_read_b128 v[152:155], v185 offset:49152
	ds_read_b128 v[156:159], v185 offset:50176
	ds_read_b128 v[160:163], v186 offset:49152
	ds_read_b128 v[164:167], v186 offset:50176
	ds_read_b128 v[168:171], v187 offset:49152
	ds_read_b128 v[192:195], v187 offset:50176
	buffer_load_dwordx4 v175, s[0:3], s64 offen lds
	s_add_i32 s66, s66, 0xe000
	s_mov_b32 m0, s42
	s_nop 0
	buffer_load_dwordx4 v175, s[0:3], s66 offen lds
	s_barrier
	s_waitcnt lgkmcnt(0)
	v_mfma_f32_16x16x32_bf16 v[60:63], v[128:131], v[144:147], v[60:63]
	v_mfma_f32_16x16x32_bf16 v[56:59], v[136:139], v[144:147], v[56:59]
	v_mfma_f32_16x16x32_bf16 v[48:51], v[136:139], v[152:155], v[48:51]
	v_mfma_f32_16x16x32_bf16 v[52:55], v[128:131], v[152:155], v[52:55]
	v_mfma_f32_16x16x32_bf16 v[44:47], v[128:131], v[160:163], v[44:47]
	v_mfma_f32_16x16x32_bf16 v[40:43], v[136:139], v[160:163], v[40:43]
	v_mfma_f32_16x16x32_bf16 v[32:35], v[136:139], v[168:171], v[32:35]
	v_mfma_f32_16x16x32_bf16 v[36:39], v[128:131], v[168:171], v[36:39]
	v_mfma_f32_16x16x32_bf16 v[60:63], v[132:135], v[148:151], v[60:63]
	v_mfma_f32_16x16x32_bf16 v[56:59], v[140:143], v[148:151], v[56:59]
	v_mfma_f32_16x16x32_bf16 v[48:51], v[140:143], v[156:159], v[48:51]
	v_mfma_f32_16x16x32_bf16 v[52:55], v[132:135], v[156:159], v[52:55]
	v_mfma_f32_16x16x32_bf16 v[44:47], v[132:135], v[164:167], v[44:47]
	v_mfma_f32_16x16x32_bf16 v[40:43], v[140:143], v[164:167], v[40:43]
	v_mfma_f32_16x16x32_bf16 v[32:35], v[140:143], v[192:195], v[32:35]
	v_mfma_f32_16x16x32_bf16 v[36:39], v[132:135], v[192:195], v[36:39]
	s_barrier
	s_mov_b32 m0, s43
	s_add_i32 s64, s67, 0xc000
	buffer_load_dwordx4 v175, s[4:7], s64 offen lds
	s_add_i32 s67, s67, 0xe000
	s_mov_b32 m0, s44
	s_nop 0
	buffer_load_dwordx4 v175, s[4:7], s67 offen lds
	s_waitcnt vmcnt(10)
	s_barrier
	v_mfma_f32_16x16x32_bf16 v[28:31], v[196:199], v[144:147], v[28:31]
	v_mfma_f32_16x16x32_bf16 v[24:27], v[204:207], v[144:147], v[24:27]
	v_mfma_f32_16x16x32_bf16 v[16:19], v[204:207], v[152:155], v[16:19]
	v_mfma_f32_16x16x32_bf16 v[20:23], v[196:199], v[152:155], v[20:23]
	v_mfma_f32_16x16x32_bf16 v[12:15], v[196:199], v[160:163], v[12:15]
	v_mfma_f32_16x16x32_bf16 v[8:11], v[204:207], v[160:163], v[8:11]
	v_mfma_f32_16x16x32_bf16 v[0:3], v[204:207], v[168:171], v[0:3]
	v_mfma_f32_16x16x32_bf16 v[4:7], v[196:199], v[168:171], v[4:7]
	v_mfma_f32_16x16x32_bf16 v[28:31], v[200:203], v[148:151], v[28:31]
	v_mfma_f32_16x16x32_bf16 v[24:27], v[208:211], v[148:151], v[24:27]
	v_mfma_f32_16x16x32_bf16 v[16:19], v[208:211], v[156:159], v[16:19]
	v_mfma_f32_16x16x32_bf16 v[20:23], v[200:203], v[156:159], v[20:23]
	v_mfma_f32_16x16x32_bf16 v[12:15], v[200:203], v[164:167], v[12:15]
	v_mfma_f32_16x16x32_bf16 v[8:11], v[208:211], v[164:167], v[8:11]
	v_mfma_f32_16x16x32_bf16 v[0:3], v[208:211], v[192:195], v[0:3]
	v_mfma_f32_16x16x32_bf16 v[4:7], v[200:203], v[192:195], v[4:7]
	s_add_i32 s62, s62, 2
	s_add_i32 s63, s63, 0x8000
	s_cmp_lt_u32 s62, 28
	s_barrier
	s_cbranch_scc1 .LBB0_565
	v_add_u32_e32 v128, s57, v174
	v_ashrrev_i32_e32 v129, 31, v128
	s_mov_b64 s[6:7], -1
	s_and_b64 vcc, exec, s[18:19]
	s_cbranch_vccz .LBB0_568
	v_lshl_add_u64 v[130:131], v[128:129], 2, s[90:91]
	v_lshl_add_u64 v[130:131], v[130:131], 0, s[20:21]
	s_mov_b64 s[6:7], 0

; #define LDA(dst, b, h)                                                                                               \
;   _Pragma("unroll") for (int m = 0; m < 4; ++m) _Pragma("unroll") for (int k = 0; k < 2; ++k) dst[m][k] =            \
;       *reinterpret_cast<const bf16x8*>(SA(b, h) + lds_byte(wr * 64 + m * 16 + fr, k * 32 + fq * 8))
; #define LDB(dst, b, h)                                                                                               \
;   _Pragma("unroll") for (int n = 0; n < 2; ++n) _Pragma("unroll") for (int k = 0; k < 2; ++k) dst[n][k] =            \
;       *reinterpret_cast<const bf16x8*>(SB(b, h) + lds_byte(wc * 32 + n * 16 + fr, k * 32 + fq * 8))
; #define WAIT_V(n) asm volatile("s_waitcnt vmcnt(" #n ")" ::: "memory")
; #define WAIT_L(n) asm volatile("s_waitcnt lgkmcnt(" #n ")" ::: "memory")
; #define BAR __builtin_amdgcn_s_barrier()
; template <int EPI>
; __device__ __forceinline__ void gemm_phase(const u16* __restrict__ A, const u16* __restrict__ Bt, const int K,
;                                            const int nN, char* shm, const EpiArgs& ea) {
;     ...
;     {
;       LDB(B0, 0, 0); LDA(At, 0, 0); STAGE(SA(1, 1), rA, brow + HALF, nt - 1);
;       WAIT_V(10); BAR; WAIT_L(0); MMA(0, 0, At, B0); BAR;
;       LDB(B1, 0, 1); WAIT_V(8); BAR; WAIT_L(0); MMA(0, 1, At, B1); BAR;
;       LDA(At, 0, 1); WAIT_V(4); BAR; WAIT_L(0); MMA(1, 0, At, B0); MMA(1, 1, At, B1); BAR;
;     }
.LBB0_570:
	s_mov_b32 m0, s46
	s_add_i32 s6, s58, 0x7c000
	global_load_dword v154, v[130:131], off
	ds_read_b128 v[128:131], v183
	ds_read_b128 v[132:135], v183 offset:1024
	ds_read_b128 v[136:139], v183 offset:2048
	ds_read_b128 v[140:143], v183 offset:3072
	ds_read_b128 v[144:147], v184
	ds_read_b128 v[148:151], v184 offset:1024
	ds_read_b128 v[156:159], v185
	ds_read_b128 v[160:163], v185 offset:1024
	ds_read_b128 v[164:167], v186
	ds_read_b128 v[168:171], v186 offset:1024
	ds_read_b128 v[192:195], v187
	ds_read_b128 v[196:199], v187 offset:1024
	buffer_load_dwordx4 v175, s[0:3], s6 offen lds
	s_add_i32 s58, s58, 0x7e000
	s_mov_b32 m0, s47
	s_nop 0
	buffer_load_dwordx4 v175, s[0:3], s58 offen lds
	s_waitcnt vmcnt(10)
	s_barrier
	s_waitcnt lgkmcnt(0)
	v_mfma_f32_16x16x32_bf16 v[124:127], v[128:131], v[144:147], v[124:127]
	v_mfma_f32_16x16x32_bf16 v[120:123], v[136:139], v[144:147], v[120:123]
	v_mfma_f32_16x16x32_bf16 v[112:115], v[136:139], v[156:159], v[112:115]
	v_mfma_f32_16x16x32_bf16 v[116:119], v[128:131], v[156:159], v[116:119]
	v_mfma_f32_16x16x32_bf16 v[108:111], v[128:131], v[164:167], v[108:111]
	v_mfma_f32_16x16x32_bf16 v[104:107], v[136:139], v[164:167], v[104:107]
	v_mfma_f32_16x16x32_bf16 v[96:99], v[136:139], v[192:195], v[96:99]
	v_mfma_f32_16x16x32_bf16 v[100:103], v[128:131], v[192:195], v[100:103]
	v_mfma_f32_16x16x32_bf16 v[124:127], v[132:135], v[148:151], v[124:127]
	v_mfma_f32_16x16x32_bf16 v[120:123], v[140:143], v[148:151], v[120:123]
	v_mfma_f32_16x16x32_bf16 v[112:115], v[140:143], v[160:163], v[112:115]
	v_mfma_f32_16x16x32_bf16 v[116:119], v[132:135], v[160:163], v[116:119]
	v_mfma_f32_16x16x32_bf16 v[108:111], v[132:135], v[168:171], v[108:111]
	v_mfma_f32_16x16x32_bf16 v[104:107], v[140:143], v[168:171], v[104:107]
	v_mfma_f32_16x16x32_bf16 v[96:99], v[140:143], v[196:199], v[96:99]
	v_mfma_f32_16x16x32_bf16 v[100:103], v[132:135], v[196:199], v[100:103]
	s_barrier
	ds_read_b128 v[200:203], v188
	ds_read_b128 v[204:207], v188 offset:1024
	ds_read_b128 v[208:211], v188 offset:2048
	ds_read_b128 v[212:215], v188 offset:3072
	s_waitcnt vmcnt(8)
	s_barrier
	s_waitcnt lgkmcnt(0)
	v_mfma_f32_16x16x32_bf16 v[92:95], v[200:203], v[144:147], v[92:95]
	v_mfma_f32_16x16x32_bf16 v[88:91], v[208:211], v[144:147], v[88:91]
	v_mfma_f32_16x16x32_bf16 v[80:83], v[208:211], v[156:159], v[80:83]
	v_mfma_f32_16x16x32_bf16 v[84:87], v[200:203], v[156:159], v[84:87]
	v_mfma_f32_16x16x32_bf16 v[76:79], v[200:203], v[164:167], v[76:79]
	v_mfma_f32_16x16x32_bf16 v[72:75], v[208:211], v[164:167], v[72:75]
	v_mfma_f32_16x16x32_bf16 v[68:71], v[200:203], v[192:195], v[68:71]
	v_mfma_f32_16x16x32_bf16 v[92:95], v[204:207], v[148:151], v[92:95]
	v_mfma_f32_16x16x32_bf16 v[88:91], v[212:215], v[148:151], v[88:91]
	v_mfma_f32_16x16x32_bf16 v[80:83], v[212:215], v[160:163], v[80:83]
	v_mfma_f32_16x16x32_bf16 v[84:87], v[204:207], v[160:163], v[84:87]
	v_mfma_f32_16x16x32_bf16 v[76:79], v[204:207], v[168:171], v[76:79]
	v_mfma_f32_16x16x32_bf16 v[72:75], v[212:215], v[168:171], v[72:75]
	v_mfma_f32_16x16x32_bf16 v[68:71], v[204:207], v[196:199], v[68:71]
	v_mfma_f32_16x16x32_bf16 v[64:67], v[208:211], v[192:195], v[64:67]
	v_mfma_f32_16x16x32_bf16 v[64:67], v[212:215], v[196:199], v[64:67]
	s_barrier
	ds_read_b128 v[144:147], v184 offset:16384
	ds_read_b128 v[148:151], v184 offset:17408
	ds_read_b128 v[156:159], v185 offset:16384
	ds_read_b128 v[160:163], v185 offset:17408
	ds_read_b128 v[164:167], v186 offset:16384
	ds_read_b128 v[168:171], v186 offset:17408
	ds_read_b128 v[192:195], v187 offset:16384
	ds_read_b128 v[196:199], v187 offset:17408
	s_waitcnt vmcnt(4)
	s_barrier
	s_waitcnt lgkmcnt(0)
	v_mfma_f32_16x16x32_bf16 v[40:43], v[136:139], v[164:167], v[40:43]
	v_mfma_f32_16x16x32_bf16 v[36:39], v[128:131], v[192:195], v[36:39]
	v_mfma_f32_16x16x32_bf16 v[60:63], v[128:131], v[144:147], v[60:63]
	v_mfma_f32_16x16x32_bf16 v[56:59], v[136:139], v[144:147], v[56:59]
	v_mfma_f32_16x16x32_bf16 v[48:51], v[136:139], v[156:159], v[48:51]
	v_mfma_f32_16x16x32_bf16 v[52:55], v[128:131], v[156:159], v[52:55]
	v_mfma_f32_16x16x32_bf16 v[44:47], v[128:131], v[164:167], v[44:47]
	v_mfma_f32_16x16x32_bf16 v[40:43], v[140:143], v[168:171], v[40:43]
	v_mfma_f32_16x16x32_bf16 v[36:39], v[132:135], v[196:199], v[36:39]
	v_mfma_f32_16x16x32_bf16 v[32:35], v[136:139], v[192:195], v[32:35]
	v_mfma_f32_16x16x32_bf16 v[60:63], v[132:135], v[148:151], v[60:63]
	v_mfma_f32_16x16x32_bf16 v[56:59], v[140:143], v[148:151], v[56:59]
	v_mfma_f32_16x16x32_bf16 v[48:51], v[140:143], v[160:163], v[48:51]
	v_mfma_f32_16x16x32_bf16 v[52:55], v[132:135], v[160:163], v[52:55]
	v_mfma_f32_16x16x32_bf16 v[44:47], v[132:135], v[168:171], v[44:47]
	v_mfma_f32_16x16x32_bf16 v[32:35], v[140:143], v[196:199], v[32:35]
	v_mfma_f32_16x16x32_bf16 v[12:15], v[200:203], v[164:167], v[12:15]
	v_mfma_f32_16x16x32_bf16 v[8:11], v[208:211], v[164:167], v[8:11]
	v_mfma_f32_16x16x32_bf16 v[0:3], v[208:211], v[192:195], v[0:3]
	v_mfma_f32_16x16x32_bf16 v[4:7], v[200:203], v[192:195], v[4:7]
	v_mfma_f32_16x16x32_bf16 v[28:31], v[200:203], v[144:147], v[28:31]
	v_mfma_f32_16x16x32_bf16 v[24:27], v[208:211], v[144:147], v[24:27]
	v_mfma_f32_16x16x32_bf16 v[16:19], v[208:211], v[156:159], v[16:19]
	v_mfma_f32_16x16x32_bf16 v[20:23], v[200:203], v[156:159], v[20:23]
	v_mfma_f32_16x16x32_bf16 v[12:15], v[204:207], v[168:171], v[12:15]
	v_mfma_f32_16x16x32_bf16 v[8:11], v[212:215], v[168:171], v[8:11]
	v_mfma_f32_16x16x32_bf16 v[0:3], v[212:215], v[196:199], v[0:3]
	v_mfma_f32_16x16x32_bf16 v[4:7], v[204:207], v[196:199], v[4:7]
	v_mfma_f32_16x16x32_bf16 v[216:219], v[204:207], v[148:151], v[28:31]
	v_mfma_f32_16x16x32_bf16 v[220:223], v[212:215], v[148:151], v[24:27]
	v_mfma_f32_16x16x32_bf16 v[224:227], v[204:207], v[160:163], v[20:23]
	v_mfma_f32_16x16x32_bf16 v[160:163], v[212:215], v[160:163], v[16:19]
	s_barrier
; #define LDA(dst, b, h)                                                                                               \
;   _Pragma("unroll") for (int m = 0; m < 4; ++m) _Pragma("unroll") for (int k = 0; k < 2; ++k) dst[m][k] =            \
;       *reinterpret_cast<const bf16x8*>(SA(b, h) + lds_byte(wr * 64 + m * 16 + fr, k * 32 + fq * 8))
; #define LDB(dst, b, h)                                                                                               \
;   _Pragma("unroll") for (int n = 0; n < 2; ++n) _Pragma("unroll") for (int k = 0; k < 2; ++k) dst[n][k] =            \
;       *reinterpret_cast<const bf16x8*>(SB(b, h) + lds_byte(wc * 32 + n * 16 + fr, k * 32 + fq * 8))
; #define WAIT_V(n) asm volatile("s_waitcnt vmcnt(" #n ")" ::: "memory")
; #define WAIT_L(n) asm volatile("s_waitcnt lgkmcnt(" #n ")" ::: "memory")
; #define BAR __builtin_amdgcn_s_barrier()
; template <int EPI>
; __device__ __forceinline__ void gemm_phase(const u16* __restrict__ A, const u16* __restrict__ Bt, const int K,
;                                            const int nN, char* shm, const EpiArgs& ea) {
;     ...
;     {
;       LDB(B0, 1, 0); LDA(At, 1, 0); WAIT_V(2); BAR; WAIT_L(0); MMA(0, 0, At, B0); BAR;
;       LDB(B1, 1, 1); WAIT_V(0); BAR; WAIT_L(0); MMA(0, 1, At, B1); BAR;
;       LDA(At, 1, 1); BAR; WAIT_L(0); MMA(1, 0, At, B0); MMA(1, 1, At, B1); BAR;
;     }
;     if (wr == 0) BAR;
	s_nop 0
	ds_read_b128 v[16:19], v189
	ds_read_b128 v[20:23], v189 offset:1024
	ds_read_b128 v[164:167], v189 offset:2048
	ds_read_b128 v[168:171], v189 offset:3072
	ds_read_b128 v[24:27], v184 offset:32768
	ds_read_b128 v[28:31], v184 offset:33792
	ds_read_b128 v[192:195], v185 offset:32768
	ds_read_b128 v[196:199], v185 offset:33792
	ds_read_b128 v[200:203], v186 offset:32768
	ds_read_b128 v[204:207], v186 offset:33792
	ds_read_b128 v[208:211], v187 offset:32768
	ds_read_b128 v[212:215], v187 offset:33792
	s_waitcnt vmcnt(2)
	s_barrier
	s_waitcnt lgkmcnt(0)
	v_mfma_f32_16x16x32_bf16 v[124:127], v[16:19], v[24:27], v[124:127]
	v_mfma_f32_16x16x32_bf16 v[120:123], v[164:167], v[24:27], v[120:123]
	v_mfma_f32_16x16x32_bf16 v[112:115], v[164:167], v[192:195], v[112:115]
	v_mfma_f32_16x16x32_bf16 v[116:119], v[16:19], v[192:195], v[116:119]
	v_mfma_f32_16x16x32_bf16 v[108:111], v[16:19], v[200:203], v[108:111]
	v_mfma_f32_16x16x32_bf16 v[104:107], v[164:167], v[200:203], v[104:107]
	v_mfma_f32_16x16x32_bf16 v[96:99], v[164:167], v[208:211], v[96:99]
	v_mfma_f32_16x16x32_bf16 v[100:103], v[16:19], v[208:211], v[100:103]
	v_mfma_f32_16x16x32_bf16 v[156:159], v[20:23], v[28:31], v[124:127]
	v_mfma_f32_16x16x32_bf16 v[148:151], v[168:171], v[28:31], v[120:123]
	v_mfma_f32_16x16x32_bf16 v[144:147], v[20:23], v[196:199], v[116:119]
	v_mfma_f32_16x16x32_bf16 v[140:143], v[168:171], v[196:199], v[112:115]
	v_mfma_f32_16x16x32_bf16 v[120:123], v[20:23], v[204:207], v[108:111]
	v_mfma_f32_16x16x32_bf16 v[116:119], v[168:171], v[204:207], v[104:107]
	v_mfma_f32_16x16x32_bf16 v[112:115], v[20:23], v[212:215], v[100:103]
	v_mfma_f32_16x16x32_bf16 v[108:111], v[168:171], v[212:215], v[96:99]
	s_barrier
	ds_read_b128 v[228:231], v190
	ds_read_b128 v[232:235], v190 offset:1024
	ds_read_b128 v[236:239], v190 offset:2048
	ds_read_b128 v[240:243], v190 offset:3072
	s_waitcnt vmcnt(0)
	s_barrier
	s_waitcnt lgkmcnt(0)
	v_mfma_f32_16x16x32_bf16 v[92:95], v[228:231], v[24:27], v[92:95]
	v_mfma_f32_16x16x32_bf16 v[24:27], v[236:239], v[24:27], v[88:91]
	v_mfma_f32_16x16x32_bf16 v[132:135], v[240:243], v[28:31], v[24:27]
	v_mfma_f32_16x16x32_bf16 v[24:27], v[228:231], v[192:195], v[84:87]
	v_mfma_f32_16x16x32_bf16 v[128:131], v[232:235], v[196:199], v[24:27]
	v_mfma_f32_16x16x32_bf16 v[24:27], v[236:239], v[192:195], v[80:83]
	v_mfma_f32_16x16x32_bf16 v[124:127], v[240:243], v[196:199], v[24:27]
	v_mfma_f32_16x16x32_bf16 v[24:27], v[228:231], v[200:203], v[76:79]
	v_mfma_f32_16x16x32_bf16 v[104:107], v[232:235], v[204:207], v[24:27]
	v_mfma_f32_16x16x32_bf16 v[24:27], v[236:239], v[200:203], v[72:75]
	v_mfma_f32_16x16x32_bf16 v[100:103], v[240:243], v[204:207], v[24:27]
	v_mfma_f32_16x16x32_bf16 v[24:27], v[228:231], v[208:211], v[68:71]
	v_mfma_f32_16x16x32_bf16 v[96:99], v[232:235], v[212:215], v[24:27]
	v_mfma_f32_16x16x32_bf16 v[24:27], v[236:239], v[208:211], v[64:67]
	v_mfma_f32_16x16x32_bf16 v[136:139], v[232:235], v[28:31], v[92:95]
	v_mfma_f32_16x16x32_bf16 v[92:95], v[240:243], v[212:215], v[24:27]
	s_barrier
	ds_read_b128 v[64:67], v184 offset:49152
	ds_read_b128 v[68:71], v184 offset:50176
	ds_read_b128 v[192:195], v185 offset:49152
	ds_read_b128 v[196:199], v185 offset:50176
	ds_read_b128 v[200:203], v186 offset:49152
	ds_read_b128 v[204:207], v186 offset:50176
	ds_read_b128 v[208:211], v187 offset:49152
	ds_read_b128 v[212:215], v187 offset:50176
	s_barrier
	s_waitcnt lgkmcnt(0)
	v_mfma_f32_16x16x32_bf16 v[24:27], v[16:19], v[64:67], v[60:63]
	v_mfma_f32_16x16x32_bf16 v[88:91], v[20:23], v[68:71], v[24:27]
	v_mfma_f32_16x16x32_bf16 v[24:27], v[164:167], v[64:67], v[56:59]
	v_mfma_f32_16x16x32_bf16 v[84:87], v[168:171], v[68:71], v[24:27]
	v_mfma_f32_16x16x32_bf16 v[24:27], v[16:19], v[192:195], v[52:55]
	v_mfma_f32_16x16x32_bf16 v[80:83], v[20:23], v[196:199], v[24:27]
	v_mfma_f32_16x16x32_bf16 v[24:27], v[164:167], v[192:195], v[48:51]
	v_mfma_f32_16x16x32_bf16 v[76:79], v[168:171], v[196:199], v[24:27]
	v_mfma_f32_16x16x32_bf16 v[24:27], v[16:19], v[200:203], v[44:47]
	v_mfma_f32_16x16x32_bf16 v[16:19], v[16:19], v[208:211], v[36:39]
	v_mfma_f32_16x16x32_bf16 v[28:31], v[20:23], v[204:207], v[24:27]
	v_mfma_f32_16x16x32_bf16 v[24:27], v[164:167], v[200:203], v[40:43]
	v_mfma_f32_16x16x32_bf16 v[20:23], v[20:23], v[212:215], v[16:19]
	v_mfma_f32_16x16x32_bf16 v[16:19], v[164:167], v[208:211], v[32:35]
	v_mfma_f32_16x16x32_bf16 v[24:27], v[168:171], v[204:207], v[24:27]
	v_mfma_f32_16x16x32_bf16 v[16:19], v[168:171], v[212:215], v[16:19]
	v_mfma_f32_16x16x32_bf16 v[32:35], v[228:231], v[64:67], v[216:219]
	v_mfma_f32_16x16x32_bf16 v[72:75], v[232:235], v[68:71], v[32:35]
	v_mfma_f32_16x16x32_bf16 v[32:35], v[236:239], v[64:67], v[220:223]
	v_mfma_f32_16x16x32_bf16 v[68:71], v[240:243], v[68:71], v[32:35]
	v_mfma_f32_16x16x32_bf16 v[32:35], v[228:231], v[192:195], v[224:227]
	v_mfma_f32_16x16x32_bf16 v[40:43], v[232:235], v[196:199], v[32:35]
	v_mfma_f32_16x16x32_bf16 v[32:35], v[236:239], v[192:195], v[160:163]
	v_mfma_f32_16x16x32_bf16 v[12:15], v[228:231], v[200:203], v[12:15]
	v_mfma_f32_16x16x32_bf16 v[8:11], v[236:239], v[200:203], v[8:11]
	v_mfma_f32_16x16x32_bf16 v[0:3], v[236:239], v[208:211], v[0:3]
	v_mfma_f32_16x16x32_bf16 v[4:7], v[228:231], v[208:211], v[4:7]
	v_mfma_f32_16x16x32_bf16 v[36:39], v[240:243], v[196:199], v[32:35]
	v_mfma_f32_16x16x32_bf16 v[12:15], v[232:235], v[204:207], v[12:15]
	v_mfma_f32_16x16x32_bf16 v[8:11], v[240:243], v[204:207], v[8:11]
	v_mfma_f32_16x16x32_bf16 v[0:3], v[240:243], v[212:215], v[0:3]
	v_mfma_f32_16x16x32_bf16 v[4:7], v[232:235], v[212:215], v[4:7]
	s_andn2_b64 vcc, exec, s[16:17]
	s_barrier
	s_cbranch_vccz .LBB0_574
	s_andn2_b64 vcc, exec, s[28:29]
	s_cbranch_vccz .LBB0_575

; #define LDA(dst, b, h)                                                                                               \
;   _Pragma("unroll") for (int m = 0; m < 4; ++m) _Pragma("unroll") for (int k = 0; k < 2; ++k) dst[m][k] =            \
;       *reinterpret_cast<const bf16x8*>(SA(b, h) + lds_byte(wr * 64 + m * 16 + fr, k * 32 + fq * 8))
; #define LDB(dst, b, h)                                                                                               \
;   _Pragma("unroll") for (int n = 0; n < 2; ++n) _Pragma("unroll") for (int k = 0; k < 2; ++k) dst[n][k] =            \
;       *reinterpret_cast<const bf16x8*>(SB(b, h) + lds_byte(wc * 32 + n * 16 + fr, k * 32 + fq * 8))
; #define WAIT_V(n) asm volatile("s_waitcnt vmcnt(" #n ")" ::: "memory")
; #define WAIT_L(n) asm volatile("s_waitcnt lgkmcnt(" #n ")" ::: "memory")
; #define BAR __builtin_amdgcn_s_barrier()
; #define SCHED __builtin_amdgcn_sched_barrier(0)
; template <int EPI>
; __device__ __forceinline__ void gemm_phase(const u16* __restrict__ A, const u16* __restrict__ Bt, const int K,
;                                            const int nN, char* shm, const EpiArgs& ea) {
;     ...
;       LDB(B0, 0, 0); SCHED; LDA(At, 0, 0); STAGE(SA(1, 1), rA, brow + HALF, t + 1);
;       WAIT_V(10); WAIT_L(8); BAR; WAIT_L(0); MMA(0, 0, At, B0); BAR; SCHED;
;       LDB(B1, 0, 1); STAGE(SB(0, 0), rB, bcol, t + 2);
;       WAIT_V(10); BAR; WAIT_L(0); MMA(0, 1, At, B1); BAR;
;       LDA(At, 0, 1); STAGE(SA(0, 0), rA, brow, t + 2);
;       BAR; WAIT_L(0); MMA(1, 0, At, B0); BAR; SCHED;
;       STAGE(SB(0, 1), rB, bcol + HALF, t + 2);
;       WAIT_V(10); BAR; MMA(1, 1, At, B1); BAR;
.LBB0_631:
	ds_read_b128 v[130:133], v141
	ds_read_b128 v[134:137], v141 offset:1024
	ds_read_b128 v[150:153], v141 offset:2048
	ds_read_b128 v[154:157], v141 offset:3072
	s_add_i32 s54, s48, s53
	s_mov_b32 m0, s41
	s_add_i32 s6, s54, 0x4000
	ds_read_b128 v[158:161], v142
	ds_read_b128 v[162:165], v142 offset:1024
	ds_read_b128 v[166:169], v143
	ds_read_b128 v[170:173], v143 offset:1024
	ds_read_b128 v[176:179], v144
	ds_read_b128 v[180:183], v144 offset:1024
	ds_read_b128 v[184:187], v145
	ds_read_b128 v[188:191], v145 offset:1024
	buffer_load_dwordx4 v138, s[0:3], s6 offen lds
	s_add_i32 s6, s54, 0x6000
	s_mov_b32 m0, s42
	s_nop 0
	buffer_load_dwordx4 v138, s[0:3], s6 offen lds
	s_waitcnt vmcnt(10)
	s_waitcnt lgkmcnt(8)
	s_barrier
	s_waitcnt lgkmcnt(0)
	v_mfma_f32_16x16x32_bf16 v[124:127], v[130:133], v[158:161], v[124:127]
	v_mfma_f32_16x16x32_bf16 v[120:123], v[150:153], v[158:161], v[120:123]
	v_mfma_f32_16x16x32_bf16 v[112:115], v[150:153], v[166:169], v[112:115]
	v_mfma_f32_16x16x32_bf16 v[116:119], v[130:133], v[166:169], v[116:119]
	v_mfma_f32_16x16x32_bf16 v[108:111], v[130:133], v[176:179], v[108:111]
	v_mfma_f32_16x16x32_bf16 v[104:107], v[150:153], v[176:179], v[104:107]
	v_mfma_f32_16x16x32_bf16 v[96:99], v[150:153], v[184:187], v[96:99]
	v_mfma_f32_16x16x32_bf16 v[100:103], v[130:133], v[184:187], v[100:103]
	v_mfma_f32_16x16x32_bf16 v[124:127], v[134:137], v[162:165], v[124:127]
	v_mfma_f32_16x16x32_bf16 v[120:123], v[154:157], v[162:165], v[120:123]
	v_mfma_f32_16x16x32_bf16 v[112:115], v[154:157], v[170:173], v[112:115]
	v_mfma_f32_16x16x32_bf16 v[116:119], v[134:137], v[170:173], v[116:119]
	v_mfma_f32_16x16x32_bf16 v[108:111], v[134:137], v[180:183], v[108:111]
	v_mfma_f32_16x16x32_bf16 v[104:107], v[154:157], v[180:183], v[104:107]
	v_mfma_f32_16x16x32_bf16 v[96:99], v[154:157], v[188:191], v[96:99]
	v_mfma_f32_16x16x32_bf16 v[100:103], v[134:137], v[188:191], v[100:103]
	s_barrier
	s_add_i32 s55, s51, s53
	s_mov_b32 m0, s19
	s_add_i32 s56, s55, 0x8000
	s_mov_b32 s6, s2
	s_mov_b32 s7, s3
	ds_read_b128 v[192:195], v146
	ds_read_b128 v[196:199], v146 offset:1024
	ds_read_b128 v[200:203], v146 offset:2048
	ds_read_b128 v[204:207], v146 offset:3072
	buffer_load_dwordx4 v138, s[4:7], s56 offen lds
	s_add_i32 s56, s55, 0xa000
	s_mov_b32 m0, s26
	s_nop 0
	buffer_load_dwordx4 v138, s[4:7], s56 offen lds
	s_waitcnt vmcnt(10)
	s_barrier
	s_waitcnt lgkmcnt(0)
	v_mfma_f32_16x16x32_bf16 v[92:95], v[192:195], v[158:161], v[92:95]
	v_mfma_f32_16x16x32_bf16 v[88:91], v[200:203], v[158:161], v[88:91]
	v_mfma_f32_16x16x32_bf16 v[80:83], v[200:203], v[166:169], v[80:83]
	v_mfma_f32_16x16x32_bf16 v[84:87], v[192:195], v[166:169], v[84:87]
	v_mfma_f32_16x16x32_bf16 v[76:79], v[192:195], v[176:179], v[76:79]
	v_mfma_f32_16x16x32_bf16 v[72:75], v[200:203], v[176:179], v[72:75]
	v_mfma_f32_16x16x32_bf16 v[64:67], v[200:203], v[184:187], v[64:67]
	v_mfma_f32_16x16x32_bf16 v[68:71], v[192:195], v[184:187], v[68:71]
	v_mfma_f32_16x16x32_bf16 v[92:95], v[196:199], v[162:165], v[92:95]
	v_mfma_f32_16x16x32_bf16 v[88:91], v[204:207], v[162:165], v[88:91]
	v_mfma_f32_16x16x32_bf16 v[80:83], v[204:207], v[170:173], v[80:83]
	v_mfma_f32_16x16x32_bf16 v[84:87], v[196:199], v[170:173], v[84:87]
	v_mfma_f32_16x16x32_bf16 v[76:79], v[196:199], v[180:183], v[76:79]
	v_mfma_f32_16x16x32_bf16 v[72:75], v[204:207], v[180:183], v[72:75]
	v_mfma_f32_16x16x32_bf16 v[64:67], v[204:207], v[188:191], v[64:67]
	v_mfma_f32_16x16x32_bf16 v[68:71], v[196:199], v[188:191], v[68:71]
	s_add_i32 s56, s50, s53
	s_mov_b32 m0, s27
	s_add_i32 s57, s56, 0x8000
	s_barrier
	ds_read_b128 v[158:161], v142 offset:16384
	ds_read_b128 v[162:165], v142 offset:17408
	ds_read_b128 v[166:169], v143 offset:16384
	ds_read_b128 v[170:173], v143 offset:17408
	ds_read_b128 v[176:179], v144 offset:16384
	ds_read_b128 v[180:183], v144 offset:17408
	ds_read_b128 v[184:187], v145 offset:16384
	ds_read_b128 v[188:191], v145 offset:17408
	buffer_load_dwordx4 v138, s[0:3], s57 offen lds
	s_add_i32 s57, s56, 0xa000
	s_mov_b32 m0, s28
	s_nop 0
	buffer_load_dwordx4 v138, s[0:3], s57 offen lds
	s_barrier
	s_waitcnt lgkmcnt(0)
	v_mfma_f32_16x16x32_bf16 v[60:63], v[130:133], v[158:161], v[60:63]
	v_mfma_f32_16x16x32_bf16 v[56:59], v[150:153], v[158:161], v[56:59]
	v_mfma_f32_16x16x32_bf16 v[48:51], v[150:153], v[166:169], v[48:51]
	v_mfma_f32_16x16x32_bf16 v[52:55], v[130:133], v[166:169], v[52:55]
	v_mfma_f32_16x16x32_bf16 v[44:47], v[130:133], v[176:179], v[44:47]
	v_mfma_f32_16x16x32_bf16 v[40:43], v[150:153], v[176:179], v[40:43]
	v_mfma_f32_16x16x32_bf16 v[32:35], v[150:153], v[184:187], v[32:35]
	v_mfma_f32_16x16x32_bf16 v[36:39], v[130:133], v[184:187], v[36:39]
	v_mfma_f32_16x16x32_bf16 v[60:63], v[134:137], v[162:165], v[60:63]
	v_mfma_f32_16x16x32_bf16 v[56:59], v[154:157], v[162:165], v[56:59]
	v_mfma_f32_16x16x32_bf16 v[48:51], v[154:157], v[170:173], v[48:51]
	v_mfma_f32_16x16x32_bf16 v[52:55], v[134:137], v[170:173], v[52:55]
	v_mfma_f32_16x16x32_bf16 v[44:47], v[134:137], v[180:183], v[44:47]
	v_mfma_f32_16x16x32_bf16 v[40:43], v[154:157], v[180:183], v[40:43]
	v_mfma_f32_16x16x32_bf16 v[32:35], v[154:157], v[188:191], v[32:35]
	v_mfma_f32_16x16x32_bf16 v[36:39], v[134:137], v[188:191], v[36:39]
	s_barrier
	s_add_i32 s57, s49, s53
	s_mov_b32 m0, s29
	s_add_i32 s58, s57, 0x8000
	buffer_load_dwordx4 v138, s[4:7], s58 offen lds
	s_add_i32 s58, s57, 0xa000
	s_mov_b32 m0, s30
	s_nop 0
	buffer_load_dwordx4 v138, s[4:7], s58 offen lds
	s_waitcnt vmcnt(10)
	s_barrier
; #define LDA(dst, b, h)                                                                                               \
;   _Pragma("unroll") for (int m = 0; m < 4; ++m) _Pragma("unroll") for (int k = 0; k < 2; ++k) dst[m][k] =            \
;       *reinterpret_cast<const bf16x8*>(SA(b, h) + lds_byte(wr * 64 + m * 16 + fr, k * 32 + fq * 8))
; #define LDB(dst, b, h)                                                                                               \
;   _Pragma("unroll") for (int n = 0; n < 2; ++n) _Pragma("unroll") for (int k = 0; k < 2; ++k) dst[n][k] =            \
;       *reinterpret_cast<const bf16x8*>(SB(b, h) + lds_byte(wc * 32 + n * 16 + fr, k * 32 + fq * 8))
; #define WAIT_V(n) asm volatile("s_waitcnt vmcnt(" #n ")" ::: "memory")
; #define WAIT_L(n) asm volatile("s_waitcnt lgkmcnt(" #n ")" ::: "memory")
; #define BAR __builtin_amdgcn_s_barrier()
; #define SCHED __builtin_amdgcn_sched_barrier(0)
; template <int EPI>
; __device__ __forceinline__ void gemm_phase(const u16* __restrict__ A, const u16* __restrict__ Bt, const int K,
;                                            const int nN, char* shm, const EpiArgs& ea) {
;     ...
;       WAIT_V(10); BAR; MMA(1, 1, At, B1); BAR;
;       LDB(B0, 1, 0); SCHED; LDA(At, 1, 0); STAGE(SA(0, 1), rA, brow + HALF, t + 2);
;       WAIT_V(10); WAIT_L(8); BAR; WAIT_L(0); MMA(0, 0, At, B0); BAR; SCHED;
;       LDB(B1, 1, 1); STAGE(SB(1, 0), rB, bcol, t + 3);
;       WAIT_V(10); BAR; WAIT_L(0); MMA(0, 1, At, B1); BAR;
;       LDA(At, 1, 1); STAGE(SA(1, 0), rA, brow, t + 3);
;       BAR; WAIT_L(0); MMA(1, 0, At, B0); BAR; SCHED;
	v_mfma_f32_16x16x32_bf16 v[28:31], v[192:195], v[158:161], v[28:31]
	v_mfma_f32_16x16x32_bf16 v[24:27], v[200:203], v[158:161], v[24:27]
	v_mfma_f32_16x16x32_bf16 v[16:19], v[200:203], v[166:169], v[16:19]
	v_mfma_f32_16x16x32_bf16 v[20:23], v[192:195], v[166:169], v[20:23]
	v_mfma_f32_16x16x32_bf16 v[12:15], v[192:195], v[176:179], v[12:15]
	v_mfma_f32_16x16x32_bf16 v[8:11], v[200:203], v[176:179], v[8:11]
	v_mfma_f32_16x16x32_bf16 v[0:3], v[200:203], v[184:187], v[0:3]
	v_mfma_f32_16x16x32_bf16 v[4:7], v[192:195], v[184:187], v[4:7]
	v_mfma_f32_16x16x32_bf16 v[28:31], v[196:199], v[162:165], v[28:31]
	v_mfma_f32_16x16x32_bf16 v[24:27], v[204:207], v[162:165], v[24:27]
	v_mfma_f32_16x16x32_bf16 v[16:19], v[204:207], v[170:173], v[16:19]
	v_mfma_f32_16x16x32_bf16 v[20:23], v[196:199], v[170:173], v[20:23]
	v_mfma_f32_16x16x32_bf16 v[12:15], v[196:199], v[180:183], v[12:15]
	v_mfma_f32_16x16x32_bf16 v[8:11], v[204:207], v[180:183], v[8:11]
	v_mfma_f32_16x16x32_bf16 v[0:3], v[204:207], v[188:191], v[0:3]
	v_mfma_f32_16x16x32_bf16 v[4:7], v[196:199], v[188:191], v[4:7]
	s_barrier
	ds_read_b128 v[130:133], v147
	ds_read_b128 v[134:137], v147 offset:1024
	ds_read_b128 v[150:153], v147 offset:2048
	ds_read_b128 v[154:157], v147 offset:3072
	s_mov_b32 m0, s31
	s_add_i32 s58, s54, 0x8000
	ds_read_b128 v[158:161], v142 offset:32768
	ds_read_b128 v[162:165], v142 offset:33792
	ds_read_b128 v[166:169], v143 offset:32768
	ds_read_b128 v[170:173], v143 offset:33792
	ds_read_b128 v[176:179], v144 offset:32768
	ds_read_b128 v[180:183], v144 offset:33792
	ds_read_b128 v[184:187], v145 offset:32768
	ds_read_b128 v[188:191], v145 offset:33792
	buffer_load_dwordx4 v138, s[0:3], s58 offen lds
	s_add_i32 s54, s54, 0xa000
	s_mov_b32 m0, s34
	s_nop 0
	buffer_load_dwordx4 v138, s[0:3], s54 offen lds
	s_waitcnt vmcnt(10)
	s_waitcnt lgkmcnt(8)
	s_barrier
	s_waitcnt lgkmcnt(0)
	v_mfma_f32_16x16x32_bf16 v[124:127], v[130:133], v[158:161], v[124:127]
	v_mfma_f32_16x16x32_bf16 v[120:123], v[150:153], v[158:161], v[120:123]
	v_mfma_f32_16x16x32_bf16 v[112:115], v[150:153], v[166:169], v[112:115]
	v_mfma_f32_16x16x32_bf16 v[116:119], v[130:133], v[166:169], v[116:119]
	v_mfma_f32_16x16x32_bf16 v[108:111], v[130:133], v[176:179], v[108:111]
	v_mfma_f32_16x16x32_bf16 v[104:107], v[150:153], v[176:179], v[104:107]
	v_mfma_f32_16x16x32_bf16 v[96:99], v[150:153], v[184:187], v[96:99]
	v_mfma_f32_16x16x32_bf16 v[100:103], v[130:133], v[184:187], v[100:103]
	v_mfma_f32_16x16x32_bf16 v[124:127], v[134:137], v[162:165], v[124:127]
	v_mfma_f32_16x16x32_bf16 v[120:123], v[154:157], v[162:165], v[120:123]
	v_mfma_f32_16x16x32_bf16 v[112:115], v[154:157], v[170:173], v[112:115]
	v_mfma_f32_16x16x32_bf16 v[116:119], v[134:137], v[170:173], v[116:119]
	v_mfma_f32_16x16x32_bf16 v[108:111], v[134:137], v[180:183], v[108:111]
	v_mfma_f32_16x16x32_bf16 v[104:107], v[154:157], v[180:183], v[104:107]
	v_mfma_f32_16x16x32_bf16 v[96:99], v[154:157], v[188:191], v[96:99]
	v_mfma_f32_16x16x32_bf16 v[100:103], v[134:137], v[188:191], v[100:103]
	s_barrier
	s_mov_b32 m0, s35
	s_add_i32 s54, s55, 0xc000
	ds_read_b128 v[192:195], v148
	ds_read_b128 v[196:199], v148 offset:1024
	ds_read_b128 v[200:203], v148 offset:2048
	ds_read_b128 v[204:207], v148 offset:3072
	buffer_load_dwordx4 v138, s[4:7], s54 offen lds
	s_add_i32 s55, s55, 0xe000
	s_mov_b32 m0, s36
	s_nop 0
	buffer_load_dwordx4 v138, s[4:7], s55 offen lds
	s_waitcnt vmcnt(10)
	s_barrier
	s_waitcnt lgkmcnt(0)
	v_mfma_f32_16x16x32_bf16 v[92:95], v[192:195], v[158:161], v[92:95]
	v_mfma_f32_16x16x32_bf16 v[88:91], v[200:203], v[158:161], v[88:91]
	v_mfma_f32_16x16x32_bf16 v[80:83], v[200:203], v[166:169], v[80:83]
	v_mfma_f32_16x16x32_bf16 v[84:87], v[192:195], v[166:169], v[84:87]
	v_mfma_f32_16x16x32_bf16 v[76:79], v[192:195], v[176:179], v[76:79]
	v_mfma_f32_16x16x32_bf16 v[72:75], v[200:203], v[176:179], v[72:75]
	v_mfma_f32_16x16x32_bf16 v[64:67], v[200:203], v[184:187], v[64:67]
	v_mfma_f32_16x16x32_bf16 v[68:71], v[192:195], v[184:187], v[68:71]
	v_mfma_f32_16x16x32_bf16 v[92:95], v[196:199], v[162:165], v[92:95]
	v_mfma_f32_16x16x32_bf16 v[88:91], v[204:207], v[162:165], v[88:91]
	v_mfma_f32_16x16x32_bf16 v[80:83], v[204:207], v[170:173], v[80:83]
	v_mfma_f32_16x16x32_bf16 v[84:87], v[196:199], v[170:173], v[84:87]
	v_mfma_f32_16x16x32_bf16 v[76:79], v[196:199], v[180:183], v[76:79]
	v_mfma_f32_16x16x32_bf16 v[72:75], v[204:207], v[180:183], v[72:75]
	v_mfma_f32_16x16x32_bf16 v[64:67], v[204:207], v[188:191], v[64:67]
	v_mfma_f32_16x16x32_bf16 v[68:71], v[196:199], v[188:191], v[68:71]
	s_mov_b32 m0, s37
	s_add_i32 s54, s56, 0xc000
	s_barrier
	ds_read_b128 v[158:161], v142 offset:49152
	ds_read_b128 v[162:165], v142 offset:50176
	ds_read_b128 v[166:169], v143 offset:49152
	ds_read_b128 v[170:173], v143 offset:50176
	ds_read_b128 v[176:179], v144 offset:49152
	ds_read_b128 v[180:183], v144 offset:50176
	ds_read_b128 v[184:187], v145 offset:49152
	ds_read_b128 v[188:191], v145 offset:50176
	buffer_load_dwordx4 v138, s[0:3], s54 offen lds
	s_add_i32 s56, s56, 0xe000
	s_mov_b32 m0, s38
	s_nop 0
	buffer_load_dwordx4 v138, s[0:3], s56 offen lds
	s_barrier
; #define LDA(dst, b, h)                                                                                               \
;   _Pragma("unroll") for (int m = 0; m < 4; ++m) _Pragma("unroll") for (int k = 0; k < 2; ++k) dst[m][k] =            \
;       *reinterpret_cast<const bf16x8*>(SA(b, h) + lds_byte(wr * 64 + m * 16 + fr, k * 32 + fq * 8))
; #define LDB(dst, b, h)                                                                                               \
;   _Pragma("unroll") for (int n = 0; n < 2; ++n) _Pragma("unroll") for (int k = 0; k < 2; ++k) dst[n][k] =            \
;       *reinterpret_cast<const bf16x8*>(SB(b, h) + lds_byte(wc * 32 + n * 16 + fr, k * 32 + fq * 8))
; #define WAIT_V(n) asm volatile("s_waitcnt vmcnt(" #n ")" ::: "memory")
; #define WAIT_L(n) asm volatile("s_waitcnt lgkmcnt(" #n ")" ::: "memory")
; #define BAR __builtin_amdgcn_s_barrier()
; #define SCHED __builtin_amdgcn_sched_barrier(0)
; template <int EPI>
; __device__ __forceinline__ void gemm_phase(const u16* __restrict__ A, const u16* __restrict__ Bt, const int K,
;                                            const int nN, char* shm, const EpiArgs& ea) {
;     ...
;       BAR; WAIT_L(0); MMA(1, 0, At, B0); BAR; SCHED;
;       STAGE(SB(1, 1), rB, bcol + HALF, t + 3);
;       WAIT_V(10); BAR; MMA(1, 1, At, B1); BAR;
;     }
;     float eC = 0.f, eB = 0.f;
;     float2 eS = make_float2(0.f, 0.f);
;     if (EPI == EPI_IN || EPI == EPI_SWIGLU_LN) {
;       if (wr == 0) {
;         eC = ea.c1[bcol + tid];
;         eS = *(const float2*)(ea.st_in + (size_t)(brow + tid) * 2);
;       } else {
;         eC = ea.c2[bcol + tid - 256];
;         if (EPI == EPI_IN) eB = ea.bias[bcol + tid - 256];
;       }
;     }
;     {
;       LDB(B0, 0, 0); LDA(At, 0, 0); STAGE(SA(1, 1), rA, brow + HALF, nt - 1);
;       WAIT_V(10); BAR; WAIT_L(0); MMA(0, 0, At, B0); BAR;
;       LDB(B1, 0, 1); WAIT_V(8); BAR; WAIT_L(0); MMA(0, 1, At, B1); BAR;
;       LDA(At, 0, 1); WAIT_V(4); BAR; WAIT_L(0); MMA(1, 0, At, B0); MMA(1, 1, At, B1); BAR;
	s_waitcnt lgkmcnt(0)
	v_mfma_f32_16x16x32_bf16 v[60:63], v[130:133], v[158:161], v[60:63]
	v_mfma_f32_16x16x32_bf16 v[56:59], v[150:153], v[158:161], v[56:59]
	v_mfma_f32_16x16x32_bf16 v[48:51], v[150:153], v[166:169], v[48:51]
	v_mfma_f32_16x16x32_bf16 v[52:55], v[130:133], v[166:169], v[52:55]
	v_mfma_f32_16x16x32_bf16 v[44:47], v[130:133], v[176:179], v[44:47]
	v_mfma_f32_16x16x32_bf16 v[40:43], v[150:153], v[176:179], v[40:43]
	v_mfma_f32_16x16x32_bf16 v[32:35], v[150:153], v[184:187], v[32:35]
	v_mfma_f32_16x16x32_bf16 v[36:39], v[130:133], v[184:187], v[36:39]
	v_mfma_f32_16x16x32_bf16 v[60:63], v[134:137], v[162:165], v[60:63]
	v_mfma_f32_16x16x32_bf16 v[56:59], v[154:157], v[162:165], v[56:59]
	v_mfma_f32_16x16x32_bf16 v[48:51], v[154:157], v[170:173], v[48:51]
	v_mfma_f32_16x16x32_bf16 v[52:55], v[134:137], v[170:173], v[52:55]
	v_mfma_f32_16x16x32_bf16 v[44:47], v[134:137], v[180:183], v[44:47]
	v_mfma_f32_16x16x32_bf16 v[40:43], v[154:157], v[180:183], v[40:43]
	v_mfma_f32_16x16x32_bf16 v[32:35], v[154:157], v[188:191], v[32:35]
	v_mfma_f32_16x16x32_bf16 v[36:39], v[134:137], v[188:191], v[36:39]
	s_barrier
	s_mov_b32 m0, s39
	s_add_i32 s54, s57, 0xc000
	buffer_load_dwordx4 v138, s[4:7], s54 offen lds
	s_add_i32 s57, s57, 0xe000
	s_mov_b32 m0, s40
	s_nop 0
	buffer_load_dwordx4 v138, s[4:7], s57 offen lds
	s_waitcnt vmcnt(10)
	s_barrier
	v_mfma_f32_16x16x32_bf16 v[28:31], v[192:195], v[158:161], v[28:31]
	v_mfma_f32_16x16x32_bf16 v[24:27], v[200:203], v[158:161], v[24:27]
	v_mfma_f32_16x16x32_bf16 v[16:19], v[200:203], v[166:169], v[16:19]
	v_mfma_f32_16x16x32_bf16 v[20:23], v[192:195], v[166:169], v[20:23]
	v_mfma_f32_16x16x32_bf16 v[12:15], v[192:195], v[176:179], v[12:15]
	v_mfma_f32_16x16x32_bf16 v[8:11], v[200:203], v[176:179], v[8:11]
	v_mfma_f32_16x16x32_bf16 v[0:3], v[200:203], v[184:187], v[0:3]
	v_mfma_f32_16x16x32_bf16 v[4:7], v[192:195], v[184:187], v[4:7]
	v_mfma_f32_16x16x32_bf16 v[28:31], v[196:199], v[162:165], v[28:31]
	v_mfma_f32_16x16x32_bf16 v[24:27], v[204:207], v[162:165], v[24:27]
	v_mfma_f32_16x16x32_bf16 v[16:19], v[204:207], v[170:173], v[16:19]
	v_mfma_f32_16x16x32_bf16 v[20:23], v[196:199], v[170:173], v[20:23]
	v_mfma_f32_16x16x32_bf16 v[12:15], v[196:199], v[180:183], v[12:15]
	v_mfma_f32_16x16x32_bf16 v[8:11], v[204:207], v[180:183], v[8:11]
	v_mfma_f32_16x16x32_bf16 v[0:3], v[204:207], v[188:191], v[0:3]
	v_mfma_f32_16x16x32_bf16 v[4:7], v[196:199], v[188:191], v[4:7]
	s_add_i32 s52, s52, 2
	s_add_i32 s53, s53, 0x8000
	s_cmpk_lt_u32 s52, 0x54
	s_barrier
	s_cbranch_scc1 .LBB0_631
	s_mov_b32 m0, s41
	s_add_i32 s6, s48, 0x15c000
	ds_read_b128 v[130:133], v141
	ds_read_b128 v[134:137], v141 offset:1024
	ds_read_b128 v[150:153], v141 offset:2048
	ds_read_b128 v[154:157], v141 offset:3072
	ds_read_b128 v[158:161], v142
	ds_read_b128 v[162:165], v142 offset:1024
	ds_read_b128 v[166:169], v143
	ds_read_b128 v[170:173], v143 offset:1024
	ds_read_b128 v[176:179], v144
	ds_read_b128 v[180:183], v144 offset:1024
	ds_read_b128 v[184:187], v145
	ds_read_b128 v[188:191], v145 offset:1024
	buffer_load_dwordx4 v138, s[0:3], s6 offen lds
	s_add_i32 s48, s48, 0x15e000
	s_mov_b32 m0, s42
	s_nop 0
	buffer_load_dwordx4 v138, s[0:3], s48 offen lds
	s_waitcnt vmcnt(10)
	s_barrier
	s_waitcnt lgkmcnt(0)
	v_mfma_f32_16x16x32_bf16 v[124:127], v[130:133], v[158:161], v[124:127]
	v_mfma_f32_16x16x32_bf16 v[120:123], v[150:153], v[158:161], v[120:123]
	v_mfma_f32_16x16x32_bf16 v[112:115], v[150:153], v[166:169], v[112:115]
	v_mfma_f32_16x16x32_bf16 v[116:119], v[130:133], v[166:169], v[116:119]
	v_mfma_f32_16x16x32_bf16 v[100:103], v[130:133], v[184:187], v[100:103]
	v_mfma_f32_16x16x32_bf16 v[96:99], v[150:153], v[184:187], v[96:99]
	v_mfma_f32_16x16x32_bf16 v[124:127], v[134:137], v[162:165], v[124:127]
	v_mfma_f32_16x16x32_bf16 v[120:123], v[154:157], v[162:165], v[120:123]
	v_mfma_f32_16x16x32_bf16 v[112:115], v[154:157], v[170:173], v[112:115]
	v_mfma_f32_16x16x32_bf16 v[116:119], v[134:137], v[170:173], v[116:119]
	v_mfma_f32_16x16x32_bf16 v[108:111], v[130:133], v[176:179], v[108:111]
	v_mfma_f32_16x16x32_bf16 v[104:107], v[150:153], v[176:179], v[104:107]
	v_mfma_f32_16x16x32_bf16 v[100:103], v[134:137], v[188:191], v[100:103]
	v_mfma_f32_16x16x32_bf16 v[96:99], v[154:157], v[188:191], v[96:99]
	v_mfma_f32_16x16x32_bf16 v[192:195], v[134:137], v[180:183], v[108:111]
	v_mfma_f32_16x16x32_bf16 v[196:199], v[154:157], v[180:183], v[104:107]
	s_barrier
	s_nop 0
	ds_read_b128 v[104:107], v146
	ds_read_b128 v[108:111], v146 offset:1024
	ds_read_b128 v[200:203], v146 offset:2048
	ds_read_b128 v[204:207], v146 offset:3072
	s_waitcnt vmcnt(8)
	s_barrier
	s_waitcnt lgkmcnt(0)
	v_mfma_f32_16x16x32_bf16 v[84:87], v[104:107], v[166:169], v[84:87]
	v_mfma_f32_16x16x32_bf16 v[80:83], v[200:203], v[166:169], v[80:83]
	v_mfma_f32_16x16x32_bf16 v[64:67], v[200:203], v[184:187], v[64:67]
	v_mfma_f32_16x16x32_bf16 v[68:71], v[104:107], v[184:187], v[68:71]
	v_mfma_f32_16x16x32_bf16 v[92:95], v[104:107], v[158:161], v[92:95]
	v_mfma_f32_16x16x32_bf16 v[88:91], v[200:203], v[158:161], v[88:91]
	v_mfma_f32_16x16x32_bf16 v[84:87], v[108:111], v[170:173], v[84:87]
	v_mfma_f32_16x16x32_bf16 v[80:83], v[204:207], v[170:173], v[80:83]
	v_mfma_f32_16x16x32_bf16 v[76:79], v[104:107], v[176:179], v[76:79]
	v_mfma_f32_16x16x32_bf16 v[72:75], v[200:203], v[176:179], v[72:75]
	v_mfma_f32_16x16x32_bf16 v[68:71], v[108:111], v[188:191], v[68:71]
	v_mfma_f32_16x16x32_bf16 v[64:67], v[204:207], v[188:191], v[64:67]
	v_mfma_f32_16x16x32_bf16 v[208:211], v[108:111], v[162:165], v[92:95]
	v_mfma_f32_16x16x32_bf16 v[158:161], v[204:207], v[162:165], v[88:91]
	v_mfma_f32_16x16x32_bf16 v[162:165], v[108:111], v[180:183], v[76:79]
	v_mfma_f32_16x16x32_bf16 v[166:169], v[204:207], v[180:183], v[72:75]
	s_barrier
; #define LDA(dst, b, h)                                                                                               \
;   _Pragma("unroll") for (int m = 0; m < 4; ++m) _Pragma("unroll") for (int k = 0; k < 2; ++k) dst[m][k] =            \
;       *reinterpret_cast<const bf16x8*>(SA(b, h) + lds_byte(wr * 64 + m * 16 + fr, k * 32 + fq * 8))
; #define LDB(dst, b, h)                                                                                               \
;   _Pragma("unroll") for (int n = 0; n < 2; ++n) _Pragma("unroll") for (int k = 0; k < 2; ++k) dst[n][k] =            \
;       *reinterpret_cast<const bf16x8*>(SB(b, h) + lds_byte(wc * 32 + n * 16 + fr, k * 32 + fq * 8))
; #define WAIT_V(n) asm volatile("s_waitcnt vmcnt(" #n ")" ::: "memory")
; #define WAIT_L(n) asm volatile("s_waitcnt lgkmcnt(" #n ")" ::: "memory")
; #define BAR __builtin_amdgcn_s_barrier()
; template <int EPI>
; __device__ __forceinline__ void gemm_phase(const u16* __restrict__ A, const u16* __restrict__ Bt, const int K,
;                                            const int nN, char* shm, const EpiArgs& ea) {
;     ...
;       LDB(B1, 0, 1); WAIT_V(8); BAR; WAIT_L(0); MMA(0, 1, At, B1); BAR;
;       LDA(At, 0, 1); WAIT_V(4); BAR; WAIT_L(0); MMA(1, 0, At, B0); MMA(1, 1, At, B1); BAR;
;     }
;     {
;       LDB(B0, 1, 0); LDA(At, 1, 0); WAIT_V(2); BAR; WAIT_L(0); MMA(0, 0, At, B0); BAR;
	s_nop 0
	ds_read_b128 v[72:75], v142 offset:16384
	ds_read_b128 v[76:79], v142 offset:17408
	ds_read_b128 v[88:91], v143 offset:16384
	ds_read_b128 v[92:95], v143 offset:17408
	ds_read_b128 v[170:173], v144 offset:16384
	ds_read_b128 v[176:179], v144 offset:17408
	ds_read_b128 v[180:183], v145 offset:16384
	ds_read_b128 v[184:187], v145 offset:17408
	s_waitcnt vmcnt(4)
	s_barrier
	s_waitcnt lgkmcnt(0)
	v_mfma_f32_16x16x32_bf16 v[60:63], v[130:133], v[72:75], v[60:63]
	v_mfma_f32_16x16x32_bf16 v[56:59], v[150:153], v[72:75], v[56:59]
	v_mfma_f32_16x16x32_bf16 v[48:51], v[150:153], v[88:91], v[48:51]
	v_mfma_f32_16x16x32_bf16 v[52:55], v[130:133], v[88:91], v[52:55]
	v_mfma_f32_16x16x32_bf16 v[36:39], v[130:133], v[180:183], v[36:39]
	v_mfma_f32_16x16x32_bf16 v[32:35], v[150:153], v[180:183], v[32:35]
	v_mfma_f32_16x16x32_bf16 v[60:63], v[134:137], v[76:79], v[60:63]
	v_mfma_f32_16x16x32_bf16 v[56:59], v[154:157], v[76:79], v[56:59]
	v_mfma_f32_16x16x32_bf16 v[48:51], v[154:157], v[92:95], v[48:51]
	v_mfma_f32_16x16x32_bf16 v[52:55], v[134:137], v[92:95], v[52:55]
	v_mfma_f32_16x16x32_bf16 v[44:47], v[130:133], v[170:173], v[44:47]
	v_mfma_f32_16x16x32_bf16 v[40:43], v[150:153], v[170:173], v[40:43]
	v_mfma_f32_16x16x32_bf16 v[36:39], v[134:137], v[184:187], v[36:39]
	v_mfma_f32_16x16x32_bf16 v[32:35], v[154:157], v[184:187], v[32:35]
	v_mfma_f32_16x16x32_bf16 v[188:191], v[134:137], v[176:179], v[44:47]
	v_mfma_f32_16x16x32_bf16 v[212:215], v[154:157], v[176:179], v[40:43]
	v_mfma_f32_16x16x32_bf16 v[20:23], v[104:107], v[88:91], v[20:23]
	v_mfma_f32_16x16x32_bf16 v[16:19], v[200:203], v[88:91], v[16:19]
	v_mfma_f32_16x16x32_bf16 v[0:3], v[200:203], v[180:183], v[0:3]
	v_mfma_f32_16x16x32_bf16 v[4:7], v[104:107], v[180:183], v[4:7]
	v_mfma_f32_16x16x32_bf16 v[28:31], v[104:107], v[72:75], v[28:31]
	v_mfma_f32_16x16x32_bf16 v[24:27], v[200:203], v[72:75], v[24:27]
	v_mfma_f32_16x16x32_bf16 v[20:23], v[108:111], v[92:95], v[20:23]
	v_mfma_f32_16x16x32_bf16 v[16:19], v[204:207], v[92:95], v[16:19]
	v_mfma_f32_16x16x32_bf16 v[12:15], v[104:107], v[170:173], v[12:15]
	v_mfma_f32_16x16x32_bf16 v[8:11], v[200:203], v[170:173], v[8:11]
	v_mfma_f32_16x16x32_bf16 v[4:7], v[108:111], v[184:187], v[4:7]
	v_mfma_f32_16x16x32_bf16 v[0:3], v[204:207], v[184:187], v[0:3]
	v_mfma_f32_16x16x32_bf16 v[130:133], v[108:111], v[76:79], v[28:31]
	v_mfma_f32_16x16x32_bf16 v[134:137], v[204:207], v[76:79], v[24:27]
	v_mfma_f32_16x16x32_bf16 v[150:153], v[108:111], v[176:179], v[12:15]
	v_mfma_f32_16x16x32_bf16 v[154:157], v[204:207], v[176:179], v[8:11]
	s_barrier
	s_nop 0
	ds_read_b128 v[8:11], v147
	ds_read_b128 v[12:15], v147 offset:1024
	ds_read_b128 v[170:173], v147 offset:2048
	ds_read_b128 v[176:179], v147 offset:3072
	ds_read_b128 v[24:27], v142 offset:32768
	ds_read_b128 v[28:31], v142 offset:33792
	ds_read_b128 v[40:43], v143 offset:32768
	ds_read_b128 v[44:47], v143 offset:33792
	ds_read_b128 v[180:183], v144 offset:32768
	ds_read_b128 v[184:187], v144 offset:33792
	ds_read_b128 v[200:203], v145 offset:32768
	ds_read_b128 v[204:207], v145 offset:33792
	s_waitcnt vmcnt(2)
	s_barrier
	s_waitcnt lgkmcnt(0)
	v_mfma_f32_16x16x32_bf16 v[72:75], v[8:11], v[24:27], v[124:127]
	v_mfma_f32_16x16x32_bf16 v[124:127], v[12:15], v[28:31], v[72:75]
	v_mfma_f32_16x16x32_bf16 v[72:75], v[170:173], v[24:27], v[120:123]
	v_mfma_f32_16x16x32_bf16 v[120:123], v[176:179], v[28:31], v[72:75]
	v_mfma_f32_16x16x32_bf16 v[72:75], v[8:11], v[40:43], v[116:119]
	v_mfma_f32_16x16x32_bf16 v[108:111], v[12:15], v[44:47], v[72:75]
	v_mfma_f32_16x16x32_bf16 v[72:75], v[170:173], v[40:43], v[112:115]
	v_mfma_f32_16x16x32_bf16 v[104:107], v[176:179], v[44:47], v[72:75]
	v_mfma_f32_16x16x32_bf16 v[72:75], v[8:11], v[180:183], v[192:195]
	v_mfma_f32_16x16x32_bf16 v[92:95], v[12:15], v[184:187], v[72:75]
	v_mfma_f32_16x16x32_bf16 v[72:75], v[170:173], v[180:183], v[196:199]
	v_mfma_f32_16x16x32_bf16 v[88:91], v[176:179], v[184:187], v[72:75]
	v_mfma_f32_16x16x32_bf16 v[72:75], v[8:11], v[200:203], v[100:103]
	v_mfma_f32_16x16x32_bf16 v[76:79], v[12:15], v[204:207], v[72:75]
	v_mfma_f32_16x16x32_bf16 v[72:75], v[170:173], v[200:203], v[96:99]
	v_mfma_f32_16x16x32_bf16 v[72:75], v[176:179], v[204:207], v[72:75]
	s_barrier
; #define LDA(dst, b, h)                                                                                               \
;   _Pragma("unroll") for (int m = 0; m < 4; ++m) _Pragma("unroll") for (int k = 0; k < 2; ++k) dst[m][k] =            \
;       *reinterpret_cast<const bf16x8*>(SA(b, h) + lds_byte(wr * 64 + m * 16 + fr, k * 32 + fq * 8))
; #define LDB(dst, b, h)                                                                                               \
;   _Pragma("unroll") for (int n = 0; n < 2; ++n) _Pragma("unroll") for (int k = 0; k < 2; ++k) dst[n][k] =            \
;       *reinterpret_cast<const bf16x8*>(SB(b, h) + lds_byte(wc * 32 + n * 16 + fr, k * 32 + fq * 8))
; #define WAIT_V(n) asm volatile("s_waitcnt vmcnt(" #n ")" ::: "memory")
; #define WAIT_L(n) asm volatile("s_waitcnt lgkmcnt(" #n ")" ::: "memory")
; #define BAR __builtin_amdgcn_s_barrier()
; template <int EPI>
; __device__ __forceinline__ void gemm_phase(const u16* __restrict__ A, const u16* __restrict__ Bt, const int K,
;                                            const int nN, char* shm, const EpiArgs& ea) {
;     ...
;       LDB(B0, 1, 0); LDA(At, 1, 0); WAIT_V(2); BAR; WAIT_L(0); MMA(0, 0, At, B0); BAR;
;       LDB(B1, 1, 1); WAIT_V(0); BAR; WAIT_L(0); MMA(0, 1, At, B1); BAR;
;       LDA(At, 1, 1); BAR; WAIT_L(0); MMA(1, 0, At, B0); MMA(1, 1, At, B1); BAR;
;     }
;     if (wr == 0) BAR;
;     if (has_next) STAGE7(brow2, bcol2);
	ds_read_b128 v[192:195], v148
	ds_read_b128 v[196:199], v148 offset:1024
	ds_read_b128 v[216:219], v148 offset:2048
	ds_read_b128 v[220:223], v148 offset:3072
	s_waitcnt vmcnt(0)
	s_barrier
	s_waitcnt lgkmcnt(0)
	v_mfma_f32_16x16x32_bf16 v[96:99], v[192:195], v[24:27], v[208:211]
	v_mfma_f32_16x16x32_bf16 v[24:27], v[216:219], v[24:27], v[158:161]
	v_mfma_f32_16x16x32_bf16 v[112:115], v[220:223], v[28:31], v[24:27]
	v_mfma_f32_16x16x32_bf16 v[24:27], v[192:195], v[40:43], v[84:87]
	v_mfma_f32_16x16x32_bf16 v[100:103], v[196:199], v[44:47], v[24:27]
	v_mfma_f32_16x16x32_bf16 v[24:27], v[216:219], v[40:43], v[80:83]
	v_mfma_f32_16x16x32_bf16 v[116:119], v[196:199], v[28:31], v[96:99]
	v_mfma_f32_16x16x32_bf16 v[96:99], v[220:223], v[44:47], v[24:27]
	v_mfma_f32_16x16x32_bf16 v[24:27], v[192:195], v[180:183], v[162:165]
	v_mfma_f32_16x16x32_bf16 v[84:87], v[196:199], v[184:187], v[24:27]
	v_mfma_f32_16x16x32_bf16 v[24:27], v[216:219], v[180:183], v[166:169]
	v_mfma_f32_16x16x32_bf16 v[80:83], v[220:223], v[184:187], v[24:27]
	v_mfma_f32_16x16x32_bf16 v[24:27], v[192:195], v[200:203], v[68:71]
	v_mfma_f32_16x16x32_bf16 v[68:71], v[196:199], v[204:207], v[24:27]
	v_mfma_f32_16x16x32_bf16 v[24:27], v[216:219], v[200:203], v[64:67]
	v_mfma_f32_16x16x32_bf16 v[64:67], v[220:223], v[204:207], v[24:27]
	s_barrier
	ds_read_b128 v[158:161], v142 offset:49152
	ds_read_b128 v[162:165], v142 offset:50176
	ds_read_b128 v[166:169], v143 offset:49152
	ds_read_b128 v[180:183], v143 offset:50176
	ds_read_b128 v[184:187], v144 offset:49152
	ds_read_b128 v[200:203], v144 offset:50176
	ds_read_b128 v[204:207], v145 offset:49152
	ds_read_b128 v[208:211], v145 offset:50176
	s_barrier
	s_waitcnt lgkmcnt(0)
	v_mfma_f32_16x16x32_bf16 v[24:27], v[8:11], v[158:161], v[60:63]
	v_mfma_f32_16x16x32_bf16 v[60:63], v[12:15], v[162:165], v[24:27]
	v_mfma_f32_16x16x32_bf16 v[24:27], v[170:173], v[158:161], v[56:59]
	v_mfma_f32_16x16x32_bf16 v[56:59], v[176:179], v[162:165], v[24:27]
	v_mfma_f32_16x16x32_bf16 v[24:27], v[8:11], v[166:169], v[52:55]
	v_mfma_f32_16x16x32_bf16 v[44:47], v[12:15], v[180:183], v[24:27]
	v_mfma_f32_16x16x32_bf16 v[24:27], v[170:173], v[166:169], v[48:51]
	v_mfma_f32_16x16x32_bf16 v[40:43], v[176:179], v[180:183], v[24:27]
	v_mfma_f32_16x16x32_bf16 v[24:27], v[8:11], v[184:187], v[188:191]
	v_mfma_f32_16x16x32_bf16 v[8:11], v[8:11], v[204:207], v[36:39]
	v_mfma_f32_16x16x32_bf16 v[28:31], v[12:15], v[200:203], v[24:27]
	v_mfma_f32_16x16x32_bf16 v[24:27], v[170:173], v[184:187], v[212:215]
	v_mfma_f32_16x16x32_bf16 v[12:15], v[12:15], v[208:211], v[8:11]
	v_mfma_f32_16x16x32_bf16 v[8:11], v[170:173], v[204:207], v[32:35]
	v_mfma_f32_16x16x32_bf16 v[24:27], v[176:179], v[200:203], v[24:27]
	v_mfma_f32_16x16x32_bf16 v[8:11], v[176:179], v[208:211], v[8:11]
	v_mfma_f32_16x16x32_bf16 v[32:35], v[192:195], v[158:161], v[130:133]
	v_mfma_f32_16x16x32_bf16 v[52:55], v[196:199], v[162:165], v[32:35]
	v_mfma_f32_16x16x32_bf16 v[32:35], v[216:219], v[158:161], v[134:137]
	v_mfma_f32_16x16x32_bf16 v[16:19], v[216:219], v[166:169], v[16:19]
	v_mfma_f32_16x16x32_bf16 v[48:51], v[220:223], v[162:165], v[32:35]
	v_mfma_f32_16x16x32_bf16 v[20:23], v[192:195], v[166:169], v[20:23]
	v_mfma_f32_16x16x32_bf16 v[32:35], v[220:223], v[180:183], v[16:19]
	v_mfma_f32_16x16x32_bf16 v[16:19], v[192:195], v[184:187], v[150:153]
	v_mfma_f32_16x16x32_bf16 v[36:39], v[196:199], v[180:183], v[20:23]
	v_mfma_f32_16x16x32_bf16 v[20:23], v[196:199], v[200:203], v[16:19]
	v_mfma_f32_16x16x32_bf16 v[16:19], v[216:219], v[184:187], v[154:157]
	v_mfma_f32_16x16x32_bf16 v[4:7], v[192:195], v[204:207], v[4:7]
	v_mfma_f32_16x16x32_bf16 v[0:3], v[216:219], v[204:207], v[0:3]
	v_mfma_f32_16x16x32_bf16 v[16:19], v[220:223], v[200:203], v[16:19]
	v_mfma_f32_16x16x32_bf16 v[4:7], v[196:199], v[208:211], v[4:7]
	v_mfma_f32_16x16x32_bf16 v[0:3], v[220:223], v[208:211], v[0:3]
	s_andn2_b64 vcc, exec, s[14:15]
	s_barrier
	s_cbranch_vccnz .LBB0_634
	s_barrier
